# first two vmcnt waits of each tile's first K-iteration allow the tile epilogue's 16 stores to stay in flight (vmcnt(24); strict on the first tile of a phase)
# speedup vs baseline: 1.0079x; 1.0016x over previous
; #define PG8_STAGEA(bufoff, gbase, voff) PG8_STAGE_X(bufoff, gbase, voff, AUXA)
;     ...
;     for (int i = 0; i < 2; ++i) { int R, C; stage_rc(tid * 16 + i * 8192, R, C); const int Rb = Epi::PERM ? ((R & ~31) + perm32(R & 31)) : R;
;         voffA[i] = (unsigned)(R * (ABLK ? 64 : g.lda) + C) * 2u; voffB[i] = (unsigned)(Rb * (BBLK ? 64 : g.ldb) + C) * 2u; }
;     const size_t kstepA = ABLK ? 32768 : 128, kstepB = BBLK ? 32768 : 128;
;     const size_t hstepA = (size_t)HALF * (ABLK ? 64 : g.lda) * 2, hstepB = (size_t)HALF * (BBLK ? 64 : g.ldb) * 2;
;     const size_t tstepA = ABLK ? (size_t)(K / 64) * 32768 : (size_t)256 * g.lda * 2, tstepB = BBLK ? (size_t)(K / 64) * 32768 : (size_t)256 * g.ldb * 2;
;     const unsigned ldsw = (unsigned)wid * 1024u;
;     const int aoff = lds_byte(wr * 64 + fr, fq * 8), boff = lds_byte(wc * 32 + fr, fq * 8);
;     ...
;     Unit cur, nxt; int ui = 0;
;     if (!S.next(0, cur)) return;
;     if (GEMM_PRIO_MODE == 2 && wr == 1) __builtin_amdgcn_s_setprio(1);
;     f32x4 acc[2][2][4][2];
; #pragma unroll
;     for (int a = 0; a < 2; ++a)
; #pragma unroll
;         for (int b = 0; b < 2; ++b)
; #pragma unroll
;             for (int m = 0; m < 4; ++m)
; #pragma unroll
;                 for (int n = 0; n < 2; ++n) acc[a][b][m][n] = (f32x4){0.f, 0.f, 0.f, 0.f};
;     bf16x8 At[4][2], B0[2][2], B1[2][2];
;     const char* cA = (const char*)g.A + (size_t)cur.pm * tstepA; const char* cB = (const char*)g.Bt + (size_t)cur.pn * tstepB;
;     S.a_ready(cur);
;     if constexpr (SP2) {
;         PG8_STAGEB(PG8_SB(0, 0), cB, voffB); PG8_STAGEB(PG8_SB(0, 1), cB + hstepB, voffB); PG8_STAGEA(PG8_SA(0, 0), cA, voffA); PG8_STAGEA(PG8_SA(0, 1), cA + hstepA, voffA);
;         if (wr == 1) PG8_BAR;
;         PG8_WAIT_V(2); PG8_BAR;
;         PG8_STAGEB(PG8_SB(1, 0), cB + kstepB, voffB); PG8_STAGEA(PG8_SA(1, 0), cA + kstepA, voffA); PG8_STAGEB(PG8_SB(1, 1), cB + hstepB + kstepB, voffB);
;         PG8_WAIT_V(6); PG8_BAR;
;     } else {
;         PG8_STAGEB(PG8_SB(0, 0), cB, voffB); PG8_STAGEA(PG8_SA(0, 0), cA, voffA); PG8_STAGEB(PG8_SB(0, 1), cB + hstepB, voffB); PG8_STAGEA(PG8_SA(0, 1), cA + hstepA, voffA);
;         if (wr == 1) PG8_BAR;
;         PG8_WAIT_V(4); PG8_BAR;
;         PG8_STAGEB(PG8_SB(1, 0), cB + kstepB, voffB); PG8_STAGEA(PG8_SA(1, 0), cA + kstepA, voffA); PG8_STAGEB(PG8_SB(1, 1), cB + hstepB + kstepB, voffB);
;         PG8_WAIT_V(6); PG8_BAR;
.LBB0_123:
	s_mov_b32 s98, 0
	v_readlane_b32 s14, v254, 33
	v_mov_b32_e32 v145, v17
	v_readlane_b32 s15, v254, 34
	s_and_b32 s5, s1, 3
	s_add_i32 m0, s51, 0x18000
	v_lshl_add_u64 v[0:1], v[0:1], 0, s[86:87]
	v_lshl_add_u64 v[12:13], s[14:15], 0, v[144:145]
	v_mov_b32_e32 v141, v17
	s_lshl_b32 s8, s0, 13
	s_lshl_b32 s9, s5, 5
	s_lshl_b32 s12, s5, 12
	s_waitcnt vmcnt(2)
	s_barrier
	global_load_lds_dwordx4 v[0:1], off
	v_lshl_add_u64 v[0:1], v[2:3], 0, s[86:87]
	s_add_i32 m0, s51, 0x1a000
	s_add_i32 s73, s51, 0x8000
	s_add_i32 s82, s51, 0xa000
	v_lshl_add_u64 v[14:15], s[14:15], 0, v[140:141]
	global_load_lds_dwordx4 v[0:1], off
	v_lshl_add_u64 v[0:1], v[12:13], 0, s[86:87]
	s_mov_b32 m0, s73
	s_add_u32 s6, s10, 0x100080
	global_load_lds_dwordx4 v[0:1], off
	v_lshl_add_u64 v[0:1], v[14:15], 0, s[86:87]
	s_mov_b32 m0, s82
	s_addc_u32 s7, s11, 0
	global_load_lds_dwordx4 v[0:1], off
	s_add_i32 m0, s51, 0x1c000
	v_lshl_add_u64 v[0:1], s[6:7], 0, v[142:143]
	global_load_lds_dwordx4 v[0:1], off
	v_lshl_add_u64 v[0:1], s[6:7], 0, v[138:139]
	s_add_i32 m0, s51, 0x1e000
	s_or_b32 s83, s5, 0x1ffffff0
	global_load_lds_dwordx4 v[0:1], off
	v_and_b32_e32 v0, 15, v6
	s_cmpk_lt_u32 s4, 0x100
	v_bfe_u32 v1, v6, 4, 2
	v_lshl_or_b32 v166, s0, 6, v0
	s_cselect_b64 s[24:25], -1, 0
	s_lshl_b32 s0, s0, 8
	v_lshlrev_b32_e32 v3, 4, v1
	s_add_i32 s0, s0, 0
	v_lshl_or_b32 v3, v0, 6, v3
	v_lshlrev_b32_e32 v0, 2, v0
	s_add_i32 s0, s0, 0x20000
	v_and_b32_e32 v6, 32, v0
	v_add_u32_e32 v168, s0, v0
	v_xor_b32_e32 v0, 16, v233
	v_cmp_lt_i32_e32 vcc, v0, v235
	v_lshlrev_b32_e32 v2, 3, v1
	s_lshl_b32 s1, s1, 6
	v_cndmask_b32_e32 v0, v233, v0, vcc
	v_lshlrev_b32_e32 v169, 2, v0
	v_xor_b32_e32 v0, 32, v233
	v_cmp_lt_i32_e32 vcc, v0, v235
	v_bitop3_b32 v167, v3, s12, v6 bitop3:0xde
	v_cmp_eq_u32_e64 s[12:13], 0, v1
	v_and_or_b32 v1, s9, 32, v2
	s_and_b32 s1, s1, 0x80
	v_cndmask_b32_e32 v0, v233, v0, vcc
	v_lshlrev_b32_e32 v170, 2, v0
	v_lshlrev_b32_e32 v16, 2, v1
	v_or_b32_e32 v0, s1, v1
	v_lshlrev_b32_e32 v1, 16, v9
	v_and_b32_e32 v1, 0xfffe0000, v1
	v_or_b32_e32 v171, s9, v2
	v_lshl_add_u32 v1, v8, 13, v1
	v_and_b32_e32 v2, 1, v9
	v_lshl_or_b32 v1, v2, 6, v1
	v_lshl_add_u32 v148, v10, 1, v1
	v_lshlrev_b32_e32 v1, 16, v4
	v_and_b32_e32 v1, 0xfffe0000, v1
	s_waitcnt vmcnt(6)
	v_readlane_b32 s4, v253, 28
	v_lshl_add_u32 v1, v5, 13, v1
	v_and_b32_e32 v2, 1, v4
	v_readlane_b32 s0, v254, 31
	v_bitop3_b32 v11, v3, s8, v6 bitop3:0xde
	v_readlane_b32 s5, v253, 29
	v_lshl_or_b32 v1, v2, 6, v1
	v_readlane_b32 s1, v254, 32
	s_mov_b32 s90, 0
	v_lshl_add_u64 v[146:147], s[4:5], 0, v[16:17]
	v_mov_b32_e32 v149, v17
	v_lshl_add_u32 v150, v7, 1, v1
	v_mov_b32_e32 v151, v17
	v_add_u32_e32 v172, 0, v11
	v_lshlrev_b32_e32 v173, 1, v0
	v_readlane_b32 s94, v254, 1
	s_mov_b32 s91, s0
	s_mov_b64 s[0:1], s[14:15]
	s_barrier
	s_branch .LBB0_126

; #define PG8_STAGEA(bufoff, gbase, voff) PG8_STAGE_X(bufoff, gbase, voff, AUXA)
; #define PG8_STR(x) PG8_STR2(x)
;     ...
;         const bool has_next = S.next(ui + 1, nxt);
;         const char* nA = has_next ? (const char*)g.A + (size_t)nxt.pm * tstepA : cA; const char* nB = has_next ? (const char*)g.Bt + (size_t)nxt.pn * tstepB : cB;
;         int t0 = 0;
;         if constexpr (SP2 && GEMM_RELAX == 1) { if (ui > 0) {
;             const char* a1 = cA + kstepA; const char* a2 = cA + 2 * kstepA; const char* b2 = cB + 2 * kstepB; const char* a3 = a2 + kstepA; const char* b3 = b2 + kstepB;
;             PG8_LDB(B0, 0, 0); PG8_LDB(B1, 0, 1); PG8_SCHED; PG8_LDA(At, 0, 0); PG8_STAGEA(PG8_SA(1, 1), a1 + hstepA, voffA);
;             PG8_WAIT_V(24); PG8_WAIT_L(0); PG8_BAR; PG8_MMA(0, 0, At, B0); PG8_MMA(0, 1, At, B1); PG8_BAR; PG8_SCHED;
;             PG8_LDA(At, 0, 1); PG8_STAGEB(PG8_SB(0, 0), b2, voffB); PG8_STAGEB(PG8_SB(0, 1), b2 + hstepB, voffB); PG8_STAGEA(PG8_SA(0, 0), a2, voffA);
;             PG8_WAIT_V(24); PG8_WAIT_L(0); PG8_BAR; PG8_MMA(1, 0, At, B0); PG8_MMA(1, 1, At, B1); PG8_BAR; PG8_SCHED;
;             PG8_LDB(B0, 1, 0); PG8_LDB(B1, 1, 1); PG8_SCHED; PG8_LDA(At, 1, 0); PG8_STAGEA(PG8_SA(0, 1), a2 + hstepA, voffA);
;             PG8_WAIT_V(8); PG8_WAIT_L(0); PG8_BAR; PG8_MMA(0, 0, At, B0); PG8_MMA(0, 1, At, B1); PG8_BAR; PG8_SCHED;
;             PG8_LDA(At, 1, 1); PG8_STAGEB(PG8_SB(1, 0), b3, voffB); PG8_STAGEB(PG8_SB(1, 1), b3 + hstepB, voffB); PG8_STAGEA(PG8_SA(1, 0), a3, voffA);
;             PG8_WAIT_V(8); PG8_WAIT_L(0); PG8_BAR; PG8_MMA(1, 0, At, B0); PG8_MMA(1, 1, At, B1); PG8_BAR; PG8_SCHED;
;             t0 = 2; } }
;     ...
;         asm volatile(".p2align " PG8_STR(GEMM_LOOP_ALIGN) ::: "memory");
;     ...
;         for (int t = t0; t < nt; t += 2) {
;             const bool last = (t == nt - 2);
;             const char* a1 = cA + (size_t)(t + 1) * kstepA;
;             const char* a2 = last ? nA : cA + (size_t)(t + 2) * kstepA; const char* b2 = last ? nB : cB + (size_t)(t + 2) * kstepB;
;             const char* a3 = a2 + kstepA; const char* b3 = b2 + kstepB;
;             if (last && has_next) S.a_ready(nxt);
;             if constexpr (SP2) {
;             PG8_LDB(B0, 0, 0); PG8_LDB(B1, 0, 1); PG8_SCHED; PG8_LDA(At, 0, 0); PG8_STAGEA(PG8_SA(1, 1), a1 + hstepA, voffA);
;     ...
;             const int relax = __builtin_amdgcn_readfirstlane((t == 0 && ui > 0) ? 1 : 0);
.LBB0_128:
	s_ashr_i32 s37, s36, 31
	s_lshl_b64 s[4:5], s[36:37], 21
	s_add_u32 s38, s56, s4
	s_addc_u32 s39, s57, s5
	s_and_b64 s[4:5], s[6:7], exec
	s_cselect_b32 s4, s39, s1
	s_cselect_b32 s5, s38, s0
	s_ashr_i32 s27, s26, 31
	s_lshl_b64 s[8:9], s[26:27], 21
	s_add_u32 s40, s43, s8
	s_addc_u32 s41, s50, s9
	s_and_b64 s[8:9], s[6:7], exec
	s_cselect_b32 s16, s41, s11
	s_cselect_b32 s17, s40, s10
	s_add_u32 s8, s0, 0x100080
	s_addc_u32 s9, s1, 0
	s_add_u32 s0, s10, 0x100
	s_addc_u32 s1, s11, 0
	s_mov_b32 s27, -2
	s_add_u32 s10, s8, 0xfff00080
	s_addc_u32 s11, s9, -1
	s_add_i32 s18, 0, 0x10000
	s_cmp_eq_u32 s27, 60
	s_cselect_b32 s15, s4, s11
	s_cselect_b32 s14, s5, s10
	v_add_u32_e32 v16, s18, v167
	s_cselect_b32 s11, s16, s1
	s_cselect_b32 s10, s17, s0
	s_add_i32 s20, 0, 0x14000
	s_waitcnt lgkmcnt(0)
	ds_read_b128 v[130:133], v16
	ds_read_b128 v[134:137], v16 offset:1024
	ds_read_b128 v[152:155], v16 offset:2048
	ds_read_b128 v[156:159], v16 offset:3072
	v_add_u32_e32 v16, s20, v167
	ds_read_b128 v[160:163], v16
	ds_read_b128 v[174:177], v16 offset:1024
	ds_read_b128 v[178:181], v16 offset:2048
	ds_read_b128 v[182:185], v16 offset:3072
	v_lshl_add_u64 v[164:165], s[8:9], 0, v[148:149]
	s_add_i32 m0, s51, 0xc000
	ds_read_b128 v[186:189], v172
	ds_read_b128 v[190:193], v172 offset:1024
	ds_read_b128 v[194:197], v172 offset:2048
	ds_read_b128 v[198:201], v172 offset:3072
	ds_read_b128 v[202:205], v172 offset:4096
	ds_read_b128 v[206:209], v172 offset:5120
	ds_read_b128 v[210:213], v172 offset:6144
	ds_read_b128 v[214:217], v172 offset:7168
	global_load_lds_dwordx4 v[164:165], off
	v_lshl_add_u64 v[164:165], s[8:9], 0, v[150:151]
	s_add_i32 m0, s51, 0xe000
	s_nop 0
	global_load_lds_dwordx4 v[164:165], off
	s_cmp_eq_u32 s98, 0
	s_cbranch_scc1 .Lrelax_s_lbb0_129_0
	s_waitcnt vmcnt(24)
	s_branch .Lrelax_d_lbb0_129_0
.Lrelax_s_lbb0_129_0:
	s_waitcnt vmcnt(8)
.Lrelax_d_lbb0_129_0:
	s_waitcnt lgkmcnt(0)
	s_nop 0
	s_setprio 1
	s_barrier
	v_mfma_f32_16x16x32_bf16 v[126:129], v[130:133], v[186:189], 0
	v_mfma_f32_16x16x32_bf16 v[122:125], v[152:155], v[186:189], 0
	v_mfma_f32_16x16x32_bf16 v[110:113], v[130:133], v[194:197], 0
	v_mfma_f32_16x16x32_bf16 v[106:109], v[152:155], v[194:197], 0
	v_mfma_f32_16x16x32_bf16 v[94:97], v[130:133], v[202:205], 0
	v_mfma_f32_16x16x32_bf16 v[90:93], v[152:155], v[202:205], 0
	v_mfma_f32_16x16x32_bf16 v[78:81], v[130:133], v[210:213], 0
	v_mfma_f32_16x16x32_bf16 v[74:77], v[152:155], v[210:213], 0
	v_mfma_f32_16x16x32_bf16 v[126:129], v[134:137], v[190:193], v[126:129]
	v_mfma_f32_16x16x32_bf16 v[122:125], v[156:159], v[190:193], v[122:125]
	v_mfma_f32_16x16x32_bf16 v[110:113], v[134:137], v[198:201], v[110:113]
	v_mfma_f32_16x16x32_bf16 v[106:109], v[156:159], v[198:201], v[106:109]
	v_mfma_f32_16x16x32_bf16 v[94:97], v[134:137], v[206:209], v[94:97]
	v_mfma_f32_16x16x32_bf16 v[90:93], v[156:159], v[206:209], v[90:93]
	v_mfma_f32_16x16x32_bf16 v[78:81], v[134:137], v[214:217], v[78:81]
	v_mfma_f32_16x16x32_bf16 v[74:77], v[156:159], v[214:217], v[74:77]
	v_mfma_f32_16x16x32_bf16 v[118:121], v[160:163], v[186:189], 0
	v_mfma_f32_16x16x32_bf16 v[114:117], v[178:181], v[186:189], 0
	v_mfma_f32_16x16x32_bf16 v[102:105], v[160:163], v[194:197], 0
	v_mfma_f32_16x16x32_bf16 v[98:101], v[178:181], v[194:197], 0
	v_mfma_f32_16x16x32_bf16 v[86:89], v[160:163], v[202:205], 0
	v_mfma_f32_16x16x32_bf16 v[82:85], v[178:181], v[202:205], 0
	v_mfma_f32_16x16x32_bf16 v[70:73], v[160:163], v[210:213], 0
	v_mfma_f32_16x16x32_bf16 v[66:69], v[178:181], v[210:213], 0
	v_mfma_f32_16x16x32_bf16 v[118:121], v[174:177], v[190:193], v[118:121]
	v_mfma_f32_16x16x32_bf16 v[114:117], v[182:185], v[190:193], v[114:117]
	v_mfma_f32_16x16x32_bf16 v[102:105], v[174:177], v[198:201], v[102:105]
	v_mfma_f32_16x16x32_bf16 v[98:101], v[182:185], v[198:201], v[98:101]
	v_mfma_f32_16x16x32_bf16 v[86:89], v[174:177], v[206:209], v[86:89]
	v_mfma_f32_16x16x32_bf16 v[82:85], v[182:185], v[206:209], v[82:85]
	v_mfma_f32_16x16x32_bf16 v[70:73], v[174:177], v[214:217], v[70:73]
	v_mfma_f32_16x16x32_bf16 v[66:69], v[182:185], v[214:217], v[66:69]
	s_barrier
	s_setprio 0
	s_add_i32 s18, s18, s42
	v_lshl_add_u64 v[164:165], s[10:11], 0, v[142:143]
	s_mov_b32 m0, s18
	ds_read_b128 v[186:189], v172 offset:16384
	ds_read_b128 v[190:193], v172 offset:17408
	ds_read_b128 v[194:197], v172 offset:18432
	ds_read_b128 v[198:201], v172 offset:19456
	ds_read_b128 v[202:205], v172 offset:20480
	ds_read_b128 v[206:209], v172 offset:21504
	ds_read_b128 v[210:213], v172 offset:22528
	ds_read_b128 v[214:217], v172 offset:23552
	global_load_lds_dwordx4 v[164:165], off
	s_add_i32 m0, s18, 0x2000
	s_add_u32 s18, s10, 0x100000
	v_lshl_add_u64 v[218:219], s[10:11], 0, v[138:139]
	s_addc_u32 s19, s11, 0
	s_add_i32 s20, s20, s42
	global_load_lds_dwordx4 v[218:219], off
	v_lshl_add_u64 v[220:221], s[18:19], 0, v[142:143]
	s_mov_b32 m0, s20
	v_lshl_add_u64 v[222:223], s[14:15], 0, v[140:141]
	global_load_lds_dwordx4 v[220:221], off
	v_lshl_add_u64 v[220:221], s[18:19], 0, v[138:139]
	s_add_i32 m0, s20, 0x2000
	s_nop 0
	global_load_lds_dwordx4 v[220:221], off
	v_lshl_add_u64 v[220:221], s[14:15], 0, v[144:145]
	s_mov_b32 m0, s51
	s_nop 0
	global_load_lds_dwordx4 v[220:221], off
	s_mov_b32 m0, s68
	s_nop 0
	global_load_lds_dwordx4 v[222:223], off
	s_cmp_eq_u32 s98, 0
	s_cbranch_scc1 .Lrelax_s_lbb0_129_1
	s_waitcnt vmcnt(24)
	s_branch .Lrelax_d_lbb0_129_1

; #define PG8_STAGEA(bufoff, gbase, voff) PG8_STAGE_X(bufoff, gbase, voff, AUXA)
; #define PG8_LDA(dst, b, h) do { _Pragma("unroll") for (int m = 0; m < 4; ++m) _Pragma("unroll") for (int k = 0; k < 2; ++k) dst[m][k] = *(const PG8_LAS bf16x8*)(lds + PG8_SA(b, h) + aoff + m * 2048 + k * 1024); } while (0)
; #define PG8_LDB(dst, b, h) do { _Pragma("unroll") for (int n = 0; n < 2; ++n) _Pragma("unroll") for (int k = 0; k < 2; ++k) dst[n][k] = *(const PG8_LAS bf16x8*)(lds + PG8_SB(b, h) + boff + n * 2048 + k * 1024); } while (0)
; #define PG8_MMA(ai, bj, At, Bt) do { if (GEMM_PRIO_MODE == 0) __builtin_amdgcn_s_setprio(1); PG8_MMA_LOOPS \
;         acc[ai][bj][m][n] = __builtin_amdgcn_mfma_f32_16x16x32_bf16(Bt[n][k], At[m][k], acc[ai][bj][m][n], 0, 0, 0); if (GEMM_PRIO_MODE == 0) __builtin_amdgcn_s_setprio(0); } while (0)
; #define PG8_WAIT_V(n) asm volatile("s_waitcnt vmcnt(" #n ")" ::: "memory")
; #define PG8_WAIT_VR(n, nr, flag) asm volatile("s_cmp_eq_u32 %0, 0\n\ts_cbranch_scc1 .Lpg8s%=\n\ts_waitcnt vmcnt(" #nr ")\n\ts_branch .Lpg8d%=\n.Lpg8s%=:\n\ts_waitcnt vmcnt(" #n ")\n.Lpg8d%=:" :: "s"(flag) : "memory", "scc")
; #define PG8_WAIT_L(n) asm volatile("s_waitcnt lgkmcnt(" #n ")" ::: "memory")
; #define PG8_BAR __builtin_amdgcn_s_barrier()
; #define PG8_SCHED __builtin_amdgcn_sched_barrier(0)
;     ...
;             PG8_WAIT_VR(8, 24, relax); PG8_WAIT_L(0); PG8_BAR; PG8_MMA(1, 0, At, B0); PG8_MMA(1, 1, At, B1); PG8_BAR; PG8_SCHED;
;     ...
;             PG8_WAIT_V(8); PG8_WAIT_L(0); PG8_BAR; PG8_MMA(1, 0, At, B0); PG8_MMA(1, 1, At, B1); PG8_BAR; PG8_SCHED;
;     ...
;             PG8_LDB(B0, 1, 0); PG8_LDB(B1, 1, 1); PG8_SCHED; PG8_LDA(At, 1, 0); PG8_STAGEA(PG8_SA(0, 1), a2 + hstepA, voffA);
;             PG8_WAIT_V(8); PG8_WAIT_L(0); PG8_BAR; PG8_MMA(0, 0, At, B0); PG8_MMA(0, 1, At, B1); PG8_BAR; PG8_SCHED;
.Lrelax_d_lbb0_129_1:
	s_waitcnt lgkmcnt(0)
	s_setprio 1
	s_barrier
	v_mfma_f32_16x16x32_bf16 v[62:65], v[130:133], v[186:189], 0
	v_mfma_f32_16x16x32_bf16 v[58:61], v[152:155], v[186:189], 0
	v_mfma_f32_16x16x32_bf16 v[46:49], v[130:133], v[194:197], 0
	v_mfma_f32_16x16x32_bf16 v[42:45], v[152:155], v[194:197], 0
	v_mfma_f32_16x16x32_bf16 v[30:33], v[130:133], v[202:205], 0
	v_mfma_f32_16x16x32_bf16 v[26:29], v[152:155], v[202:205], 0
	v_mfma_f32_16x16x32_bf16 v[12:15], v[130:133], v[210:213], 0
	v_mfma_f32_16x16x32_bf16 v[8:11], v[152:155], v[210:213], 0
	v_mfma_f32_16x16x32_bf16 v[62:65], v[134:137], v[190:193], v[62:65]
	v_mfma_f32_16x16x32_bf16 v[58:61], v[156:159], v[190:193], v[58:61]
	v_mfma_f32_16x16x32_bf16 v[46:49], v[134:137], v[198:201], v[46:49]
	v_mfma_f32_16x16x32_bf16 v[42:45], v[156:159], v[198:201], v[42:45]
	v_mfma_f32_16x16x32_bf16 v[30:33], v[134:137], v[206:209], v[30:33]
	v_mfma_f32_16x16x32_bf16 v[26:29], v[156:159], v[206:209], v[26:29]
	v_mfma_f32_16x16x32_bf16 v[12:15], v[134:137], v[214:217], v[12:15]
	v_mfma_f32_16x16x32_bf16 v[8:11], v[156:159], v[214:217], v[8:11]
	v_mfma_f32_16x16x32_bf16 v[54:57], v[160:163], v[186:189], 0
	v_mfma_f32_16x16x32_bf16 v[50:53], v[178:181], v[186:189], 0
	v_mfma_f32_16x16x32_bf16 v[38:41], v[160:163], v[194:197], 0
	v_mfma_f32_16x16x32_bf16 v[34:37], v[178:181], v[194:197], 0
	v_mfma_f32_16x16x32_bf16 v[22:25], v[160:163], v[202:205], 0
	v_mfma_f32_16x16x32_bf16 v[18:21], v[178:181], v[202:205], 0
	v_mfma_f32_16x16x32_bf16 v[4:7], v[160:163], v[210:213], 0
	v_mfma_f32_16x16x32_bf16 v[0:3], v[178:181], v[210:213], 0
	v_mfma_f32_16x16x32_bf16 v[54:57], v[174:177], v[190:193], v[54:57]
	v_mfma_f32_16x16x32_bf16 v[50:53], v[182:185], v[190:193], v[50:53]
	v_mfma_f32_16x16x32_bf16 v[38:41], v[174:177], v[198:201], v[38:41]
	v_mfma_f32_16x16x32_bf16 v[34:37], v[182:185], v[198:201], v[34:37]
	v_mfma_f32_16x16x32_bf16 v[22:25], v[174:177], v[206:209], v[22:25]
	v_mfma_f32_16x16x32_bf16 v[18:21], v[182:185], v[206:209], v[18:21]
	v_mfma_f32_16x16x32_bf16 v[4:7], v[174:177], v[214:217], v[4:7]
	v_mfma_f32_16x16x32_bf16 v[0:3], v[182:185], v[214:217], v[0:3]
	s_barrier
	s_setprio 0
	s_add_i32 s18, 0, 0x18000
	v_add_u32_e32 v16, s18, v167
	s_add_i32 s19, 0, 0x1c000
	ds_read_b128 v[130:133], v16
	ds_read_b128 v[134:137], v16 offset:1024
	ds_read_b128 v[152:155], v16 offset:2048
	ds_read_b128 v[156:159], v16 offset:3072
	v_add_u32_e32 v16, s19, v167
	ds_read_b128 v[160:163], v16
	ds_read_b128 v[174:177], v16 offset:1024
	ds_read_b128 v[178:181], v16 offset:2048
	ds_read_b128 v[182:185], v16 offset:3072
	s_add_u32 s14, s14, 0x100000
	s_addc_u32 s15, s15, 0
	s_mov_b32 m0, s69
	v_lshl_add_u64 v[224:225], s[14:15], 0, v[144:145]
	ds_read_b128 v[186:189], v172 offset:32768
	ds_read_b128 v[190:193], v172 offset:33792
	ds_read_b128 v[194:197], v172 offset:34816
	ds_read_b128 v[198:201], v172 offset:35840
	ds_read_b128 v[202:205], v172 offset:36864
	ds_read_b128 v[206:209], v172 offset:37888
	ds_read_b128 v[210:213], v172 offset:38912
	ds_read_b128 v[214:217], v172 offset:39936
	global_load_lds_dwordx4 v[224:225], off
	v_lshl_add_u64 v[224:225], s[14:15], 0, v[140:141]
	s_mov_b32 m0, s72
	s_nop 0
	global_load_lds_dwordx4 v[224:225], off
	s_waitcnt vmcnt(8)
	s_waitcnt lgkmcnt(0)
	s_setprio 1
	s_barrier
	v_mfma_f32_16x16x32_bf16 v[126:129], v[130:133], v[186:189], v[126:129]
	v_mfma_f32_16x16x32_bf16 v[122:125], v[152:155], v[186:189], v[122:125]
	v_mfma_f32_16x16x32_bf16 v[110:113], v[130:133], v[194:197], v[110:113]
	v_mfma_f32_16x16x32_bf16 v[106:109], v[152:155], v[194:197], v[106:109]
	v_mfma_f32_16x16x32_bf16 v[94:97], v[130:133], v[202:205], v[94:97]
	v_mfma_f32_16x16x32_bf16 v[90:93], v[152:155], v[202:205], v[90:93]
	v_mfma_f32_16x16x32_bf16 v[78:81], v[130:133], v[210:213], v[78:81]
	v_mfma_f32_16x16x32_bf16 v[74:77], v[152:155], v[210:213], v[74:77]
	v_mfma_f32_16x16x32_bf16 v[126:129], v[134:137], v[190:193], v[126:129]
	v_mfma_f32_16x16x32_bf16 v[122:125], v[156:159], v[190:193], v[122:125]
	v_mfma_f32_16x16x32_bf16 v[110:113], v[134:137], v[198:201], v[110:113]
	v_mfma_f32_16x16x32_bf16 v[106:109], v[156:159], v[198:201], v[106:109]
	v_mfma_f32_16x16x32_bf16 v[94:97], v[134:137], v[206:209], v[94:97]
	v_mfma_f32_16x16x32_bf16 v[90:93], v[156:159], v[206:209], v[90:93]
	v_mfma_f32_16x16x32_bf16 v[78:81], v[134:137], v[214:217], v[78:81]
	v_mfma_f32_16x16x32_bf16 v[74:77], v[156:159], v[214:217], v[74:77]
	v_mfma_f32_16x16x32_bf16 v[118:121], v[160:163], v[186:189], v[118:121]
	v_mfma_f32_16x16x32_bf16 v[114:117], v[178:181], v[186:189], v[114:117]
	v_mfma_f32_16x16x32_bf16 v[102:105], v[160:163], v[194:197], v[102:105]
	v_mfma_f32_16x16x32_bf16 v[98:101], v[178:181], v[194:197], v[98:101]
	v_mfma_f32_16x16x32_bf16 v[86:89], v[160:163], v[202:205], v[86:89]
	v_mfma_f32_16x16x32_bf16 v[82:85], v[178:181], v[202:205], v[82:85]
	v_mfma_f32_16x16x32_bf16 v[70:73], v[160:163], v[210:213], v[70:73]
	v_mfma_f32_16x16x32_bf16 v[66:69], v[178:181], v[210:213], v[66:69]
	v_mfma_f32_16x16x32_bf16 v[118:121], v[174:177], v[190:193], v[118:121]
	v_mfma_f32_16x16x32_bf16 v[114:117], v[182:185], v[190:193], v[114:117]
	v_mfma_f32_16x16x32_bf16 v[102:105], v[174:177], v[198:201], v[102:105]
	v_mfma_f32_16x16x32_bf16 v[98:101], v[182:185], v[198:201], v[98:101]
	v_mfma_f32_16x16x32_bf16 v[86:89], v[174:177], v[206:209], v[86:89]
	v_mfma_f32_16x16x32_bf16 v[82:85], v[182:185], v[206:209], v[82:85]
	v_mfma_f32_16x16x32_bf16 v[70:73], v[174:177], v[214:217], v[70:73]
	v_mfma_f32_16x16x32_bf16 v[66:69], v[182:185], v[214:217], v[66:69]
	s_barrier
; #define PG8_STAGEA(bufoff, gbase, voff) PG8_STAGE_X(bufoff, gbase, voff, AUXA)
; #define PG8_STAGEB(bufoff, gbase, voff) PG8_STAGE_X(bufoff, gbase, voff, AUXB)
; #define PG8_LDA(dst, b, h) do { _Pragma("unroll") for (int m = 0; m < 4; ++m) _Pragma("unroll") for (int k = 0; k < 2; ++k) dst[m][k] = *(const PG8_LAS bf16x8*)(lds + PG8_SA(b, h) + aoff + m * 2048 + k * 1024); } while (0)
; #define PG8_WAIT_V(n) asm volatile("s_waitcnt vmcnt(" #n ")" ::: "memory")
; #define PG8_WAIT_L(n) asm volatile("s_waitcnt lgkmcnt(" #n ")" ::: "memory")
;     ...
;         for (int t = t0; t < nt; t += 2) {
;             const bool last = (t == nt - 2);
;             const char* a1 = cA + (size_t)(t + 1) * kstepA;
;             const char* a2 = last ? nA : cA + (size_t)(t + 2) * kstepA; const char* b2 = last ? nB : cB + (size_t)(t + 2) * kstepB;
;             const char* a3 = a2 + kstepA; const char* b3 = b2 + kstepB;
;             if (last && has_next) S.a_ready(nxt);
;             if constexpr (SP2) {
;             PG8_LDB(B0, 0, 0); PG8_LDB(B1, 0, 1); PG8_SCHED; PG8_LDA(At, 0, 0); PG8_STAGEA(PG8_SA(1, 1), a1 + hstepA, voffA);
;     ...
;             const int relax = __builtin_amdgcn_readfirstlane((t == 0 && ui > 0) ? 1 : 0);
;             PG8_WAIT_VR(8, 24, relax); PG8_WAIT_L(0); PG8_BAR; PG8_MMA(0, 0, At, B0); PG8_MMA(0, 1, At, B1); PG8_BAR; PG8_SCHED;
;     ...
;             PG8_WAIT_V(8); PG8_WAIT_L(0); PG8_BAR; PG8_MMA(0, 0, At, B0); PG8_MMA(0, 1, At, B1); PG8_BAR; PG8_SCHED;
;     ...
;             PG8_LDA(At, 0, 1); PG8_STAGEB(PG8_SB(0, 0), b2, voffB); PG8_STAGEB(PG8_SB(0, 1), b2 + hstepB, voffB); PG8_STAGEA(PG8_SA(0, 0), a2, voffA);
;     ...
;             PG8_WAIT_VR(8, 24, relax); PG8_WAIT_L(0); PG8_BAR; PG8_MMA(1, 0, At, B0); PG8_MMA(1, 1, At, B1); PG8_BAR; PG8_SCHED;
;     ...
;             PG8_WAIT_V(8); PG8_WAIT_L(0); PG8_BAR; PG8_MMA(1, 0, At, B0); PG8_MMA(1, 1, At, B1); PG8_BAR; PG8_SCHED;
;     ...
;             PG8_LDB(B0, 1, 0); PG8_LDB(B1, 1, 1); PG8_SCHED; PG8_LDA(At, 1, 0); PG8_STAGEA(PG8_SA(0, 1), a2 + hstepA, voffA);
;             PG8_WAIT_V(8); PG8_WAIT_L(0); PG8_BAR; PG8_MMA(0, 0, At, B0); PG8_MMA(0, 1, At, B1); PG8_BAR; PG8_SCHED;
;             PG8_LDA(At, 1, 1); PG8_STAGEB(PG8_SB(1, 0), b3, voffB); PG8_STAGEB(PG8_SB(1, 1), b3 + hstepB, voffB); PG8_STAGEA(PG8_SA(1, 0), a3, voffA);
;             PG8_WAIT_V(8); PG8_WAIT_L(0); PG8_BAR; PG8_MMA(1, 0, At, B0); PG8_MMA(1, 1, At, B1); PG8_BAR; PG8_SCHED;
	s_setprio 0
	s_add_i32 s14, s18, s42
	v_lshl_add_u64 v[164:165], v[164:165], 0, s[86:87]
	s_mov_b32 m0, s14
	ds_read_b128 v[186:189], v172 offset:49152
	ds_read_b128 v[190:193], v172 offset:50176
	ds_read_b128 v[194:197], v172 offset:51200
	ds_read_b128 v[198:201], v172 offset:52224
	ds_read_b128 v[202:205], v172 offset:53248
	ds_read_b128 v[206:209], v172 offset:54272
	ds_read_b128 v[210:213], v172 offset:55296
	ds_read_b128 v[214:217], v172 offset:56320
	global_load_lds_dwordx4 v[164:165], off
	s_add_i32 m0, s14, 0x2000
	s_add_u32 s10, s10, 0x100080
	v_lshl_add_u64 v[164:165], v[218:219], 0, s[86:87]
	s_addc_u32 s11, s11, 0
	s_add_i32 s14, s19, s42
	global_load_lds_dwordx4 v[164:165], off
	v_lshl_add_u64 v[164:165], s[10:11], 0, v[142:143]
	s_mov_b32 m0, s14
	s_nop 0
	global_load_lds_dwordx4 v[164:165], off
	v_lshl_add_u64 v[164:165], s[10:11], 0, v[138:139]
	s_add_i32 m0, s14, 0x2000
	s_nop 0
	global_load_lds_dwordx4 v[164:165], off
	v_lshl_add_u64 v[164:165], v[220:221], 0, s[86:87]
	s_mov_b32 m0, s73
	s_nop 0
	global_load_lds_dwordx4 v[164:165], off
	v_lshl_add_u64 v[164:165], v[222:223], 0, s[86:87]
	s_mov_b32 m0, s82
	s_nop 0
	global_load_lds_dwordx4 v[164:165], off
	s_waitcnt vmcnt(8)
	s_waitcnt lgkmcnt(0)
	s_nop 0
	s_setprio 1
	s_barrier
	v_mfma_f32_16x16x32_bf16 v[62:65], v[130:133], v[186:189], v[62:65]
	v_mfma_f32_16x16x32_bf16 v[58:61], v[152:155], v[186:189], v[58:61]
	v_mfma_f32_16x16x32_bf16 v[46:49], v[130:133], v[194:197], v[46:49]
	v_mfma_f32_16x16x32_bf16 v[42:45], v[152:155], v[194:197], v[42:45]
	v_mfma_f32_16x16x32_bf16 v[30:33], v[130:133], v[202:205], v[30:33]
	v_mfma_f32_16x16x32_bf16 v[26:29], v[152:155], v[202:205], v[26:29]
	v_mfma_f32_16x16x32_bf16 v[12:15], v[130:133], v[210:213], v[12:15]
	v_mfma_f32_16x16x32_bf16 v[8:11], v[152:155], v[210:213], v[8:11]
	v_mfma_f32_16x16x32_bf16 v[62:65], v[134:137], v[190:193], v[62:65]
	v_mfma_f32_16x16x32_bf16 v[58:61], v[156:159], v[190:193], v[58:61]
	v_mfma_f32_16x16x32_bf16 v[46:49], v[134:137], v[198:201], v[46:49]
	v_mfma_f32_16x16x32_bf16 v[42:45], v[156:159], v[198:201], v[42:45]
	v_mfma_f32_16x16x32_bf16 v[30:33], v[134:137], v[206:209], v[30:33]
	v_mfma_f32_16x16x32_bf16 v[26:29], v[156:159], v[206:209], v[26:29]
	v_mfma_f32_16x16x32_bf16 v[12:15], v[134:137], v[214:217], v[12:15]
	v_mfma_f32_16x16x32_bf16 v[8:11], v[156:159], v[214:217], v[8:11]
	v_mfma_f32_16x16x32_bf16 v[54:57], v[160:163], v[186:189], v[54:57]
	v_mfma_f32_16x16x32_bf16 v[50:53], v[178:181], v[186:189], v[50:53]
	v_mfma_f32_16x16x32_bf16 v[38:41], v[160:163], v[194:197], v[38:41]
	v_mfma_f32_16x16x32_bf16 v[34:37], v[178:181], v[194:197], v[34:37]
	v_mfma_f32_16x16x32_bf16 v[22:25], v[160:163], v[202:205], v[22:25]
	v_mfma_f32_16x16x32_bf16 v[18:21], v[178:181], v[202:205], v[18:21]
	v_mfma_f32_16x16x32_bf16 v[4:7], v[160:163], v[210:213], v[4:7]
	v_mfma_f32_16x16x32_bf16 v[0:3], v[178:181], v[210:213], v[0:3]
	v_mfma_f32_16x16x32_bf16 v[54:57], v[174:177], v[190:193], v[54:57]
	v_mfma_f32_16x16x32_bf16 v[50:53], v[182:185], v[190:193], v[50:53]
	v_mfma_f32_16x16x32_bf16 v[38:41], v[174:177], v[198:201], v[38:41]
	v_mfma_f32_16x16x32_bf16 v[34:37], v[182:185], v[198:201], v[34:37]
	v_mfma_f32_16x16x32_bf16 v[22:25], v[174:177], v[206:209], v[22:25]
	v_mfma_f32_16x16x32_bf16 v[18:21], v[182:185], v[206:209], v[18:21]
	v_mfma_f32_16x16x32_bf16 v[4:7], v[174:177], v[214:217], v[4:7]
	v_mfma_f32_16x16x32_bf16 v[0:3], v[182:185], v[214:217], v[0:3]
	s_barrier
	s_setprio 0
	s_add_i32 s27, s27, 2
	s_add_u32 s8, s8, 0x100
	s_addc_u32 s9, s9, 0
	s_add_u32 s0, s0, 0x100
	s_addc_u32 s1, s1, 0
	v_add_u32_e32 v226, 0x10000, v167
.LBB0_129:
	s_add_u32 s10, s8, 0xfff00080
	s_addc_u32 s11, s9, -1
	s_add_i32 s18, 0, 0x10000
	s_cmp_eq_u32 s27, 60
	s_cselect_b32 s15, s4, s11
	s_cselect_b32 s14, s5, s10
	s_cselect_b32 s11, s16, s1
	s_cselect_b32 s10, s17, s0
	s_add_i32 s20, 0, 0x14000
	s_waitcnt lgkmcnt(0)
	ds_read_b128 v[130:133], v226
	ds_read_b128 v[134:137], v226 offset:1024
	ds_read_b128 v[152:155], v226 offset:2048
	ds_read_b128 v[156:159], v226 offset:3072
	ds_read_b128 v[160:163], v226 offset:16384
	ds_read_b128 v[174:177], v226 offset:17408
	ds_read_b128 v[178:181], v226 offset:18432
	ds_read_b128 v[182:185], v226 offset:19456
	s_add_i32 m0, s51, 0xc000
	ds_read_b128 v[186:189], v172
	ds_read_b128 v[190:193], v172 offset:1024
	ds_read_b128 v[194:197], v172 offset:2048
	ds_read_b128 v[198:201], v172 offset:3072
	ds_read_b128 v[202:205], v172 offset:4096
	ds_read_b128 v[206:209], v172 offset:5120
	ds_read_b128 v[210:213], v172 offset:6144
	ds_read_b128 v[214:217], v172 offset:7168
	global_load_lds_dwordx4 v148, s[8:9]
	s_add_i32 m0, s51, 0xe000
	s_nop 0
	global_load_lds_dwordx4 v150, s[8:9]
	s_waitcnt vmcnt(8)
	s_waitcnt lgkmcnt(0)
	s_nop 0
	s_setprio 1
	s_barrier
; #define PG8_STAGEA(bufoff, gbase, voff) PG8_STAGE_X(bufoff, gbase, voff, AUXA)
; #define PG8_STAGEB(bufoff, gbase, voff) PG8_STAGE_X(bufoff, gbase, voff, AUXB)
; #define PG8_LDA(dst, b, h) do { _Pragma("unroll") for (int m = 0; m < 4; ++m) _Pragma("unroll") for (int k = 0; k < 2; ++k) dst[m][k] = *(const PG8_LAS bf16x8*)(lds + PG8_SA(b, h) + aoff + m * 2048 + k * 1024); } while (0)
; #define PG8_MMA(ai, bj, At, Bt) do { if (GEMM_PRIO_MODE == 0) __builtin_amdgcn_s_setprio(1); PG8_MMA_LOOPS \
;         acc[ai][bj][m][n] = __builtin_amdgcn_mfma_f32_16x16x32_bf16(Bt[n][k], At[m][k], acc[ai][bj][m][n], 0, 0, 0); if (GEMM_PRIO_MODE == 0) __builtin_amdgcn_s_setprio(0); } while (0)
; #define PG8_WAIT_V(n) asm volatile("s_waitcnt vmcnt(" #n ")" ::: "memory")
; #define PG8_WAIT_VR(n, nr, flag) asm volatile("s_cmp_eq_u32 %0, 0\n\ts_cbranch_scc1 .Lpg8s%=\n\ts_waitcnt vmcnt(" #nr ")\n\ts_branch .Lpg8d%=\n.Lpg8s%=:\n\ts_waitcnt vmcnt(" #n ")\n.Lpg8d%=:" :: "s"(flag) : "memory", "scc")
; #define PG8_WAIT_L(n) asm volatile("s_waitcnt lgkmcnt(" #n ")" ::: "memory")
; #define PG8_BAR __builtin_amdgcn_s_barrier()
; #define PG8_SCHED __builtin_amdgcn_sched_barrier(0)
;     ...
;             PG8_WAIT_V(8); PG8_WAIT_L(0); PG8_BAR; PG8_MMA(0, 0, At, B0); PG8_MMA(0, 1, At, B1); PG8_BAR; PG8_SCHED;
;     ...
;             PG8_LDA(At, 0, 1); PG8_STAGEB(PG8_SB(0, 0), b2, voffB); PG8_STAGEB(PG8_SB(0, 1), b2 + hstepB, voffB); PG8_STAGEA(PG8_SA(0, 0), a2, voffA);
;     ...
;             PG8_WAIT_VR(8, 24, relax); PG8_WAIT_L(0); PG8_BAR; PG8_MMA(1, 0, At, B0); PG8_MMA(1, 1, At, B1); PG8_BAR; PG8_SCHED;
;     ...
;             PG8_WAIT_V(8); PG8_WAIT_L(0); PG8_BAR; PG8_MMA(1, 0, At, B0); PG8_MMA(1, 1, At, B1); PG8_BAR; PG8_SCHED;
	v_mfma_f32_16x16x32_bf16 v[126:129], v[130:133], v[186:189], v[126:129]
	v_mfma_f32_16x16x32_bf16 v[122:125], v[152:155], v[186:189], v[122:125]
	v_mfma_f32_16x16x32_bf16 v[110:113], v[130:133], v[194:197], v[110:113]
	v_mfma_f32_16x16x32_bf16 v[106:109], v[152:155], v[194:197], v[106:109]
	v_mfma_f32_16x16x32_bf16 v[94:97], v[130:133], v[202:205], v[94:97]
	v_mfma_f32_16x16x32_bf16 v[90:93], v[152:155], v[202:205], v[90:93]
	v_mfma_f32_16x16x32_bf16 v[78:81], v[130:133], v[210:213], v[78:81]
	v_mfma_f32_16x16x32_bf16 v[74:77], v[152:155], v[210:213], v[74:77]
	v_mfma_f32_16x16x32_bf16 v[126:129], v[134:137], v[190:193], v[126:129]
	v_mfma_f32_16x16x32_bf16 v[122:125], v[156:159], v[190:193], v[122:125]
	v_mfma_f32_16x16x32_bf16 v[110:113], v[134:137], v[198:201], v[110:113]
	v_mfma_f32_16x16x32_bf16 v[106:109], v[156:159], v[198:201], v[106:109]
	v_mfma_f32_16x16x32_bf16 v[94:97], v[134:137], v[206:209], v[94:97]
	v_mfma_f32_16x16x32_bf16 v[90:93], v[156:159], v[206:209], v[90:93]
	v_mfma_f32_16x16x32_bf16 v[78:81], v[134:137], v[214:217], v[78:81]
	v_mfma_f32_16x16x32_bf16 v[74:77], v[156:159], v[214:217], v[74:77]
	v_mfma_f32_16x16x32_bf16 v[118:121], v[160:163], v[186:189], v[118:121]
	v_mfma_f32_16x16x32_bf16 v[114:117], v[178:181], v[186:189], v[114:117]
	v_mfma_f32_16x16x32_bf16 v[102:105], v[160:163], v[194:197], v[102:105]
	v_mfma_f32_16x16x32_bf16 v[98:101], v[178:181], v[194:197], v[98:101]
	v_mfma_f32_16x16x32_bf16 v[86:89], v[160:163], v[202:205], v[86:89]
	v_mfma_f32_16x16x32_bf16 v[82:85], v[178:181], v[202:205], v[82:85]
	v_mfma_f32_16x16x32_bf16 v[70:73], v[160:163], v[210:213], v[70:73]
	v_mfma_f32_16x16x32_bf16 v[66:69], v[178:181], v[210:213], v[66:69]
	v_mfma_f32_16x16x32_bf16 v[118:121], v[174:177], v[190:193], v[118:121]
	v_mfma_f32_16x16x32_bf16 v[114:117], v[182:185], v[190:193], v[114:117]
	v_mfma_f32_16x16x32_bf16 v[102:105], v[174:177], v[198:201], v[102:105]
	v_mfma_f32_16x16x32_bf16 v[98:101], v[182:185], v[198:201], v[98:101]
	v_mfma_f32_16x16x32_bf16 v[86:89], v[174:177], v[206:209], v[86:89]
	v_mfma_f32_16x16x32_bf16 v[82:85], v[182:185], v[206:209], v[82:85]
	v_mfma_f32_16x16x32_bf16 v[70:73], v[174:177], v[214:217], v[70:73]
	v_mfma_f32_16x16x32_bf16 v[66:69], v[182:185], v[214:217], v[66:69]
	s_barrier
	s_setprio 0
	s_add_i32 s18, s18, s42
	s_mov_b32 m0, s18
	ds_read_b128 v[186:189], v172 offset:16384
	ds_read_b128 v[190:193], v172 offset:17408
	ds_read_b128 v[194:197], v172 offset:18432
	ds_read_b128 v[198:201], v172 offset:19456
	ds_read_b128 v[202:205], v172 offset:20480
	ds_read_b128 v[206:209], v172 offset:21504
	ds_read_b128 v[210:213], v172 offset:22528
	ds_read_b128 v[214:217], v172 offset:23552
	s_add_u32 s100, s14, 0x80
	s_addc_u32 s101, s15, 0
	global_load_lds_dwordx4 v142, s[10:11]
	s_add_i32 m0, s18, 0x2000
	s_add_u32 s18, s10, 0x100000
	s_addc_u32 s19, s11, 0
	s_add_i32 s20, s20, s42
	global_load_lds_dwordx4 v138, s[10:11]
	s_mov_b32 m0, s20
	s_nop 0
	global_load_lds_dwordx4 v142, s[18:19]
	s_add_i32 m0, s20, 0x2000
	s_nop 0
	global_load_lds_dwordx4 v138, s[18:19]
	s_mov_b32 m0, s51
	s_nop 0
	global_load_lds_dwordx4 v144, s[14:15]
	s_mov_b32 m0, s68
	s_nop 0
	global_load_lds_dwordx4 v140, s[14:15]
	s_waitcnt vmcnt(8)
	s_waitcnt lgkmcnt(0)
	s_nop 0
	s_nop 0
	s_setprio 1
	s_barrier
	v_mfma_f32_16x16x32_bf16 v[62:65], v[130:133], v[186:189], v[62:65]
	v_mfma_f32_16x16x32_bf16 v[58:61], v[152:155], v[186:189], v[58:61]
	v_mfma_f32_16x16x32_bf16 v[46:49], v[130:133], v[194:197], v[46:49]
	v_mfma_f32_16x16x32_bf16 v[42:45], v[152:155], v[194:197], v[42:45]
	v_mfma_f32_16x16x32_bf16 v[30:33], v[130:133], v[202:205], v[30:33]
	v_mfma_f32_16x16x32_bf16 v[26:29], v[152:155], v[202:205], v[26:29]
	v_mfma_f32_16x16x32_bf16 v[12:15], v[130:133], v[210:213], v[12:15]
	v_mfma_f32_16x16x32_bf16 v[8:11], v[152:155], v[210:213], v[8:11]
	v_mfma_f32_16x16x32_bf16 v[62:65], v[134:137], v[190:193], v[62:65]
	v_mfma_f32_16x16x32_bf16 v[58:61], v[156:159], v[190:193], v[58:61]
	v_mfma_f32_16x16x32_bf16 v[46:49], v[134:137], v[198:201], v[46:49]
	v_mfma_f32_16x16x32_bf16 v[42:45], v[156:159], v[198:201], v[42:45]
	v_mfma_f32_16x16x32_bf16 v[30:33], v[134:137], v[206:209], v[30:33]
	v_mfma_f32_16x16x32_bf16 v[26:29], v[156:159], v[206:209], v[26:29]
	v_mfma_f32_16x16x32_bf16 v[12:15], v[134:137], v[214:217], v[12:15]
	v_mfma_f32_16x16x32_bf16 v[8:11], v[156:159], v[214:217], v[8:11]
	v_mfma_f32_16x16x32_bf16 v[54:57], v[160:163], v[186:189], v[54:57]
	v_mfma_f32_16x16x32_bf16 v[50:53], v[178:181], v[186:189], v[50:53]
	v_mfma_f32_16x16x32_bf16 v[38:41], v[160:163], v[194:197], v[38:41]
	v_mfma_f32_16x16x32_bf16 v[34:37], v[178:181], v[194:197], v[34:37]
	v_mfma_f32_16x16x32_bf16 v[22:25], v[160:163], v[202:205], v[22:25]
	v_mfma_f32_16x16x32_bf16 v[18:21], v[178:181], v[202:205], v[18:21]
	v_mfma_f32_16x16x32_bf16 v[4:7], v[160:163], v[210:213], v[4:7]
	v_mfma_f32_16x16x32_bf16 v[0:3], v[178:181], v[210:213], v[0:3]
	v_mfma_f32_16x16x32_bf16 v[54:57], v[174:177], v[190:193], v[54:57]
	v_mfma_f32_16x16x32_bf16 v[50:53], v[182:185], v[190:193], v[50:53]
	v_mfma_f32_16x16x32_bf16 v[38:41], v[174:177], v[198:201], v[38:41]
	v_mfma_f32_16x16x32_bf16 v[34:37], v[182:185], v[198:201], v[34:37]
	v_mfma_f32_16x16x32_bf16 v[22:25], v[174:177], v[206:209], v[22:25]
	v_mfma_f32_16x16x32_bf16 v[18:21], v[182:185], v[206:209], v[18:21]
	v_mfma_f32_16x16x32_bf16 v[4:7], v[174:177], v[214:217], v[4:7]
	v_mfma_f32_16x16x32_bf16 v[0:3], v[182:185], v[214:217], v[0:3]
	s_barrier
; #define PG8_STAGEA(bufoff, gbase, voff) PG8_STAGE_X(bufoff, gbase, voff, AUXA)
; #define PG8_STAGEB(bufoff, gbase, voff) PG8_STAGE_X(bufoff, gbase, voff, AUXB)
; #define PG8_LDA(dst, b, h) do { _Pragma("unroll") for (int m = 0; m < 4; ++m) _Pragma("unroll") for (int k = 0; k < 2; ++k) dst[m][k] = *(const PG8_LAS bf16x8*)(lds + PG8_SA(b, h) + aoff + m * 2048 + k * 1024); } while (0)
; #define PG8_LDB(dst, b, h) do { _Pragma("unroll") for (int n = 0; n < 2; ++n) _Pragma("unroll") for (int k = 0; k < 2; ++k) dst[n][k] = *(const PG8_LAS bf16x8*)(lds + PG8_SB(b, h) + boff + n * 2048 + k * 1024); } while (0)
; #define PG8_MMA(ai, bj, At, Bt) do { if (GEMM_PRIO_MODE == 0) __builtin_amdgcn_s_setprio(1); PG8_MMA_LOOPS \
;         acc[ai][bj][m][n] = __builtin_amdgcn_mfma_f32_16x16x32_bf16(Bt[n][k], At[m][k], acc[ai][bj][m][n], 0, 0, 0); if (GEMM_PRIO_MODE == 0) __builtin_amdgcn_s_setprio(0); } while (0)
; #define PG8_WAIT_V(n) asm volatile("s_waitcnt vmcnt(" #n ")" ::: "memory")
; #define PG8_WAIT_L(n) asm volatile("s_waitcnt lgkmcnt(" #n ")" ::: "memory")
; #define PG8_BAR __builtin_amdgcn_s_barrier()
; #define PG8_SCHED __builtin_amdgcn_sched_barrier(0)
;     ...
;             PG8_LDB(B0, 1, 0); PG8_LDB(B1, 1, 1); PG8_SCHED; PG8_LDA(At, 1, 0); PG8_STAGEA(PG8_SA(0, 1), a2 + hstepA, voffA);
;             PG8_WAIT_V(8); PG8_WAIT_L(0); PG8_BAR; PG8_MMA(0, 0, At, B0); PG8_MMA(0, 1, At, B1); PG8_BAR; PG8_SCHED;
;             PG8_LDA(At, 1, 1); PG8_STAGEB(PG8_SB(1, 0), b3, voffB); PG8_STAGEB(PG8_SB(1, 1), b3 + hstepB, voffB); PG8_STAGEA(PG8_SA(1, 0), a3, voffA);
;             PG8_WAIT_V(8); PG8_WAIT_L(0); PG8_BAR; PG8_MMA(1, 0, At, B0); PG8_MMA(1, 1, At, B1); PG8_BAR; PG8_SCHED;
;     ...
;         if constexpr (ALIGN_EPI) { if (wr == 0) PG8_BAR; }
	s_setprio 0
	s_add_i32 s18, 0, 0x18000
	s_add_i32 s19, 0, 0x1c000
	ds_read_b128 v[130:133], v226 offset:32768
	ds_read_b128 v[134:137], v226 offset:33792
	ds_read_b128 v[152:155], v226 offset:34816
	ds_read_b128 v[156:159], v226 offset:35840
	ds_read_b128 v[160:163], v226 offset:49152
	ds_read_b128 v[174:177], v226 offset:50176
	ds_read_b128 v[178:181], v226 offset:51200
	ds_read_b128 v[182:185], v226 offset:52224
	s_add_u32 s14, s14, 0x100000
	s_addc_u32 s15, s15, 0
	s_mov_b32 m0, s69
	ds_read_b128 v[186:189], v172 offset:32768
	ds_read_b128 v[190:193], v172 offset:33792
	ds_read_b128 v[194:197], v172 offset:34816
	ds_read_b128 v[198:201], v172 offset:35840
	ds_read_b128 v[202:205], v172 offset:36864
	ds_read_b128 v[206:209], v172 offset:37888
	ds_read_b128 v[210:213], v172 offset:38912
	ds_read_b128 v[214:217], v172 offset:39936
	global_load_lds_dwordx4 v144, s[14:15]
	s_mov_b32 m0, s72
	s_nop 0
	global_load_lds_dwordx4 v140, s[14:15]
	s_waitcnt vmcnt(8)
	s_waitcnt lgkmcnt(0)
	s_setprio 1
	s_barrier
	v_mfma_f32_16x16x32_bf16 v[126:129], v[130:133], v[186:189], v[126:129]
	v_mfma_f32_16x16x32_bf16 v[122:125], v[152:155], v[186:189], v[122:125]
	v_mfma_f32_16x16x32_bf16 v[110:113], v[130:133], v[194:197], v[110:113]
	v_mfma_f32_16x16x32_bf16 v[106:109], v[152:155], v[194:197], v[106:109]
	v_mfma_f32_16x16x32_bf16 v[94:97], v[130:133], v[202:205], v[94:97]
	v_mfma_f32_16x16x32_bf16 v[90:93], v[152:155], v[202:205], v[90:93]
	v_mfma_f32_16x16x32_bf16 v[78:81], v[130:133], v[210:213], v[78:81]
	v_mfma_f32_16x16x32_bf16 v[74:77], v[152:155], v[210:213], v[74:77]
	v_mfma_f32_16x16x32_bf16 v[126:129], v[134:137], v[190:193], v[126:129]
	v_mfma_f32_16x16x32_bf16 v[122:125], v[156:159], v[190:193], v[122:125]
	v_mfma_f32_16x16x32_bf16 v[110:113], v[134:137], v[198:201], v[110:113]
	v_mfma_f32_16x16x32_bf16 v[106:109], v[156:159], v[198:201], v[106:109]
	v_mfma_f32_16x16x32_bf16 v[94:97], v[134:137], v[206:209], v[94:97]
	v_mfma_f32_16x16x32_bf16 v[90:93], v[156:159], v[206:209], v[90:93]
	v_mfma_f32_16x16x32_bf16 v[78:81], v[134:137], v[214:217], v[78:81]
	v_mfma_f32_16x16x32_bf16 v[74:77], v[156:159], v[214:217], v[74:77]
	v_mfma_f32_16x16x32_bf16 v[118:121], v[160:163], v[186:189], v[118:121]
	v_mfma_f32_16x16x32_bf16 v[114:117], v[178:181], v[186:189], v[114:117]
	v_mfma_f32_16x16x32_bf16 v[102:105], v[160:163], v[194:197], v[102:105]
	v_mfma_f32_16x16x32_bf16 v[98:101], v[178:181], v[194:197], v[98:101]
	v_mfma_f32_16x16x32_bf16 v[86:89], v[160:163], v[202:205], v[86:89]
	v_mfma_f32_16x16x32_bf16 v[82:85], v[178:181], v[202:205], v[82:85]
	v_mfma_f32_16x16x32_bf16 v[70:73], v[160:163], v[210:213], v[70:73]
	v_mfma_f32_16x16x32_bf16 v[66:69], v[178:181], v[210:213], v[66:69]
	v_mfma_f32_16x16x32_bf16 v[118:121], v[174:177], v[190:193], v[118:121]
	v_mfma_f32_16x16x32_bf16 v[114:117], v[182:185], v[190:193], v[114:117]
	v_mfma_f32_16x16x32_bf16 v[102:105], v[174:177], v[198:201], v[102:105]
	v_mfma_f32_16x16x32_bf16 v[98:101], v[182:185], v[198:201], v[98:101]
	v_mfma_f32_16x16x32_bf16 v[86:89], v[174:177], v[206:209], v[86:89]
	v_mfma_f32_16x16x32_bf16 v[82:85], v[182:185], v[206:209], v[82:85]
	v_mfma_f32_16x16x32_bf16 v[70:73], v[174:177], v[214:217], v[70:73]
	v_mfma_f32_16x16x32_bf16 v[66:69], v[182:185], v[214:217], v[66:69]
	s_barrier
	s_setprio 0
	s_add_i32 s14, s18, s42
	s_mov_b32 m0, s14
	ds_read_b128 v[186:189], v172 offset:49152
	ds_read_b128 v[190:193], v172 offset:50176
	ds_read_b128 v[194:197], v172 offset:51200
	ds_read_b128 v[198:201], v172 offset:52224
	ds_read_b128 v[202:205], v172 offset:53248
	ds_read_b128 v[206:209], v172 offset:54272
	ds_read_b128 v[210:213], v172 offset:55296
	ds_read_b128 v[214:217], v172 offset:56320
	s_add_u32 vcc_lo, s10, 0x80
	s_addc_u32 vcc_hi, s11, 0
	global_load_lds_dwordx4 v142, vcc
	s_add_i32 m0, s14, 0x2000
	s_add_u32 s10, s10, 0x100080
	s_addc_u32 s11, s11, 0
	s_add_i32 s14, s19, s42
	global_load_lds_dwordx4 v138, vcc
	s_mov_b32 m0, s14
	s_nop 0
	global_load_lds_dwordx4 v142, s[10:11]
	s_add_i32 m0, s14, 0x2000
	s_nop 0
	global_load_lds_dwordx4 v138, s[10:11]
	s_mov_b32 m0, s73
	s_nop 0
	global_load_lds_dwordx4 v144, s[100:101]
	s_mov_b32 m0, s82
	s_nop 0
	global_load_lds_dwordx4 v140, s[100:101]
	s_waitcnt vmcnt(8)
	s_waitcnt lgkmcnt(0)
	s_setprio 1
	s_barrier
	v_mfma_f32_16x16x32_bf16 v[62:65], v[130:133], v[186:189], v[62:65]
	v_mfma_f32_16x16x32_bf16 v[58:61], v[152:155], v[186:189], v[58:61]
	v_mfma_f32_16x16x32_bf16 v[46:49], v[130:133], v[194:197], v[46:49]
	v_mfma_f32_16x16x32_bf16 v[42:45], v[152:155], v[194:197], v[42:45]
	v_mfma_f32_16x16x32_bf16 v[30:33], v[130:133], v[202:205], v[30:33]
	v_mfma_f32_16x16x32_bf16 v[26:29], v[152:155], v[202:205], v[26:29]
	v_mfma_f32_16x16x32_bf16 v[12:15], v[130:133], v[210:213], v[12:15]
	v_mfma_f32_16x16x32_bf16 v[8:11], v[152:155], v[210:213], v[8:11]
	v_mfma_f32_16x16x32_bf16 v[62:65], v[134:137], v[190:193], v[62:65]
	v_mfma_f32_16x16x32_bf16 v[58:61], v[156:159], v[190:193], v[58:61]
	v_mfma_f32_16x16x32_bf16 v[46:49], v[134:137], v[198:201], v[46:49]
	v_mfma_f32_16x16x32_bf16 v[42:45], v[156:159], v[198:201], v[42:45]
	v_mfma_f32_16x16x32_bf16 v[30:33], v[134:137], v[206:209], v[30:33]
	v_mfma_f32_16x16x32_bf16 v[26:29], v[156:159], v[206:209], v[26:29]
	v_mfma_f32_16x16x32_bf16 v[12:15], v[134:137], v[214:217], v[12:15]
	v_mfma_f32_16x16x32_bf16 v[8:11], v[156:159], v[214:217], v[8:11]
	v_mfma_f32_16x16x32_bf16 v[54:57], v[160:163], v[186:189], v[54:57]
	v_mfma_f32_16x16x32_bf16 v[50:53], v[178:181], v[186:189], v[50:53]
	v_mfma_f32_16x16x32_bf16 v[38:41], v[160:163], v[194:197], v[38:41]
	v_mfma_f32_16x16x32_bf16 v[34:37], v[178:181], v[194:197], v[34:37]
	v_mfma_f32_16x16x32_bf16 v[22:25], v[160:163], v[202:205], v[22:25]
	v_mfma_f32_16x16x32_bf16 v[18:21], v[178:181], v[202:205], v[18:21]
	v_mfma_f32_16x16x32_bf16 v[4:7], v[160:163], v[210:213], v[4:7]
	v_mfma_f32_16x16x32_bf16 v[0:3], v[178:181], v[210:213], v[0:3]
	v_mfma_f32_16x16x32_bf16 v[54:57], v[174:177], v[190:193], v[54:57]
	v_mfma_f32_16x16x32_bf16 v[50:53], v[182:185], v[190:193], v[50:53]
	v_mfma_f32_16x16x32_bf16 v[38:41], v[174:177], v[198:201], v[38:41]
	v_mfma_f32_16x16x32_bf16 v[34:37], v[182:185], v[198:201], v[34:37]
	v_mfma_f32_16x16x32_bf16 v[22:25], v[174:177], v[206:209], v[22:25]
	v_mfma_f32_16x16x32_bf16 v[18:21], v[182:185], v[206:209], v[18:21]
	v_mfma_f32_16x16x32_bf16 v[4:7], v[174:177], v[214:217], v[4:7]
	v_mfma_f32_16x16x32_bf16 v[0:3], v[182:185], v[214:217], v[0:3]
	s_barrier
	s_setprio 0
	s_add_i32 s27, s27, 2
	s_add_u32 s8, s8, 0x100
	s_addc_u32 s9, s9, 0
	s_add_u32 s0, s0, 0x100
	s_addc_u32 s1, s1, 0
	s_cmp_gt_u32 s27, 61
	s_cbranch_scc0 .LBB0_129
	s_mov_b32 s98, 1
	s_and_b64 vcc, exec, s[24:25]
	s_cbranch_vccz .LBB0_132
	s_barrier

; #define PG8_STAGEA(bufoff, gbase, voff) PG8_STAGE_X(bufoff, gbase, voff, AUXA)
; #define PG8_STAGEB(bufoff, gbase, voff) PG8_STAGE_X(bufoff, gbase, voff, AUXB)
; #define PG8_WAIT_V(n) asm volatile("s_waitcnt vmcnt(" #n ")" ::: "memory")
; #define PG8_BAR __builtin_amdgcn_s_barrier()
;     ...
;     const int wid = __builtin_amdgcn_readfirstlane(tid >> 6), lane = tid & 63, wr = wid >> 2, wc = wid & 3, fr = lane & 15, fq = lane >> 4;
;     const int K = g.K, nt = K / BK;
;     unsigned voffA[2], voffB[2];
; #pragma unroll
;     for (int i = 0; i < 2; ++i) { int R, C; stage_rc(tid * 16 + i * 8192, R, C); const int Rb = Epi::PERM ? ((R & ~31) + perm32(R & 31)) : R;
;         voffA[i] = (unsigned)(R * (ABLK ? 64 : g.lda) + C) * 2u; voffB[i] = (unsigned)(Rb * (BBLK ? 64 : g.ldb) + C) * 2u; }
;     const size_t kstepA = ABLK ? 32768 : 128, kstepB = BBLK ? 32768 : 128;
;     const size_t hstepA = (size_t)HALF * (ABLK ? 64 : g.lda) * 2, hstepB = (size_t)HALF * (BBLK ? 64 : g.ldb) * 2;
;     const size_t tstepA = ABLK ? (size_t)(K / 64) * 32768 : (size_t)256 * g.lda * 2, tstepB = BBLK ? (size_t)(K / 64) * 32768 : (size_t)256 * g.ldb * 2;
;     const unsigned ldsw = (unsigned)wid * 1024u;
;     const int aoff = lds_byte(wr * 64 + fr, fq * 8), boff = lds_byte(wc * 32 + fr, fq * 8);
;     ...
;     if constexpr (SP2) {
;         PG8_STAGEB(PG8_SB(0, 0), cB, voffB); PG8_STAGEB(PG8_SB(0, 1), cB + hstepB, voffB); PG8_STAGEA(PG8_SA(0, 0), cA, voffA); PG8_STAGEA(PG8_SA(0, 1), cA + hstepA, voffA);
;         if (wr == 1) PG8_BAR;
;         PG8_WAIT_V(2); PG8_BAR;
;         PG8_STAGEB(PG8_SB(1, 0), cB + kstepB, voffB); PG8_STAGEA(PG8_SA(1, 0), cA + kstepA, voffA); PG8_STAGEB(PG8_SB(1, 1), cB + hstepB + kstepB, voffB);
;         PG8_WAIT_V(6); PG8_BAR;
.LBB0_552:
	s_mov_b32 s98, 0
	v_bfe_u32 v18, v6, 4, 2
	v_and_b32_e32 v7, 15, v6
	v_lshlrev_b32_e32 v20, 4, v18
	v_lshlrev_b32_e32 v6, 2, v6
	s_and_b32 s51, s6, 3
	v_lshl_or_b32 v156, s1, 6, v7
	v_lshl_or_b32 v7, v7, 6, v20
	s_lshl_b32 s1, s1, 13
	v_and_b32_e32 v6, 32, v6
	v_lshl_add_u64 v[8:9], s[40:41], 0, v[16:17]
	v_mov_b32_e32 v139, v17
	v_readlane_b32 s16, v254, 4
	v_bitop3_b32 v20, v7, s1, v6 bitop3:0xde
	s_lshl_b32 s1, s51, 12
	v_lshl_add_u64 v[10:11], s[40:41], 0, v[138:139]
	v_mov_b32_e32 v143, v17
	v_readlane_b32 s17, v254, 5
	v_bitop3_b32 v157, v7, s1, v6 bitop3:0xde
	s_add_i32 m0, s13, 0x18000
	v_lshl_add_u64 v[6:7], v[8:9], 0, s[86:87]
	v_lshl_add_u64 v[12:13], s[16:17], 0, v[142:143]
	v_mov_b32_e32 v141, v17
	s_waitcnt vmcnt(2)
	s_barrier
	global_load_lds_dwordx4 v[6:7], off
	v_lshl_add_u64 v[6:7], v[10:11], 0, s[86:87]
	s_add_i32 m0, s13, 0x1a000
	s_add_i32 s68, s13, 0x8000
	s_add_i32 s69, s13, 0xa000
	v_lshl_add_u64 v[14:15], s[16:17], 0, v[140:141]
	global_load_lds_dwordx4 v[6:7], off
	v_lshl_add_u64 v[6:7], v[12:13], 0, s[86:87]
	s_mov_b32 m0, s68
	s_add_u32 s6, s40, 0x100080
	global_load_lds_dwordx4 v[6:7], off
	v_lshl_add_u64 v[6:7], v[14:15], 0, s[86:87]
	s_mov_b32 m0, s69
	s_addc_u32 s7, s41, 0
	global_load_lds_dwordx4 v[6:7], off
	s_add_i32 m0, s13, 0x1c000
	v_lshl_add_u64 v[6:7], s[6:7], 0, v[16:17]
	global_load_lds_dwordx4 v[6:7], off
	v_lshl_add_u64 v[6:7], s[6:7], 0, v[138:139]
	s_add_i32 m0, s13, 0x1e000
	s_cmpk_lt_u32 s0, 0x100
	global_load_lds_dwordx4 v[6:7], off
	v_xor_b32_e32 v6, 16, v233
	v_cmp_lt_i32_e32 vcc, v6, v235
	v_readlane_b32 s0, v254, 19
	v_readlane_b32 s1, v254, 20
	v_cndmask_b32_e32 v6, v233, v6, vcc
	v_lshlrev_b32_e32 v159, 2, v6
	v_xor_b32_e32 v6, 32, v233
	v_cmp_lt_i32_e32 vcc, v6, v235
	s_waitcnt vmcnt(6)
	s_mov_b32 s73, s0
	v_readlane_b32 s0, v254, 17
	v_cndmask_b32_e32 v6, v233, v6, vcc
	v_lshlrev_b32_e32 v160, 2, v6
	v_lshlrev_b32_e32 v6, 16, v4
	v_and_b32_e32 v6, 0xfffe0000, v6
	v_lshl_add_u32 v3, v3, 13, v6
	v_and_b32_e32 v4, 1, v4
	v_lshl_or_b32 v3, v4, 6, v3
	v_lshl_add_u32 v144, v5, 1, v3
	v_lshlrev_b32_e32 v3, 16, v0
	v_and_b32_e32 v3, 0xfffe0000, v3
	v_lshl_add_u32 v1, v1, 13, v3
	v_and_b32_e32 v0, 1, v0
	v_lshlrev_b32_e32 v19, 3, v18
	v_lshl_or_b32 v0, v0, 6, v1
	v_readlane_b32 s1, v254, 18
	v_lshl_or_b32 v158, s51, 5, v19
	s_cselect_b64 s[18:19], -1, 0
	s_mov_b32 s72, 0
	v_cmp_eq_u32_e64 s[10:11], 0, v18
	v_mov_b32_e32 v145, v17
	v_lshl_add_u32 v146, v2, 1, v0
	v_mov_b32_e32 v147, v17
	v_add_u32_e32 v161, 0, v20
	s_mov_b32 s78, s0
	s_mov_b64 s[0:1], s[16:17]
	s_barrier
	s_branch .LBB0_555

; #define PG8_STAGEA(bufoff, gbase, voff) PG8_STAGE_X(bufoff, gbase, voff, AUXA)
; #define PG8_LDA(dst, b, h) do { _Pragma("unroll") for (int m = 0; m < 4; ++m) _Pragma("unroll") for (int k = 0; k < 2; ++k) dst[m][k] = *(const PG8_LAS bf16x8*)(lds + PG8_SA(b, h) + aoff + m * 2048 + k * 1024); } while (0)
; #define PG8_LDB(dst, b, h) do { _Pragma("unroll") for (int n = 0; n < 2; ++n) _Pragma("unroll") for (int k = 0; k < 2; ++k) dst[n][k] = *(const PG8_LAS bf16x8*)(lds + PG8_SB(b, h) + boff + n * 2048 + k * 1024); } while (0)
; #define PG8_MMA(ai, bj, At, Bt) do { if (GEMM_PRIO_MODE == 0) __builtin_amdgcn_s_setprio(1); PG8_MMA_LOOPS \
;         acc[ai][bj][m][n] = __builtin_amdgcn_mfma_f32_16x16x32_bf16(Bt[n][k], At[m][k], acc[ai][bj][m][n], 0, 0, 0); if (GEMM_PRIO_MODE == 0) __builtin_amdgcn_s_setprio(0); } while (0)
; #define PG8_WAIT_VR(n, nr, flag) asm volatile("s_cmp_eq_u32 %0, 0\n\ts_cbranch_scc1 .Lpg8s%=\n\ts_waitcnt vmcnt(" #nr ")\n\ts_branch .Lpg8d%=\n.Lpg8s%=:\n\ts_waitcnt vmcnt(" #n ")\n.Lpg8d%=:" :: "s"(flag) : "memory", "scc")
; #define PG8_WAIT_L(n) asm volatile("s_waitcnt lgkmcnt(" #n ")" ::: "memory")
; #define PG8_BAR __builtin_amdgcn_s_barrier()
; #define PG8_SCHED __builtin_amdgcn_sched_barrier(0)
;     ...
;         for (int t = t0; t < nt; t += 2) {
;             const bool last = (t == nt - 2);
;             const char* a1 = cA + (size_t)(t + 1) * kstepA;
;             const char* a2 = last ? nA : cA + (size_t)(t + 2) * kstepA; const char* b2 = last ? nB : cB + (size_t)(t + 2) * kstepB;
;             const char* a3 = a2 + kstepA; const char* b3 = b2 + kstepB;
;             if (last && has_next) S.a_ready(nxt);
;             if constexpr (SP2) {
;             PG8_LDB(B0, 0, 0); PG8_LDB(B1, 0, 1); PG8_SCHED; PG8_LDA(At, 0, 0); PG8_STAGEA(PG8_SA(1, 1), a1 + hstepA, voffA);
;     ...
;             const int relax = __builtin_amdgcn_readfirstlane((t == 0 && ui > 0) ? 1 : 0);
;             PG8_WAIT_VR(8, 24, relax); PG8_WAIT_L(0); PG8_BAR; PG8_MMA(0, 0, At, B0); PG8_MMA(0, 1, At, B1); PG8_BAR; PG8_SCHED;
.LBB0_557:
	s_ashr_i32 s21, s20, 31
	s_lshl_b64 s[6:7], s[20:21], 21
	s_add_u32 s24, s60, s6
	s_addc_u32 s25, s61, s7
	s_and_b64 s[6:7], s[26:27], exec
	s_cselect_b32 s21, s25, s1
	s_cselect_b32 s82, s24, s0
	s_ashr_i32 s23, s22, 31
	s_lshl_b64 s[6:7], s[22:23], 21
	s_add_u32 s36, s4, s6
	s_addc_u32 s37, s5, s7
	s_and_b64 s[6:7], s[26:27], exec
	s_cselect_b32 s23, s37, s41
	s_cselect_b32 s83, s36, s40
	s_add_u32 s38, s0, 0x100080
	s_addc_u32 s39, s1, 0
	s_add_u32 s0, s40, 0x100
	s_addc_u32 s1, s41, 0
	s_mov_b32 s90, -2
	s_waitcnt lgkmcnt(0)
	s_waitcnt vmcnt(0)
	s_add_u32 s6, s38, 0xfff00080
	s_addc_u32 s7, s39, -1
	s_add_i32 s91, 0, 0x10000
	s_cmp_eq_u32 s90, 60
	s_cselect_b32 s41, s21, s7
	s_cselect_b32 s40, s82, s6
	s_cselect_b32 s17, s23, s1
	s_cselect_b32 s16, s83, s0
	s_add_i32 s94, 0, 0x14000
	v_add_u32_e32 v152, s91, v157
	v_add_u32_e32 v174, s94, v157
	ds_read_b128 v[130:133], v152
	ds_read_b128 v[134:137], v152 offset:1024
	ds_read_b128 v[148:151], v152 offset:2048
	ds_read_b128 v[152:155], v152 offset:3072
	ds_read_b128 v[162:165], v174
	ds_read_b128 v[166:169], v174 offset:1024
	ds_read_b128 v[170:173], v174 offset:2048
	ds_read_b128 v[174:177], v174 offset:3072
	v_lshl_add_u64 v[210:211], s[38:39], 0, v[144:145]
	s_add_i32 m0, s13, 0xc000
	ds_read_b128 v[178:181], v161
	ds_read_b128 v[182:185], v161 offset:1024
	ds_read_b128 v[186:189], v161 offset:2048
	ds_read_b128 v[190:193], v161 offset:3072
	ds_read_b128 v[194:197], v161 offset:4096
	ds_read_b128 v[198:201], v161 offset:5120
	ds_read_b128 v[202:205], v161 offset:6144
	ds_read_b128 v[206:209], v161 offset:7168
	global_load_lds_dwordx4 v[210:211], off
	v_lshl_add_u64 v[210:211], s[38:39], 0, v[146:147]
	s_add_i32 m0, s13, 0xe000
	s_nop 0
	global_load_lds_dwordx4 v[210:211], off
	s_cmp_eq_u32 s98, 0
	s_cbranch_scc1 .Lrelax_s_lbb0_558_0
	s_waitcnt vmcnt(24)
	s_branch .Lrelax_d_lbb0_558_0

; #define PG8_STAGEA(bufoff, gbase, voff) PG8_STAGE_X(bufoff, gbase, voff, AUXA)
; #define PG8_STAGEB(bufoff, gbase, voff) PG8_STAGE_X(bufoff, gbase, voff, AUXB)
; #define PG8_LDA(dst, b, h) do { _Pragma("unroll") for (int m = 0; m < 4; ++m) _Pragma("unroll") for (int k = 0; k < 2; ++k) dst[m][k] = *(const PG8_LAS bf16x8*)(lds + PG8_SA(b, h) + aoff + m * 2048 + k * 1024); } while (0)
; #define PG8_MMA(ai, bj, At, Bt) do { if (GEMM_PRIO_MODE == 0) __builtin_amdgcn_s_setprio(1); PG8_MMA_LOOPS \
;         acc[ai][bj][m][n] = __builtin_amdgcn_mfma_f32_16x16x32_bf16(Bt[n][k], At[m][k], acc[ai][bj][m][n], 0, 0, 0); if (GEMM_PRIO_MODE == 0) __builtin_amdgcn_s_setprio(0); } while (0)
; #define PG8_WAIT_V(n) asm volatile("s_waitcnt vmcnt(" #n ")" ::: "memory")
; #define PG8_WAIT_VR(n, nr, flag) asm volatile("s_cmp_eq_u32 %0, 0\n\ts_cbranch_scc1 .Lpg8s%=\n\ts_waitcnt vmcnt(" #nr ")\n\ts_branch .Lpg8d%=\n.Lpg8s%=:\n\ts_waitcnt vmcnt(" #n ")\n.Lpg8d%=:" :: "s"(flag) : "memory", "scc")
; #define PG8_WAIT_L(n) asm volatile("s_waitcnt lgkmcnt(" #n ")" ::: "memory")
; #define PG8_BAR __builtin_amdgcn_s_barrier()
; #define PG8_SCHED __builtin_amdgcn_sched_barrier(0)
;     ...
;             PG8_WAIT_VR(8, 24, relax); PG8_WAIT_L(0); PG8_BAR; PG8_MMA(0, 0, At, B0); PG8_MMA(0, 1, At, B1); PG8_BAR; PG8_SCHED;
;     ...
;             PG8_WAIT_V(8); PG8_WAIT_L(0); PG8_BAR; PG8_MMA(0, 0, At, B0); PG8_MMA(0, 1, At, B1); PG8_BAR; PG8_SCHED;
;     ...
;             PG8_LDA(At, 0, 1); PG8_STAGEB(PG8_SB(0, 0), b2, voffB); PG8_STAGEB(PG8_SB(0, 1), b2 + hstepB, voffB); PG8_STAGEA(PG8_SA(0, 0), a2, voffA);
;     ...
;             PG8_WAIT_VR(8, 24, relax); PG8_WAIT_L(0); PG8_BAR; PG8_MMA(1, 0, At, B0); PG8_MMA(1, 1, At, B1); PG8_BAR; PG8_SCHED;
.Lrelax_d_lbb0_558_0:
	s_waitcnt lgkmcnt(0)
	s_setprio 1
	s_barrier
	v_mfma_f32_16x16x32_bf16 v[126:129], v[130:133], v[178:181], 0
	v_mfma_f32_16x16x32_bf16 v[122:125], v[148:151], v[178:181], 0
	v_mfma_f32_16x16x32_bf16 v[110:113], v[130:133], v[186:189], 0
	v_mfma_f32_16x16x32_bf16 v[106:109], v[148:151], v[186:189], 0
	v_mfma_f32_16x16x32_bf16 v[94:97], v[130:133], v[194:197], 0
	v_mfma_f32_16x16x32_bf16 v[90:93], v[148:151], v[194:197], 0
	v_mfma_f32_16x16x32_bf16 v[78:81], v[130:133], v[202:205], 0
	v_mfma_f32_16x16x32_bf16 v[74:77], v[148:151], v[202:205], 0
	v_mfma_f32_16x16x32_bf16 v[126:129], v[134:137], v[182:185], v[126:129]
	v_mfma_f32_16x16x32_bf16 v[122:125], v[152:155], v[182:185], v[122:125]
	v_mfma_f32_16x16x32_bf16 v[110:113], v[134:137], v[190:193], v[110:113]
	v_mfma_f32_16x16x32_bf16 v[106:109], v[152:155], v[190:193], v[106:109]
	v_mfma_f32_16x16x32_bf16 v[94:97], v[134:137], v[198:201], v[94:97]
	v_mfma_f32_16x16x32_bf16 v[90:93], v[152:155], v[198:201], v[90:93]
	v_mfma_f32_16x16x32_bf16 v[78:81], v[134:137], v[206:209], v[78:81]
	v_mfma_f32_16x16x32_bf16 v[74:77], v[152:155], v[206:209], v[74:77]
	v_mfma_f32_16x16x32_bf16 v[118:121], v[162:165], v[178:181], 0
	v_mfma_f32_16x16x32_bf16 v[114:117], v[170:173], v[178:181], 0
	v_mfma_f32_16x16x32_bf16 v[102:105], v[162:165], v[186:189], 0
	v_mfma_f32_16x16x32_bf16 v[98:101], v[170:173], v[186:189], 0
	v_mfma_f32_16x16x32_bf16 v[86:89], v[162:165], v[194:197], 0
	v_mfma_f32_16x16x32_bf16 v[82:85], v[170:173], v[194:197], 0
	v_mfma_f32_16x16x32_bf16 v[70:73], v[162:165], v[202:205], 0
	v_mfma_f32_16x16x32_bf16 v[66:69], v[170:173], v[202:205], 0
	v_mfma_f32_16x16x32_bf16 v[118:121], v[166:169], v[182:185], v[118:121]
	v_mfma_f32_16x16x32_bf16 v[114:117], v[174:177], v[182:185], v[114:117]
	v_mfma_f32_16x16x32_bf16 v[102:105], v[166:169], v[190:193], v[102:105]
	v_mfma_f32_16x16x32_bf16 v[98:101], v[174:177], v[190:193], v[98:101]
	v_mfma_f32_16x16x32_bf16 v[86:89], v[166:169], v[198:201], v[86:89]
	v_mfma_f32_16x16x32_bf16 v[82:85], v[174:177], v[198:201], v[82:85]
	v_mfma_f32_16x16x32_bf16 v[70:73], v[166:169], v[206:209], v[70:73]
	v_mfma_f32_16x16x32_bf16 v[66:69], v[174:177], v[206:209], v[66:69]
	s_barrier
	s_setprio 0
	s_add_i32 s6, s91, s12
	v_lshl_add_u64 v[210:211], s[16:17], 0, v[16:17]
	s_mov_b32 m0, s6
	ds_read_b128 v[178:181], v161 offset:16384
	ds_read_b128 v[182:185], v161 offset:17408
	ds_read_b128 v[186:189], v161 offset:18432
	ds_read_b128 v[190:193], v161 offset:19456
	ds_read_b128 v[194:197], v161 offset:20480
	ds_read_b128 v[198:201], v161 offset:21504
	ds_read_b128 v[202:205], v161 offset:22528
	ds_read_b128 v[206:209], v161 offset:23552
	global_load_lds_dwordx4 v[210:211], off
	s_add_i32 m0, s6, 0x2000
	s_add_u32 s6, s16, 0x100000
	v_lshl_add_u64 v[212:213], s[16:17], 0, v[138:139]
	s_addc_u32 s7, s17, 0
	s_add_i32 s91, s94, s12
	global_load_lds_dwordx4 v[212:213], off
	v_lshl_add_u64 v[214:215], s[6:7], 0, v[16:17]
	s_mov_b32 m0, s91
	v_lshl_add_u64 v[216:217], s[40:41], 0, v[140:141]
	global_load_lds_dwordx4 v[214:215], off
	v_lshl_add_u64 v[214:215], s[6:7], 0, v[138:139]
	s_add_i32 m0, s91, 0x2000
	s_nop 0
	global_load_lds_dwordx4 v[214:215], off
	v_lshl_add_u64 v[214:215], s[40:41], 0, v[142:143]
	s_mov_b32 m0, s13
	s_nop 0
	global_load_lds_dwordx4 v[214:215], off
	s_mov_b32 m0, s42
	s_nop 0
	global_load_lds_dwordx4 v[216:217], off
	s_cmp_eq_u32 s98, 0
	s_cbranch_scc1 .Lrelax_s_lbb0_558_1
	s_waitcnt vmcnt(24)
	s_branch .Lrelax_d_lbb0_558_1

; #define PG8_STAGEA(bufoff, gbase, voff) PG8_STAGE_X(bufoff, gbase, voff, AUXA)
; #define PG8_LDA(dst, b, h) do { _Pragma("unroll") for (int m = 0; m < 4; ++m) _Pragma("unroll") for (int k = 0; k < 2; ++k) dst[m][k] = *(const PG8_LAS bf16x8*)(lds + PG8_SA(b, h) + aoff + m * 2048 + k * 1024); } while (0)
; #define PG8_LDB(dst, b, h) do { _Pragma("unroll") for (int n = 0; n < 2; ++n) _Pragma("unroll") for (int k = 0; k < 2; ++k) dst[n][k] = *(const PG8_LAS bf16x8*)(lds + PG8_SB(b, h) + boff + n * 2048 + k * 1024); } while (0)
; #define PG8_MMA(ai, bj, At, Bt) do { if (GEMM_PRIO_MODE == 0) __builtin_amdgcn_s_setprio(1); PG8_MMA_LOOPS \
;         acc[ai][bj][m][n] = __builtin_amdgcn_mfma_f32_16x16x32_bf16(Bt[n][k], At[m][k], acc[ai][bj][m][n], 0, 0, 0); if (GEMM_PRIO_MODE == 0) __builtin_amdgcn_s_setprio(0); } while (0)
; #define PG8_WAIT_V(n) asm volatile("s_waitcnt vmcnt(" #n ")" ::: "memory")
; #define PG8_WAIT_VR(n, nr, flag) asm volatile("s_cmp_eq_u32 %0, 0\n\ts_cbranch_scc1 .Lpg8s%=\n\ts_waitcnt vmcnt(" #nr ")\n\ts_branch .Lpg8d%=\n.Lpg8s%=:\n\ts_waitcnt vmcnt(" #n ")\n.Lpg8d%=:" :: "s"(flag) : "memory", "scc")
; #define PG8_WAIT_L(n) asm volatile("s_waitcnt lgkmcnt(" #n ")" ::: "memory")
; #define PG8_BAR __builtin_amdgcn_s_barrier()
; #define PG8_SCHED __builtin_amdgcn_sched_barrier(0)
;     ...
;             PG8_WAIT_VR(8, 24, relax); PG8_WAIT_L(0); PG8_BAR; PG8_MMA(1, 0, At, B0); PG8_MMA(1, 1, At, B1); PG8_BAR; PG8_SCHED;
;     ...
;             PG8_WAIT_V(8); PG8_WAIT_L(0); PG8_BAR; PG8_MMA(1, 0, At, B0); PG8_MMA(1, 1, At, B1); PG8_BAR; PG8_SCHED;
;     ...
;             PG8_LDB(B0, 1, 0); PG8_LDB(B1, 1, 1); PG8_SCHED; PG8_LDA(At, 1, 0); PG8_STAGEA(PG8_SA(0, 1), a2 + hstepA, voffA);
;             PG8_WAIT_V(8); PG8_WAIT_L(0); PG8_BAR; PG8_MMA(0, 0, At, B0); PG8_MMA(0, 1, At, B1); PG8_BAR; PG8_SCHED;
.Lrelax_d_lbb0_558_1:
	s_waitcnt lgkmcnt(0)
	s_setprio 1
	s_barrier
	v_mfma_f32_16x16x32_bf16 v[62:65], v[130:133], v[178:181], 0
	v_mfma_f32_16x16x32_bf16 v[58:61], v[148:151], v[178:181], 0
	v_mfma_f32_16x16x32_bf16 v[46:49], v[130:133], v[186:189], 0
	v_mfma_f32_16x16x32_bf16 v[42:45], v[148:151], v[186:189], 0
	v_mfma_f32_16x16x32_bf16 v[30:33], v[130:133], v[194:197], 0
	v_mfma_f32_16x16x32_bf16 v[26:29], v[148:151], v[194:197], 0
	v_mfma_f32_16x16x32_bf16 v[12:15], v[130:133], v[202:205], 0
	v_mfma_f32_16x16x32_bf16 v[8:11], v[148:151], v[202:205], 0
	v_mfma_f32_16x16x32_bf16 v[62:65], v[134:137], v[182:185], v[62:65]
	v_mfma_f32_16x16x32_bf16 v[58:61], v[152:155], v[182:185], v[58:61]
	v_mfma_f32_16x16x32_bf16 v[46:49], v[134:137], v[190:193], v[46:49]
	v_mfma_f32_16x16x32_bf16 v[42:45], v[152:155], v[190:193], v[42:45]
	v_mfma_f32_16x16x32_bf16 v[30:33], v[134:137], v[198:201], v[30:33]
	v_mfma_f32_16x16x32_bf16 v[26:29], v[152:155], v[198:201], v[26:29]
	v_mfma_f32_16x16x32_bf16 v[12:15], v[134:137], v[206:209], v[12:15]
	v_mfma_f32_16x16x32_bf16 v[8:11], v[152:155], v[206:209], v[8:11]
	v_mfma_f32_16x16x32_bf16 v[54:57], v[162:165], v[178:181], 0
	v_mfma_f32_16x16x32_bf16 v[50:53], v[170:173], v[178:181], 0
	v_mfma_f32_16x16x32_bf16 v[38:41], v[162:165], v[186:189], 0
	v_mfma_f32_16x16x32_bf16 v[34:37], v[170:173], v[186:189], 0
	v_mfma_f32_16x16x32_bf16 v[22:25], v[162:165], v[194:197], 0
	v_mfma_f32_16x16x32_bf16 v[18:21], v[170:173], v[194:197], 0
	v_mfma_f32_16x16x32_bf16 v[4:7], v[162:165], v[202:205], 0
	v_mfma_f32_16x16x32_bf16 v[0:3], v[170:173], v[202:205], 0
	v_mfma_f32_16x16x32_bf16 v[54:57], v[166:169], v[182:185], v[54:57]
	v_mfma_f32_16x16x32_bf16 v[50:53], v[174:177], v[182:185], v[50:53]
	v_mfma_f32_16x16x32_bf16 v[38:41], v[166:169], v[190:193], v[38:41]
	v_mfma_f32_16x16x32_bf16 v[34:37], v[174:177], v[190:193], v[34:37]
	v_mfma_f32_16x16x32_bf16 v[22:25], v[166:169], v[198:201], v[22:25]
	v_mfma_f32_16x16x32_bf16 v[18:21], v[174:177], v[198:201], v[18:21]
	v_mfma_f32_16x16x32_bf16 v[4:7], v[166:169], v[206:209], v[4:7]
	v_mfma_f32_16x16x32_bf16 v[0:3], v[174:177], v[206:209], v[0:3]
	s_barrier
	s_setprio 0
	s_add_i32 s91, 0, 0x18000
	s_add_i32 s94, 0, 0x1c000
	v_add_u32_e32 v152, s91, v157
	v_add_u32_e32 v174, s94, v157
	ds_read_b128 v[130:133], v152
	ds_read_b128 v[134:137], v152 offset:1024
	ds_read_b128 v[148:151], v152 offset:2048
	ds_read_b128 v[152:155], v152 offset:3072
	ds_read_b128 v[162:165], v174
	ds_read_b128 v[166:169], v174 offset:1024
	ds_read_b128 v[170:173], v174 offset:2048
	ds_read_b128 v[174:177], v174 offset:3072
	s_add_u32 s6, s40, 0x100000
	s_addc_u32 s7, s41, 0
	s_mov_b32 m0, s43
	v_lshl_add_u64 v[218:219], s[6:7], 0, v[142:143]
	ds_read_b128 v[178:181], v161 offset:32768
	ds_read_b128 v[182:185], v161 offset:33792
	ds_read_b128 v[186:189], v161 offset:34816
	ds_read_b128 v[190:193], v161 offset:35840
	ds_read_b128 v[194:197], v161 offset:36864
	ds_read_b128 v[198:201], v161 offset:37888
	ds_read_b128 v[202:205], v161 offset:38912
	ds_read_b128 v[206:209], v161 offset:39936
	global_load_lds_dwordx4 v[218:219], off
	v_lshl_add_u64 v[218:219], s[6:7], 0, v[140:141]
	s_mov_b32 m0, s50
	s_nop 0
	global_load_lds_dwordx4 v[218:219], off
	s_waitcnt vmcnt(8)
	s_waitcnt lgkmcnt(0)
	s_setprio 1
	s_barrier
	v_mfma_f32_16x16x32_bf16 v[126:129], v[130:133], v[178:181], v[126:129]
	v_mfma_f32_16x16x32_bf16 v[122:125], v[148:151], v[178:181], v[122:125]
	v_mfma_f32_16x16x32_bf16 v[110:113], v[130:133], v[186:189], v[110:113]
	v_mfma_f32_16x16x32_bf16 v[106:109], v[148:151], v[186:189], v[106:109]
	v_mfma_f32_16x16x32_bf16 v[94:97], v[130:133], v[194:197], v[94:97]
	v_mfma_f32_16x16x32_bf16 v[90:93], v[148:151], v[194:197], v[90:93]
	v_mfma_f32_16x16x32_bf16 v[78:81], v[130:133], v[202:205], v[78:81]
	v_mfma_f32_16x16x32_bf16 v[74:77], v[148:151], v[202:205], v[74:77]
	v_mfma_f32_16x16x32_bf16 v[126:129], v[134:137], v[182:185], v[126:129]
	v_mfma_f32_16x16x32_bf16 v[122:125], v[152:155], v[182:185], v[122:125]
	v_mfma_f32_16x16x32_bf16 v[110:113], v[134:137], v[190:193], v[110:113]
	v_mfma_f32_16x16x32_bf16 v[106:109], v[152:155], v[190:193], v[106:109]
	v_mfma_f32_16x16x32_bf16 v[94:97], v[134:137], v[198:201], v[94:97]
	v_mfma_f32_16x16x32_bf16 v[90:93], v[152:155], v[198:201], v[90:93]
	v_mfma_f32_16x16x32_bf16 v[78:81], v[134:137], v[206:209], v[78:81]
	v_mfma_f32_16x16x32_bf16 v[74:77], v[152:155], v[206:209], v[74:77]
	v_mfma_f32_16x16x32_bf16 v[118:121], v[162:165], v[178:181], v[118:121]
	v_mfma_f32_16x16x32_bf16 v[114:117], v[170:173], v[178:181], v[114:117]
	v_mfma_f32_16x16x32_bf16 v[102:105], v[162:165], v[186:189], v[102:105]
	v_mfma_f32_16x16x32_bf16 v[98:101], v[170:173], v[186:189], v[98:101]
	v_mfma_f32_16x16x32_bf16 v[86:89], v[162:165], v[194:197], v[86:89]
	v_mfma_f32_16x16x32_bf16 v[82:85], v[170:173], v[194:197], v[82:85]
	v_mfma_f32_16x16x32_bf16 v[70:73], v[162:165], v[202:205], v[70:73]
	v_mfma_f32_16x16x32_bf16 v[66:69], v[170:173], v[202:205], v[66:69]
	v_mfma_f32_16x16x32_bf16 v[118:121], v[166:169], v[182:185], v[118:121]
	v_mfma_f32_16x16x32_bf16 v[114:117], v[174:177], v[182:185], v[114:117]
	v_mfma_f32_16x16x32_bf16 v[102:105], v[166:169], v[190:193], v[102:105]
	v_mfma_f32_16x16x32_bf16 v[98:101], v[174:177], v[190:193], v[98:101]
	v_mfma_f32_16x16x32_bf16 v[86:89], v[166:169], v[198:201], v[86:89]
	v_mfma_f32_16x16x32_bf16 v[82:85], v[174:177], v[198:201], v[82:85]
	v_mfma_f32_16x16x32_bf16 v[70:73], v[166:169], v[206:209], v[70:73]
	v_mfma_f32_16x16x32_bf16 v[66:69], v[174:177], v[206:209], v[66:69]
	s_barrier
; #define PG8_STAGEA(bufoff, gbase, voff) PG8_STAGE_X(bufoff, gbase, voff, AUXA)
; #define PG8_STAGEB(bufoff, gbase, voff) PG8_STAGE_X(bufoff, gbase, voff, AUXB)
; #define PG8_LDA(dst, b, h) do { _Pragma("unroll") for (int m = 0; m < 4; ++m) _Pragma("unroll") for (int k = 0; k < 2; ++k) dst[m][k] = *(const PG8_LAS bf16x8*)(lds + PG8_SA(b, h) + aoff + m * 2048 + k * 1024); } while (0)
; #define PG8_WAIT_V(n) asm volatile("s_waitcnt vmcnt(" #n ")" ::: "memory")
; #define PG8_WAIT_L(n) asm volatile("s_waitcnt lgkmcnt(" #n ")" ::: "memory")
;     ...
;         for (int t = t0; t < nt; t += 2) {
;             const bool last = (t == nt - 2);
;             const char* a1 = cA + (size_t)(t + 1) * kstepA;
;             const char* a2 = last ? nA : cA + (size_t)(t + 2) * kstepA; const char* b2 = last ? nB : cB + (size_t)(t + 2) * kstepB;
;             const char* a3 = a2 + kstepA; const char* b3 = b2 + kstepB;
;             if (last && has_next) S.a_ready(nxt);
;             if constexpr (SP2) {
;             PG8_LDB(B0, 0, 0); PG8_LDB(B1, 0, 1); PG8_SCHED; PG8_LDA(At, 0, 0); PG8_STAGEA(PG8_SA(1, 1), a1 + hstepA, voffA);
;     ...
;             const int relax = __builtin_amdgcn_readfirstlane((t == 0 && ui > 0) ? 1 : 0);
;             PG8_WAIT_VR(8, 24, relax); PG8_WAIT_L(0); PG8_BAR; PG8_MMA(0, 0, At, B0); PG8_MMA(0, 1, At, B1); PG8_BAR; PG8_SCHED;
;     ...
;             PG8_WAIT_V(8); PG8_WAIT_L(0); PG8_BAR; PG8_MMA(0, 0, At, B0); PG8_MMA(0, 1, At, B1); PG8_BAR; PG8_SCHED;
;     ...
;             PG8_LDA(At, 0, 1); PG8_STAGEB(PG8_SB(0, 0), b2, voffB); PG8_STAGEB(PG8_SB(0, 1), b2 + hstepB, voffB); PG8_STAGEA(PG8_SA(0, 0), a2, voffA);
;     ...
;             PG8_WAIT_VR(8, 24, relax); PG8_WAIT_L(0); PG8_BAR; PG8_MMA(1, 0, At, B0); PG8_MMA(1, 1, At, B1); PG8_BAR; PG8_SCHED;
;     ...
;             PG8_WAIT_V(8); PG8_WAIT_L(0); PG8_BAR; PG8_MMA(1, 0, At, B0); PG8_MMA(1, 1, At, B1); PG8_BAR; PG8_SCHED;
;     ...
;             PG8_LDB(B0, 1, 0); PG8_LDB(B1, 1, 1); PG8_SCHED; PG8_LDA(At, 1, 0); PG8_STAGEA(PG8_SA(0, 1), a2 + hstepA, voffA);
;             PG8_WAIT_V(8); PG8_WAIT_L(0); PG8_BAR; PG8_MMA(0, 0, At, B0); PG8_MMA(0, 1, At, B1); PG8_BAR; PG8_SCHED;
;             PG8_LDA(At, 1, 1); PG8_STAGEB(PG8_SB(1, 0), b3, voffB); PG8_STAGEB(PG8_SB(1, 1), b3 + hstepB, voffB); PG8_STAGEA(PG8_SA(1, 0), a3, voffA);
;             PG8_WAIT_V(8); PG8_WAIT_L(0); PG8_BAR; PG8_MMA(1, 0, At, B0); PG8_MMA(1, 1, At, B1); PG8_BAR; PG8_SCHED;
	s_setprio 0
	s_add_i32 s6, s91, s12
	v_lshl_add_u64 v[210:211], v[210:211], 0, s[86:87]
	s_mov_b32 m0, s6
	ds_read_b128 v[178:181], v161 offset:49152
	ds_read_b128 v[182:185], v161 offset:50176
	ds_read_b128 v[186:189], v161 offset:51200
	ds_read_b128 v[190:193], v161 offset:52224
	ds_read_b128 v[194:197], v161 offset:53248
	ds_read_b128 v[198:201], v161 offset:54272
	ds_read_b128 v[202:205], v161 offset:55296
	ds_read_b128 v[206:209], v161 offset:56320
	global_load_lds_dwordx4 v[210:211], off
	s_add_i32 m0, s6, 0x2000
	s_add_u32 s6, s16, 0x100080
	v_lshl_add_u64 v[210:211], v[212:213], 0, s[86:87]
	s_addc_u32 s7, s17, 0
	s_add_i32 s16, s94, s12
	global_load_lds_dwordx4 v[210:211], off
	v_lshl_add_u64 v[210:211], s[6:7], 0, v[16:17]
	s_mov_b32 m0, s16
	s_nop 0
	global_load_lds_dwordx4 v[210:211], off
	v_lshl_add_u64 v[210:211], s[6:7], 0, v[138:139]
	s_add_i32 m0, s16, 0x2000
	s_nop 0
	global_load_lds_dwordx4 v[210:211], off
	v_lshl_add_u64 v[210:211], v[214:215], 0, s[86:87]
	s_mov_b32 m0, s68
	s_nop 0
	global_load_lds_dwordx4 v[210:211], off
	v_lshl_add_u64 v[210:211], v[216:217], 0, s[86:87]
	s_mov_b32 m0, s69
	s_nop 0
	global_load_lds_dwordx4 v[210:211], off
	s_waitcnt vmcnt(8)
	s_waitcnt lgkmcnt(0)
	s_nop 0
	s_setprio 1
	s_barrier
	v_mfma_f32_16x16x32_bf16 v[62:65], v[130:133], v[178:181], v[62:65]
	v_mfma_f32_16x16x32_bf16 v[58:61], v[148:151], v[178:181], v[58:61]
	v_mfma_f32_16x16x32_bf16 v[46:49], v[130:133], v[186:189], v[46:49]
	v_mfma_f32_16x16x32_bf16 v[42:45], v[148:151], v[186:189], v[42:45]
	v_mfma_f32_16x16x32_bf16 v[30:33], v[130:133], v[194:197], v[30:33]
	v_mfma_f32_16x16x32_bf16 v[26:29], v[148:151], v[194:197], v[26:29]
	v_mfma_f32_16x16x32_bf16 v[12:15], v[130:133], v[202:205], v[12:15]
	v_mfma_f32_16x16x32_bf16 v[8:11], v[148:151], v[202:205], v[8:11]
	v_mfma_f32_16x16x32_bf16 v[62:65], v[134:137], v[182:185], v[62:65]
	v_mfma_f32_16x16x32_bf16 v[58:61], v[152:155], v[182:185], v[58:61]
	v_mfma_f32_16x16x32_bf16 v[46:49], v[134:137], v[190:193], v[46:49]
	v_mfma_f32_16x16x32_bf16 v[42:45], v[152:155], v[190:193], v[42:45]
	v_mfma_f32_16x16x32_bf16 v[30:33], v[134:137], v[198:201], v[30:33]
	v_mfma_f32_16x16x32_bf16 v[26:29], v[152:155], v[198:201], v[26:29]
	v_mfma_f32_16x16x32_bf16 v[12:15], v[134:137], v[206:209], v[12:15]
	v_mfma_f32_16x16x32_bf16 v[8:11], v[152:155], v[206:209], v[8:11]
	v_mfma_f32_16x16x32_bf16 v[54:57], v[162:165], v[178:181], v[54:57]
	v_mfma_f32_16x16x32_bf16 v[50:53], v[170:173], v[178:181], v[50:53]
	v_mfma_f32_16x16x32_bf16 v[38:41], v[162:165], v[186:189], v[38:41]
	v_mfma_f32_16x16x32_bf16 v[34:37], v[170:173], v[186:189], v[34:37]
	v_mfma_f32_16x16x32_bf16 v[22:25], v[162:165], v[194:197], v[22:25]
	v_mfma_f32_16x16x32_bf16 v[18:21], v[170:173], v[194:197], v[18:21]
	v_mfma_f32_16x16x32_bf16 v[4:7], v[162:165], v[202:205], v[4:7]
	v_mfma_f32_16x16x32_bf16 v[0:3], v[170:173], v[202:205], v[0:3]
	v_mfma_f32_16x16x32_bf16 v[54:57], v[166:169], v[182:185], v[54:57]
	v_mfma_f32_16x16x32_bf16 v[50:53], v[174:177], v[182:185], v[50:53]
	v_mfma_f32_16x16x32_bf16 v[38:41], v[166:169], v[190:193], v[38:41]
	v_mfma_f32_16x16x32_bf16 v[34:37], v[174:177], v[190:193], v[34:37]
	v_mfma_f32_16x16x32_bf16 v[22:25], v[166:169], v[198:201], v[22:25]
	v_mfma_f32_16x16x32_bf16 v[18:21], v[174:177], v[198:201], v[18:21]
	v_mfma_f32_16x16x32_bf16 v[4:7], v[166:169], v[206:209], v[4:7]
	v_mfma_f32_16x16x32_bf16 v[0:3], v[174:177], v[206:209], v[0:3]
	s_barrier
	s_setprio 0
	s_add_i32 s90, s90, 2
	s_add_u32 s38, s38, 0x100
	s_addc_u32 s39, s39, 0
	s_add_u32 s0, s0, 0x100
	s_addc_u32 s1, s1, 0
	v_add_u32_e32 v220, 0x10000, v157
.LBB0_558:
	s_add_u32 s6, s38, 0xfff00080
	s_addc_u32 s7, s39, -1
	s_add_i32 s91, 0, 0x10000
	s_cmp_eq_u32 s90, 60
	s_cselect_b32 s41, s21, s7
	s_cselect_b32 s40, s82, s6
	s_cselect_b32 s17, s23, s1
	s_cselect_b32 s16, s83, s0
	s_add_i32 s94, 0, 0x14000
	ds_read_b128 v[130:133], v220
	ds_read_b128 v[134:137], v220 offset:1024
	ds_read_b128 v[148:151], v220 offset:2048
	ds_read_b128 v[152:155], v220 offset:3072
	ds_read_b128 v[162:165], v220 offset:16384
	ds_read_b128 v[166:169], v220 offset:17408
	ds_read_b128 v[170:173], v220 offset:18432
	ds_read_b128 v[174:177], v220 offset:19456
	s_add_i32 m0, s13, 0xc000
	ds_read_b128 v[178:181], v161
	ds_read_b128 v[182:185], v161 offset:1024
	ds_read_b128 v[186:189], v161 offset:2048
	ds_read_b128 v[190:193], v161 offset:3072
	ds_read_b128 v[194:197], v161 offset:4096
	ds_read_b128 v[198:201], v161 offset:5120
	ds_read_b128 v[202:205], v161 offset:6144
	ds_read_b128 v[206:209], v161 offset:7168
	global_load_lds_dwordx4 v144, s[38:39]
	s_add_i32 m0, s13, 0xe000
	s_nop 0
	global_load_lds_dwordx4 v146, s[38:39]
	s_waitcnt vmcnt(8)
	s_waitcnt lgkmcnt(0)
	s_setprio 1
	s_barrier
; #define PG8_STAGEA(bufoff, gbase, voff) PG8_STAGE_X(bufoff, gbase, voff, AUXA)
; #define PG8_STAGEB(bufoff, gbase, voff) PG8_STAGE_X(bufoff, gbase, voff, AUXB)
; #define PG8_LDA(dst, b, h) do { _Pragma("unroll") for (int m = 0; m < 4; ++m) _Pragma("unroll") for (int k = 0; k < 2; ++k) dst[m][k] = *(const PG8_LAS bf16x8*)(lds + PG8_SA(b, h) + aoff + m * 2048 + k * 1024); } while (0)
; #define PG8_LDB(dst, b, h) do { _Pragma("unroll") for (int n = 0; n < 2; ++n) _Pragma("unroll") for (int k = 0; k < 2; ++k) dst[n][k] = *(const PG8_LAS bf16x8*)(lds + PG8_SB(b, h) + boff + n * 2048 + k * 1024); } while (0)
; #define PG8_MMA(ai, bj, At, Bt) do { if (GEMM_PRIO_MODE == 0) __builtin_amdgcn_s_setprio(1); PG8_MMA_LOOPS \
;         acc[ai][bj][m][n] = __builtin_amdgcn_mfma_f32_16x16x32_bf16(Bt[n][k], At[m][k], acc[ai][bj][m][n], 0, 0, 0); if (GEMM_PRIO_MODE == 0) __builtin_amdgcn_s_setprio(0); } while (0)
; #define PG8_WAIT_V(n) asm volatile("s_waitcnt vmcnt(" #n ")" ::: "memory")
; #define PG8_WAIT_VR(n, nr, flag) asm volatile("s_cmp_eq_u32 %0, 0\n\ts_cbranch_scc1 .Lpg8s%=\n\ts_waitcnt vmcnt(" #nr ")\n\ts_branch .Lpg8d%=\n.Lpg8s%=:\n\ts_waitcnt vmcnt(" #n ")\n.Lpg8d%=:" :: "s"(flag) : "memory", "scc")
; #define PG8_WAIT_L(n) asm volatile("s_waitcnt lgkmcnt(" #n ")" ::: "memory")
; #define PG8_BAR __builtin_amdgcn_s_barrier()
; #define PG8_SCHED __builtin_amdgcn_sched_barrier(0)
;     ...
;             PG8_WAIT_V(8); PG8_WAIT_L(0); PG8_BAR; PG8_MMA(0, 0, At, B0); PG8_MMA(0, 1, At, B1); PG8_BAR; PG8_SCHED;
;     ...
;             PG8_LDA(At, 0, 1); PG8_STAGEB(PG8_SB(0, 0), b2, voffB); PG8_STAGEB(PG8_SB(0, 1), b2 + hstepB, voffB); PG8_STAGEA(PG8_SA(0, 0), a2, voffA);
;     ...
;             PG8_WAIT_VR(8, 24, relax); PG8_WAIT_L(0); PG8_BAR; PG8_MMA(1, 0, At, B0); PG8_MMA(1, 1, At, B1); PG8_BAR; PG8_SCHED;
;     ...
;             PG8_WAIT_V(8); PG8_WAIT_L(0); PG8_BAR; PG8_MMA(1, 0, At, B0); PG8_MMA(1, 1, At, B1); PG8_BAR; PG8_SCHED;
;     ...
;             PG8_LDB(B0, 1, 0); PG8_LDB(B1, 1, 1); PG8_SCHED; PG8_LDA(At, 1, 0); PG8_STAGEA(PG8_SA(0, 1), a2 + hstepA, voffA);
;             PG8_WAIT_V(8); PG8_WAIT_L(0); PG8_BAR; PG8_MMA(0, 0, At, B0); PG8_MMA(0, 1, At, B1); PG8_BAR; PG8_SCHED;
	v_mfma_f32_16x16x32_bf16 v[126:129], v[130:133], v[178:181], v[126:129]
	v_mfma_f32_16x16x32_bf16 v[122:125], v[148:151], v[178:181], v[122:125]
	v_mfma_f32_16x16x32_bf16 v[110:113], v[130:133], v[186:189], v[110:113]
	v_mfma_f32_16x16x32_bf16 v[106:109], v[148:151], v[186:189], v[106:109]
	v_mfma_f32_16x16x32_bf16 v[94:97], v[130:133], v[194:197], v[94:97]
	v_mfma_f32_16x16x32_bf16 v[90:93], v[148:151], v[194:197], v[90:93]
	v_mfma_f32_16x16x32_bf16 v[78:81], v[130:133], v[202:205], v[78:81]
	v_mfma_f32_16x16x32_bf16 v[74:77], v[148:151], v[202:205], v[74:77]
	v_mfma_f32_16x16x32_bf16 v[126:129], v[134:137], v[182:185], v[126:129]
	v_mfma_f32_16x16x32_bf16 v[122:125], v[152:155], v[182:185], v[122:125]
	v_mfma_f32_16x16x32_bf16 v[110:113], v[134:137], v[190:193], v[110:113]
	v_mfma_f32_16x16x32_bf16 v[106:109], v[152:155], v[190:193], v[106:109]
	v_mfma_f32_16x16x32_bf16 v[94:97], v[134:137], v[198:201], v[94:97]
	v_mfma_f32_16x16x32_bf16 v[90:93], v[152:155], v[198:201], v[90:93]
	v_mfma_f32_16x16x32_bf16 v[78:81], v[134:137], v[206:209], v[78:81]
	v_mfma_f32_16x16x32_bf16 v[74:77], v[152:155], v[206:209], v[74:77]
	v_mfma_f32_16x16x32_bf16 v[118:121], v[162:165], v[178:181], v[118:121]
	v_mfma_f32_16x16x32_bf16 v[114:117], v[170:173], v[178:181], v[114:117]
	v_mfma_f32_16x16x32_bf16 v[102:105], v[162:165], v[186:189], v[102:105]
	v_mfma_f32_16x16x32_bf16 v[98:101], v[170:173], v[186:189], v[98:101]
	v_mfma_f32_16x16x32_bf16 v[86:89], v[162:165], v[194:197], v[86:89]
	v_mfma_f32_16x16x32_bf16 v[82:85], v[170:173], v[194:197], v[82:85]
	v_mfma_f32_16x16x32_bf16 v[70:73], v[162:165], v[202:205], v[70:73]
	v_mfma_f32_16x16x32_bf16 v[66:69], v[170:173], v[202:205], v[66:69]
	v_mfma_f32_16x16x32_bf16 v[118:121], v[166:169], v[182:185], v[118:121]
	v_mfma_f32_16x16x32_bf16 v[114:117], v[174:177], v[182:185], v[114:117]
	v_mfma_f32_16x16x32_bf16 v[102:105], v[166:169], v[190:193], v[102:105]
	v_mfma_f32_16x16x32_bf16 v[98:101], v[174:177], v[190:193], v[98:101]
	v_mfma_f32_16x16x32_bf16 v[86:89], v[166:169], v[198:201], v[86:89]
	v_mfma_f32_16x16x32_bf16 v[82:85], v[174:177], v[198:201], v[82:85]
	v_mfma_f32_16x16x32_bf16 v[70:73], v[166:169], v[206:209], v[70:73]
	v_mfma_f32_16x16x32_bf16 v[66:69], v[174:177], v[206:209], v[66:69]
	s_barrier
	s_setprio 0
	s_add_i32 s6, s91, s12
	s_mov_b32 m0, s6
	ds_read_b128 v[178:181], v161 offset:16384
	ds_read_b128 v[182:185], v161 offset:17408
	ds_read_b128 v[186:189], v161 offset:18432
	ds_read_b128 v[190:193], v161 offset:19456
	ds_read_b128 v[194:197], v161 offset:20480
	ds_read_b128 v[198:201], v161 offset:21504
	ds_read_b128 v[202:205], v161 offset:22528
	ds_read_b128 v[206:209], v161 offset:23552
	global_load_lds_dwordx4 v16, s[16:17]
	s_add_i32 m0, s6, 0x2000
	s_add_u32 s6, s16, 0x100000
	s_addc_u32 s7, s17, 0
	s_add_i32 s91, s94, s12
	global_load_lds_dwordx4 v138, s[16:17]
	s_mov_b32 m0, s91
	s_nop 0
	global_load_lds_dwordx4 v16, s[6:7]
	s_add_i32 m0, s91, 0x2000
	s_nop 0
	global_load_lds_dwordx4 v138, s[6:7]
	s_mov_b32 m0, s13
	s_nop 0
	global_load_lds_dwordx4 v142, s[40:41]
	s_mov_b32 m0, s42
	s_nop 0
	global_load_lds_dwordx4 v140, s[40:41]
	s_waitcnt vmcnt(8)
	s_waitcnt lgkmcnt(0)
	s_nop 0
	s_setprio 1
	s_barrier
	v_mfma_f32_16x16x32_bf16 v[62:65], v[130:133], v[178:181], v[62:65]
	v_mfma_f32_16x16x32_bf16 v[58:61], v[148:151], v[178:181], v[58:61]
	v_mfma_f32_16x16x32_bf16 v[46:49], v[130:133], v[186:189], v[46:49]
	v_mfma_f32_16x16x32_bf16 v[42:45], v[148:151], v[186:189], v[42:45]
	v_mfma_f32_16x16x32_bf16 v[30:33], v[130:133], v[194:197], v[30:33]
	v_mfma_f32_16x16x32_bf16 v[26:29], v[148:151], v[194:197], v[26:29]
	v_mfma_f32_16x16x32_bf16 v[12:15], v[130:133], v[202:205], v[12:15]
	v_mfma_f32_16x16x32_bf16 v[8:11], v[148:151], v[202:205], v[8:11]
	v_mfma_f32_16x16x32_bf16 v[62:65], v[134:137], v[182:185], v[62:65]
	v_mfma_f32_16x16x32_bf16 v[58:61], v[152:155], v[182:185], v[58:61]
	v_mfma_f32_16x16x32_bf16 v[46:49], v[134:137], v[190:193], v[46:49]
	v_mfma_f32_16x16x32_bf16 v[42:45], v[152:155], v[190:193], v[42:45]
	v_mfma_f32_16x16x32_bf16 v[30:33], v[134:137], v[198:201], v[30:33]
	v_mfma_f32_16x16x32_bf16 v[26:29], v[152:155], v[198:201], v[26:29]
	v_mfma_f32_16x16x32_bf16 v[12:15], v[134:137], v[206:209], v[12:15]
	v_mfma_f32_16x16x32_bf16 v[8:11], v[152:155], v[206:209], v[8:11]
	v_mfma_f32_16x16x32_bf16 v[54:57], v[162:165], v[178:181], v[54:57]
	v_mfma_f32_16x16x32_bf16 v[50:53], v[170:173], v[178:181], v[50:53]
	v_mfma_f32_16x16x32_bf16 v[38:41], v[162:165], v[186:189], v[38:41]
	v_mfma_f32_16x16x32_bf16 v[34:37], v[170:173], v[186:189], v[34:37]
	v_mfma_f32_16x16x32_bf16 v[22:25], v[162:165], v[194:197], v[22:25]
	v_mfma_f32_16x16x32_bf16 v[18:21], v[170:173], v[194:197], v[18:21]
	v_mfma_f32_16x16x32_bf16 v[4:7], v[162:165], v[202:205], v[4:7]
	v_mfma_f32_16x16x32_bf16 v[0:3], v[170:173], v[202:205], v[0:3]
	v_mfma_f32_16x16x32_bf16 v[54:57], v[166:169], v[182:185], v[54:57]
	v_mfma_f32_16x16x32_bf16 v[50:53], v[174:177], v[182:185], v[50:53]
	v_mfma_f32_16x16x32_bf16 v[38:41], v[166:169], v[190:193], v[38:41]
	v_mfma_f32_16x16x32_bf16 v[34:37], v[174:177], v[190:193], v[34:37]
	v_mfma_f32_16x16x32_bf16 v[22:25], v[166:169], v[198:201], v[22:25]
	v_mfma_f32_16x16x32_bf16 v[18:21], v[174:177], v[198:201], v[18:21]
	v_mfma_f32_16x16x32_bf16 v[4:7], v[166:169], v[206:209], v[4:7]
	v_mfma_f32_16x16x32_bf16 v[0:3], v[174:177], v[206:209], v[0:3]
	s_barrier
; #define PG8_STAGEA(bufoff, gbase, voff) PG8_STAGE_X(bufoff, gbase, voff, AUXA)
; #define PG8_STAGEB(bufoff, gbase, voff) PG8_STAGE_X(bufoff, gbase, voff, AUXB)
; #define PG8_LDA(dst, b, h) do { _Pragma("unroll") for (int m = 0; m < 4; ++m) _Pragma("unroll") for (int k = 0; k < 2; ++k) dst[m][k] = *(const PG8_LAS bf16x8*)(lds + PG8_SA(b, h) + aoff + m * 2048 + k * 1024); } while (0)
; #define PG8_LDB(dst, b, h) do { _Pragma("unroll") for (int n = 0; n < 2; ++n) _Pragma("unroll") for (int k = 0; k < 2; ++k) dst[n][k] = *(const PG8_LAS bf16x8*)(lds + PG8_SB(b, h) + boff + n * 2048 + k * 1024); } while (0)
; #define PG8_MMA(ai, bj, At, Bt) do { if (GEMM_PRIO_MODE == 0) __builtin_amdgcn_s_setprio(1); PG8_MMA_LOOPS \
;         acc[ai][bj][m][n] = __builtin_amdgcn_mfma_f32_16x16x32_bf16(Bt[n][k], At[m][k], acc[ai][bj][m][n], 0, 0, 0); if (GEMM_PRIO_MODE == 0) __builtin_amdgcn_s_setprio(0); } while (0)
; #define PG8_WAIT_V(n) asm volatile("s_waitcnt vmcnt(" #n ")" ::: "memory")
; #define PG8_WAIT_L(n) asm volatile("s_waitcnt lgkmcnt(" #n ")" ::: "memory")
; #define PG8_BAR __builtin_amdgcn_s_barrier()
; #define PG8_SCHED __builtin_amdgcn_sched_barrier(0)
;     ...
;             PG8_LDB(B0, 1, 0); PG8_LDB(B1, 1, 1); PG8_SCHED; PG8_LDA(At, 1, 0); PG8_STAGEA(PG8_SA(0, 1), a2 + hstepA, voffA);
;             PG8_WAIT_V(8); PG8_WAIT_L(0); PG8_BAR; PG8_MMA(0, 0, At, B0); PG8_MMA(0, 1, At, B1); PG8_BAR; PG8_SCHED;
;             PG8_LDA(At, 1, 1); PG8_STAGEB(PG8_SB(1, 0), b3, voffB); PG8_STAGEB(PG8_SB(1, 1), b3 + hstepB, voffB); PG8_STAGEA(PG8_SA(1, 0), a3, voffA);
;             PG8_WAIT_V(8); PG8_WAIT_L(0); PG8_BAR; PG8_MMA(1, 0, At, B0); PG8_MMA(1, 1, At, B1); PG8_BAR; PG8_SCHED;
;     ...
;         if constexpr (ALIGN_EPI) { if (wr == 0) PG8_BAR; }
	s_setprio 0
	s_add_i32 s91, 0, 0x18000
	s_add_i32 s94, 0, 0x1c000
	ds_read_b128 v[130:133], v220 offset:32768
	ds_read_b128 v[134:137], v220 offset:33792
	ds_read_b128 v[148:151], v220 offset:34816
	ds_read_b128 v[152:155], v220 offset:35840
	ds_read_b128 v[162:165], v220 offset:49152
	ds_read_b128 v[166:169], v220 offset:50176
	ds_read_b128 v[170:173], v220 offset:51200
	ds_read_b128 v[174:177], v220 offset:52224
	s_add_u32 s6, s40, 0x100000
	s_addc_u32 s7, s41, 0
	s_mov_b32 m0, s43
	ds_read_b128 v[178:181], v161 offset:32768
	ds_read_b128 v[182:185], v161 offset:33792
	ds_read_b128 v[186:189], v161 offset:34816
	ds_read_b128 v[190:193], v161 offset:35840
	ds_read_b128 v[194:197], v161 offset:36864
	ds_read_b128 v[198:201], v161 offset:37888
	ds_read_b128 v[202:205], v161 offset:38912
	ds_read_b128 v[206:209], v161 offset:39936
	global_load_lds_dwordx4 v142, s[6:7]
	s_mov_b32 m0, s50
	s_nop 0
	global_load_lds_dwordx4 v140, s[6:7]
	s_waitcnt vmcnt(8)
	s_waitcnt lgkmcnt(0)
	s_nop 0
	s_nop 0
	s_setprio 1
	s_barrier
	v_mfma_f32_16x16x32_bf16 v[126:129], v[130:133], v[178:181], v[126:129]
	v_mfma_f32_16x16x32_bf16 v[122:125], v[148:151], v[178:181], v[122:125]
	v_mfma_f32_16x16x32_bf16 v[110:113], v[130:133], v[186:189], v[110:113]
	v_mfma_f32_16x16x32_bf16 v[106:109], v[148:151], v[186:189], v[106:109]
	v_mfma_f32_16x16x32_bf16 v[94:97], v[130:133], v[194:197], v[94:97]
	v_mfma_f32_16x16x32_bf16 v[90:93], v[148:151], v[194:197], v[90:93]
	v_mfma_f32_16x16x32_bf16 v[78:81], v[130:133], v[202:205], v[78:81]
	v_mfma_f32_16x16x32_bf16 v[74:77], v[148:151], v[202:205], v[74:77]
	v_mfma_f32_16x16x32_bf16 v[126:129], v[134:137], v[182:185], v[126:129]
	v_mfma_f32_16x16x32_bf16 v[122:125], v[152:155], v[182:185], v[122:125]
	v_mfma_f32_16x16x32_bf16 v[110:113], v[134:137], v[190:193], v[110:113]
	v_mfma_f32_16x16x32_bf16 v[106:109], v[152:155], v[190:193], v[106:109]
	v_mfma_f32_16x16x32_bf16 v[94:97], v[134:137], v[198:201], v[94:97]
	v_mfma_f32_16x16x32_bf16 v[90:93], v[152:155], v[198:201], v[90:93]
	v_mfma_f32_16x16x32_bf16 v[78:81], v[134:137], v[206:209], v[78:81]
	v_mfma_f32_16x16x32_bf16 v[74:77], v[152:155], v[206:209], v[74:77]
	v_mfma_f32_16x16x32_bf16 v[118:121], v[162:165], v[178:181], v[118:121]
	v_mfma_f32_16x16x32_bf16 v[114:117], v[170:173], v[178:181], v[114:117]
	v_mfma_f32_16x16x32_bf16 v[102:105], v[162:165], v[186:189], v[102:105]
	v_mfma_f32_16x16x32_bf16 v[98:101], v[170:173], v[186:189], v[98:101]
	v_mfma_f32_16x16x32_bf16 v[86:89], v[162:165], v[194:197], v[86:89]
	v_mfma_f32_16x16x32_bf16 v[82:85], v[170:173], v[194:197], v[82:85]
	v_mfma_f32_16x16x32_bf16 v[70:73], v[162:165], v[202:205], v[70:73]
	v_mfma_f32_16x16x32_bf16 v[66:69], v[170:173], v[202:205], v[66:69]
	v_mfma_f32_16x16x32_bf16 v[118:121], v[166:169], v[182:185], v[118:121]
	v_mfma_f32_16x16x32_bf16 v[114:117], v[174:177], v[182:185], v[114:117]
	v_mfma_f32_16x16x32_bf16 v[102:105], v[166:169], v[190:193], v[102:105]
	v_mfma_f32_16x16x32_bf16 v[98:101], v[174:177], v[190:193], v[98:101]
	v_mfma_f32_16x16x32_bf16 v[86:89], v[166:169], v[198:201], v[86:89]
	v_mfma_f32_16x16x32_bf16 v[82:85], v[174:177], v[198:201], v[82:85]
	v_mfma_f32_16x16x32_bf16 v[70:73], v[166:169], v[206:209], v[70:73]
	v_mfma_f32_16x16x32_bf16 v[66:69], v[174:177], v[206:209], v[66:69]
	s_barrier
	s_setprio 0
	s_add_i32 s6, s91, s12
	s_mov_b32 m0, s6
	ds_read_b128 v[178:181], v161 offset:49152
	ds_read_b128 v[182:185], v161 offset:50176
	ds_read_b128 v[186:189], v161 offset:51200
	ds_read_b128 v[190:193], v161 offset:52224
	ds_read_b128 v[194:197], v161 offset:53248
	ds_read_b128 v[198:201], v161 offset:54272
	ds_read_b128 v[202:205], v161 offset:55296
	ds_read_b128 v[206:209], v161 offset:56320
	s_add_u32 s100, s16, 0x80
	s_addc_u32 s101, s17, 0
	global_load_lds_dwordx4 v16, s[100:101]
	s_add_i32 m0, s6, 0x2000
	s_add_u32 s6, s16, 0x100080
	s_addc_u32 s7, s17, 0
	s_add_i32 s16, s94, s12
	global_load_lds_dwordx4 v138, s[100:101]
	s_mov_b32 m0, s16
	s_nop 0
	global_load_lds_dwordx4 v16, s[6:7]
	s_add_i32 m0, s16, 0x2000
	s_nop 0
	global_load_lds_dwordx4 v138, s[6:7]
	s_mov_b32 m0, s68
	s_nop 0
	s_add_u32 vcc_lo, s40, 0x80
	s_addc_u32 vcc_hi, s41, 0
	global_load_lds_dwordx4 v142, vcc
	s_mov_b32 m0, s69
	s_nop 0
	global_load_lds_dwordx4 v140, vcc
	s_waitcnt vmcnt(8)
	s_waitcnt lgkmcnt(0)
	s_nop 0
	s_setprio 1
	s_barrier
	v_mfma_f32_16x16x32_bf16 v[62:65], v[130:133], v[178:181], v[62:65]
	v_mfma_f32_16x16x32_bf16 v[58:61], v[148:151], v[178:181], v[58:61]
	v_mfma_f32_16x16x32_bf16 v[46:49], v[130:133], v[186:189], v[46:49]
	v_mfma_f32_16x16x32_bf16 v[42:45], v[148:151], v[186:189], v[42:45]
	v_mfma_f32_16x16x32_bf16 v[30:33], v[130:133], v[194:197], v[30:33]
	v_mfma_f32_16x16x32_bf16 v[26:29], v[148:151], v[194:197], v[26:29]
	v_mfma_f32_16x16x32_bf16 v[12:15], v[130:133], v[202:205], v[12:15]
	v_mfma_f32_16x16x32_bf16 v[8:11], v[148:151], v[202:205], v[8:11]
	v_mfma_f32_16x16x32_bf16 v[62:65], v[134:137], v[182:185], v[62:65]
	v_mfma_f32_16x16x32_bf16 v[58:61], v[152:155], v[182:185], v[58:61]
	v_mfma_f32_16x16x32_bf16 v[46:49], v[134:137], v[190:193], v[46:49]
	v_mfma_f32_16x16x32_bf16 v[42:45], v[152:155], v[190:193], v[42:45]
	v_mfma_f32_16x16x32_bf16 v[30:33], v[134:137], v[198:201], v[30:33]
	v_mfma_f32_16x16x32_bf16 v[26:29], v[152:155], v[198:201], v[26:29]
	v_mfma_f32_16x16x32_bf16 v[12:15], v[134:137], v[206:209], v[12:15]
	v_mfma_f32_16x16x32_bf16 v[8:11], v[152:155], v[206:209], v[8:11]
	v_mfma_f32_16x16x32_bf16 v[54:57], v[162:165], v[178:181], v[54:57]
	v_mfma_f32_16x16x32_bf16 v[50:53], v[170:173], v[178:181], v[50:53]
	v_mfma_f32_16x16x32_bf16 v[38:41], v[162:165], v[186:189], v[38:41]
	v_mfma_f32_16x16x32_bf16 v[34:37], v[170:173], v[186:189], v[34:37]
	v_mfma_f32_16x16x32_bf16 v[22:25], v[162:165], v[194:197], v[22:25]
	v_mfma_f32_16x16x32_bf16 v[18:21], v[170:173], v[194:197], v[18:21]
	v_mfma_f32_16x16x32_bf16 v[4:7], v[162:165], v[202:205], v[4:7]
	v_mfma_f32_16x16x32_bf16 v[0:3], v[170:173], v[202:205], v[0:3]
	v_mfma_f32_16x16x32_bf16 v[54:57], v[166:169], v[182:185], v[54:57]
	v_mfma_f32_16x16x32_bf16 v[50:53], v[174:177], v[182:185], v[50:53]
	v_mfma_f32_16x16x32_bf16 v[38:41], v[166:169], v[190:193], v[38:41]
	v_mfma_f32_16x16x32_bf16 v[34:37], v[174:177], v[190:193], v[34:37]
	v_mfma_f32_16x16x32_bf16 v[22:25], v[166:169], v[198:201], v[22:25]
	v_mfma_f32_16x16x32_bf16 v[18:21], v[174:177], v[198:201], v[18:21]
	v_mfma_f32_16x16x32_bf16 v[4:7], v[166:169], v[206:209], v[4:7]
	v_mfma_f32_16x16x32_bf16 v[0:3], v[174:177], v[206:209], v[0:3]
	s_barrier
	s_setprio 0
	s_add_i32 s90, s90, 2
	s_add_u32 s38, s38, 0x100
	s_addc_u32 s39, s39, 0
	s_add_u32 s0, s0, 0x100
	s_addc_u32 s1, s1, 0
	s_cmp_gt_u32 s90, 61
	s_cbranch_scc0 .LBB0_558
	s_mov_b32 s98, 1
	s_and_b64 vcc, exec, s[18:19]
	s_cbranch_vccz .LBB0_561
	s_barrier

; #define PG8_STAGEA(bufoff, gbase, voff) PG8_STAGE_X(bufoff, gbase, voff, AUXA)
; #define PG8_STAGEB(bufoff, gbase, voff) PG8_STAGE_X(bufoff, gbase, voff, AUXB)
; #define PG8_WAIT_V(n) asm volatile("s_waitcnt vmcnt(" #n ")" ::: "memory")
; #define PG8_BAR __builtin_amdgcn_s_barrier()
;     ...
;     const int wid = __builtin_amdgcn_readfirstlane(tid >> 6), lane = tid & 63, wr = wid >> 2, wc = wid & 3, fr = lane & 15, fq = lane >> 4;
;     const int K = g.K, nt = K / BK;
;     unsigned voffA[2], voffB[2];
; #pragma unroll
;     for (int i = 0; i < 2; ++i) { int R, C; stage_rc(tid * 16 + i * 8192, R, C); const int Rb = Epi::PERM ? ((R & ~31) + perm32(R & 31)) : R;
;         voffA[i] = (unsigned)(R * (ABLK ? 64 : g.lda) + C) * 2u; voffB[i] = (unsigned)(Rb * (BBLK ? 64 : g.ldb) + C) * 2u; }
;     const size_t kstepA = ABLK ? 32768 : 128, kstepB = BBLK ? 32768 : 128;
;     const size_t hstepA = (size_t)HALF * (ABLK ? 64 : g.lda) * 2, hstepB = (size_t)HALF * (BBLK ? 64 : g.ldb) * 2;
;     const size_t tstepA = ABLK ? (size_t)(K / 64) * 32768 : (size_t)256 * g.lda * 2, tstepB = BBLK ? (size_t)(K / 64) * 32768 : (size_t)256 * g.ldb * 2;
;     const unsigned ldsw = (unsigned)wid * 1024u;
;     const int aoff = lds_byte(wr * 64 + fr, fq * 8), boff = lds_byte(wc * 32 + fr, fq * 8);
;     ...
;     if constexpr (SP2) {
;         PG8_STAGEB(PG8_SB(0, 0), cB, voffB); PG8_STAGEB(PG8_SB(0, 1), cB + hstepB, voffB); PG8_STAGEA(PG8_SA(0, 0), cA, voffA); PG8_STAGEA(PG8_SA(0, 1), cA + hstepA, voffA);
;         if (wr == 1) PG8_BAR;
;         PG8_WAIT_V(2); PG8_BAR;
;         PG8_STAGEB(PG8_SB(1, 0), cB + kstepB, voffB); PG8_STAGEA(PG8_SA(1, 0), cA + kstepA, voffA); PG8_STAGEB(PG8_SB(1, 1), cB + hstepB + kstepB, voffB);
;         PG8_WAIT_V(6); PG8_BAR;
.LBB0_702:
	s_mov_b32 s98, 0
	v_readlane_b32 s16, v254, 13
	v_mov_b32_e32 v137, v17
	v_readlane_b32 s17, v254, 14
	s_and_b32 s7, s1, 3
	s_add_i32 m0, s69, 0x18000
	v_lshl_add_u64 v[0:1], v[0:1], 0, s[86:87]
	v_lshl_add_u64 v[12:13], s[16:17], 0, v[136:137]
	v_mov_b32_e32 v133, v17
	s_lshl_b32 s12, s6, 13
	s_lshl_b32 s13, s1, 5
	s_lshl_b32 s7, s7, 12
	s_waitcnt vmcnt(2)
	s_barrier
	global_load_lds_dwordx4 v[0:1], off
	v_lshl_add_u64 v[0:1], v[2:3], 0, s[86:87]
	s_add_i32 m0, s69, 0x1a000
	s_add_i32 s83, s69, 0x8000
	s_add_i32 s90, s69, 0xa000
	v_lshl_add_u64 v[14:15], s[16:17], 0, v[132:133]
	global_load_lds_dwordx4 v[0:1], off
	v_lshl_add_u64 v[0:1], v[12:13], 0, s[86:87]
	s_mov_b32 m0, s83
	s_add_u32 s10, s42, 0x100080
	global_load_lds_dwordx4 v[0:1], off
	v_lshl_add_u64 v[0:1], v[14:15], 0, s[86:87]
	s_mov_b32 m0, s90
	s_addc_u32 s11, s43, 0
	global_load_lds_dwordx4 v[0:1], off
	s_add_i32 m0, s69, 0x1c000
	v_lshl_add_u64 v[0:1], s[10:11], 0, v[134:135]
	global_load_lds_dwordx4 v[0:1], off
	v_lshl_add_u64 v[0:1], s[10:11], 0, v[130:131]
	s_add_i32 m0, s69, 0x1e000
	s_cmpk_lt_u32 s0, 0x100
	global_load_lds_dwordx4 v[0:1], off
	v_and_b32_e32 v1, 15, v5
	v_lshrrev_b32_e32 v0, 1, v5
	v_lshl_or_b32 v2, s6, 6, v1
	v_and_b32_e32 v0, 24, v0
	v_lshlrev_b32_e32 v138, 6, v2
	v_lshlrev_b32_e32 v3, 1, v0
	s_movk_i32 s6, 0x3c0
	v_and_or_b32 v11, v138, s6, v3
	v_lshl_or_b32 v1, v1, 6, v3
	v_lshlrev_b32_e32 v3, 2, v5
	v_and_b32_e32 v3, 32, v3
	v_bitop3_b32 v146, v1, s7, v3 bitop3:0xde
	v_lshlrev_b32_e32 v1, 16, v9
	v_lshlrev_b32_e32 v2, 2, v2
	s_cselect_b64 s[18:19], -1, 0
	s_bfe_u32 s20, s1, 0x10001
	s_add_i32 s1, 0, 0x20000
	v_and_b32_e32 v1, 0xfffe0000, v1
	v_and_b32_e32 v12, 32, v2
	v_add_u32_e32 v147, s1, v2
	v_lshl_add_u32 v1, v8, 13, v1
	v_and_b32_e32 v2, 1, v9
	v_lshl_or_b32 v1, v2, 6, v1
	v_lshl_add_u32 v140, v10, 1, v1
	v_lshlrev_b32_e32 v1, 16, v4
	v_and_b32_e32 v1, 0xfffe0000, v1
	s_waitcnt vmcnt(6)
	v_lshl_add_u32 v1, v6, 13, v1
	v_and_b32_e32 v2, 1, v4
	v_bitop3_b32 v11, v11, s12, v12 bitop3:0xde
	s_and_b32 s0, s13, 32
	v_lshl_or_b32 v1, v2, 6, v1
	s_mov_b32 s21, s79
	v_ashrrev_i32_e32 v139, 31, v138
	v_mov_b32_e32 v141, v17
	v_lshl_add_u32 v142, v7, 1, v1
	v_mov_b32_e32 v143, v17
	s_mov_b32 s91, 0
	v_add_u32_e32 v148, 0, v11
	s_lshl_b32 s78, s0, 1
	v_lshlrev_b32_e32 v16, 1, v0
	v_readlane_b32 s94, v254, 8
	v_readlane_b32 s38, v254, 11
	s_mov_b64 s[12:13], s[16:17]
	s_barrier
	v_readlane_b32 s39, v254, 12
	s_branch .LBB0_705

; #define PG8_STAGEA(bufoff, gbase, voff) PG8_STAGE_X(bufoff, gbase, voff, AUXA)
; #define PG8_LDA(dst, b, h) do { _Pragma("unroll") for (int m = 0; m < 4; ++m) _Pragma("unroll") for (int k = 0; k < 2; ++k) dst[m][k] = *(const PG8_LAS bf16x8*)(lds + PG8_SA(b, h) + aoff + m * 2048 + k * 1024); } while (0)
; #define PG8_LDB(dst, b, h) do { _Pragma("unroll") for (int n = 0; n < 2; ++n) _Pragma("unroll") for (int k = 0; k < 2; ++k) dst[n][k] = *(const PG8_LAS bf16x8*)(lds + PG8_SB(b, h) + boff + n * 2048 + k * 1024); } while (0)
; #define PG8_MMA(ai, bj, At, Bt) do { if (GEMM_PRIO_MODE == 0) __builtin_amdgcn_s_setprio(1); PG8_MMA_LOOPS \
;         acc[ai][bj][m][n] = __builtin_amdgcn_mfma_f32_16x16x32_bf16(Bt[n][k], At[m][k], acc[ai][bj][m][n], 0, 0, 0); if (GEMM_PRIO_MODE == 0) __builtin_amdgcn_s_setprio(0); } while (0)
; #define PG8_WAIT_VR(n, nr, flag) asm volatile("s_cmp_eq_u32 %0, 0\n\ts_cbranch_scc1 .Lpg8s%=\n\ts_waitcnt vmcnt(" #nr ")\n\ts_branch .Lpg8d%=\n.Lpg8s%=:\n\ts_waitcnt vmcnt(" #n ")\n.Lpg8d%=:" :: "s"(flag) : "memory", "scc")
; #define PG8_WAIT_L(n) asm volatile("s_waitcnt lgkmcnt(" #n ")" ::: "memory")
; #define PG8_BAR __builtin_amdgcn_s_barrier()
; #define PG8_SCHED __builtin_amdgcn_sched_barrier(0)
;     ...
;         for (int t = t0; t < nt; t += 2) {
;             const bool last = (t == nt - 2);
;             const char* a1 = cA + (size_t)(t + 1) * kstepA;
;             const char* a2 = last ? nA : cA + (size_t)(t + 2) * kstepA; const char* b2 = last ? nB : cB + (size_t)(t + 2) * kstepB;
;             const char* a3 = a2 + kstepA; const char* b3 = b2 + kstepB;
;             if (last && has_next) S.a_ready(nxt);
;             if constexpr (SP2) {
;             PG8_LDB(B0, 0, 0); PG8_LDB(B1, 0, 1); PG8_SCHED; PG8_LDA(At, 0, 0); PG8_STAGEA(PG8_SA(1, 1), a1 + hstepA, voffA);
;     ...
;             const int relax = __builtin_amdgcn_readfirstlane((t == 0 && ui > 0) ? 1 : 0);
;             PG8_WAIT_VR(8, 24, relax); PG8_WAIT_L(0); PG8_BAR; PG8_MMA(0, 0, At, B0); PG8_MMA(0, 1, At, B1); PG8_BAR; PG8_SCHED;
.LBB0_711:
	s_ashr_i32 s25, s24, 31
	s_lshl_b64 s[0:1], s[24:25], 21
	s_add_u32 s26, s56, s0
	s_addc_u32 s27, s57, s1
	s_and_b64 s[0:1], s[10:11], exec
	s_cselect_b32 s0, s27, s13
	s_cselect_b32 s1, s26, s12
	s_ashr_i32 s23, s22, 31
	s_lshl_b64 s[6:7], s[22:23], 21
	s_add_u32 s36, s51, s6
	s_addc_u32 s37, s68, s7
	s_and_b64 s[6:7], s[10:11], exec
	s_cselect_b32 s23, s37, s43
	s_cselect_b32 s25, s36, s42
	s_add_u32 s40, s12, 0x100080
	s_addc_u32 s41, s13, 0
	s_add_u32 s12, s42, 0x100
	s_addc_u32 s13, s43, 0
	s_mov_b32 s39, -2
	s_add_u32 s6, s40, 0xfff00080
	s_addc_u32 s7, s41, -1
	s_add_i32 s95, 0, 0x10000
	s_cmp_eq_u32 s39, 60
	s_cselect_b32 s43, s0, s7
	s_cselect_b32 s42, s1, s6
	v_add_u32_e32 v144, s95, v146
	s_cselect_b32 s17, s23, s13
	s_cselect_b32 s16, s25, s12
	s_add_i32 vcc_lo, 0, 0x14000
	ds_read_b128 v[150:153], v144
	ds_read_b128 v[154:157], v144 offset:1024
	ds_read_b128 v[158:161], v144 offset:2048
	ds_read_b128 v[162:165], v144 offset:3072
	v_add_u32_e32 v144, vcc_lo, v146
	ds_read_b128 v[166:169], v144
	ds_read_b128 v[170:173], v144 offset:1024
	ds_read_b128 v[174:177], v144 offset:2048
	ds_read_b128 v[178:181], v144 offset:3072
	v_lshl_add_u64 v[144:145], s[40:41], 0, v[140:141]
	s_add_i32 m0, s69, 0xc000
	ds_read_b128 v[182:185], v148
	ds_read_b128 v[186:189], v148 offset:1024
	ds_read_b128 v[190:193], v148 offset:2048
	ds_read_b128 v[194:197], v148 offset:3072
	ds_read_b128 v[198:201], v148 offset:4096
	ds_read_b128 v[202:205], v148 offset:5120
	ds_read_b128 v[206:209], v148 offset:6144
	ds_read_b128 v[210:213], v148 offset:7168
	global_load_lds_dwordx4 v[144:145], off
	v_lshl_add_u64 v[144:145], s[40:41], 0, v[142:143]
	s_add_i32 m0, s69, 0xe000
	s_nop 0
	global_load_lds_dwordx4 v[144:145], off
	s_cmp_eq_u32 s98, 0
	s_cbranch_scc1 .Lrelax_s_lbb0_712_0
	s_waitcnt vmcnt(24)
	s_branch .Lrelax_d_lbb0_712_0

; #define PG8_STAGEA(bufoff, gbase, voff) PG8_STAGE_X(bufoff, gbase, voff, AUXA)
; #define PG8_STAGEB(bufoff, gbase, voff) PG8_STAGE_X(bufoff, gbase, voff, AUXB)
; #define PG8_LDA(dst, b, h) do { _Pragma("unroll") for (int m = 0; m < 4; ++m) _Pragma("unroll") for (int k = 0; k < 2; ++k) dst[m][k] = *(const PG8_LAS bf16x8*)(lds + PG8_SA(b, h) + aoff + m * 2048 + k * 1024); } while (0)
; #define PG8_MMA(ai, bj, At, Bt) do { if (GEMM_PRIO_MODE == 0) __builtin_amdgcn_s_setprio(1); PG8_MMA_LOOPS \
;         acc[ai][bj][m][n] = __builtin_amdgcn_mfma_f32_16x16x32_bf16(Bt[n][k], At[m][k], acc[ai][bj][m][n], 0, 0, 0); if (GEMM_PRIO_MODE == 0) __builtin_amdgcn_s_setprio(0); } while (0)
; #define PG8_WAIT_V(n) asm volatile("s_waitcnt vmcnt(" #n ")" ::: "memory")
; #define PG8_WAIT_VR(n, nr, flag) asm volatile("s_cmp_eq_u32 %0, 0\n\ts_cbranch_scc1 .Lpg8s%=\n\ts_waitcnt vmcnt(" #nr ")\n\ts_branch .Lpg8d%=\n.Lpg8s%=:\n\ts_waitcnt vmcnt(" #n ")\n.Lpg8d%=:" :: "s"(flag) : "memory", "scc")
; #define PG8_WAIT_L(n) asm volatile("s_waitcnt lgkmcnt(" #n ")" ::: "memory")
; #define PG8_BAR __builtin_amdgcn_s_barrier()
; #define PG8_SCHED __builtin_amdgcn_sched_barrier(0)
;     ...
;             PG8_WAIT_VR(8, 24, relax); PG8_WAIT_L(0); PG8_BAR; PG8_MMA(0, 0, At, B0); PG8_MMA(0, 1, At, B1); PG8_BAR; PG8_SCHED;
;     ...
;             PG8_WAIT_V(8); PG8_WAIT_L(0); PG8_BAR; PG8_MMA(0, 0, At, B0); PG8_MMA(0, 1, At, B1); PG8_BAR; PG8_SCHED;
;     ...
;             PG8_LDA(At, 0, 1); PG8_STAGEB(PG8_SB(0, 0), b2, voffB); PG8_STAGEB(PG8_SB(0, 1), b2 + hstepB, voffB); PG8_STAGEA(PG8_SA(0, 0), a2, voffA);
;     ...
;             PG8_WAIT_VR(8, 24, relax); PG8_WAIT_L(0); PG8_BAR; PG8_MMA(1, 0, At, B0); PG8_MMA(1, 1, At, B1); PG8_BAR; PG8_SCHED;
.Lrelax_d_lbb0_712_0:
	s_waitcnt lgkmcnt(0)
	s_nop 0
	s_setprio 1
	s_barrier
	v_mfma_f32_16x16x32_bf16 v[126:129], v[150:153], v[182:185], 0
	v_mfma_f32_16x16x32_bf16 v[122:125], v[158:161], v[182:185], 0
	v_mfma_f32_16x16x32_bf16 v[110:113], v[150:153], v[190:193], 0
	v_mfma_f32_16x16x32_bf16 v[106:109], v[158:161], v[190:193], 0
	v_mfma_f32_16x16x32_bf16 v[94:97], v[150:153], v[198:201], 0
	v_mfma_f32_16x16x32_bf16 v[90:93], v[158:161], v[198:201], 0
	v_mfma_f32_16x16x32_bf16 v[78:81], v[150:153], v[206:209], 0
	v_mfma_f32_16x16x32_bf16 v[74:77], v[158:161], v[206:209], 0
	v_mfma_f32_16x16x32_bf16 v[126:129], v[154:157], v[186:189], v[126:129]
	v_mfma_f32_16x16x32_bf16 v[122:125], v[162:165], v[186:189], v[122:125]
	v_mfma_f32_16x16x32_bf16 v[110:113], v[154:157], v[194:197], v[110:113]
	v_mfma_f32_16x16x32_bf16 v[106:109], v[162:165], v[194:197], v[106:109]
	v_mfma_f32_16x16x32_bf16 v[94:97], v[154:157], v[202:205], v[94:97]
	v_mfma_f32_16x16x32_bf16 v[90:93], v[162:165], v[202:205], v[90:93]
	v_mfma_f32_16x16x32_bf16 v[78:81], v[154:157], v[210:213], v[78:81]
	v_mfma_f32_16x16x32_bf16 v[74:77], v[162:165], v[210:213], v[74:77]
	v_mfma_f32_16x16x32_bf16 v[118:121], v[166:169], v[182:185], 0
	v_mfma_f32_16x16x32_bf16 v[114:117], v[174:177], v[182:185], 0
	v_mfma_f32_16x16x32_bf16 v[102:105], v[166:169], v[190:193], 0
	v_mfma_f32_16x16x32_bf16 v[98:101], v[174:177], v[190:193], 0
	v_mfma_f32_16x16x32_bf16 v[86:89], v[166:169], v[198:201], 0
	v_mfma_f32_16x16x32_bf16 v[82:85], v[174:177], v[198:201], 0
	v_mfma_f32_16x16x32_bf16 v[70:73], v[166:169], v[206:209], 0
	v_mfma_f32_16x16x32_bf16 v[66:69], v[174:177], v[206:209], 0
	v_mfma_f32_16x16x32_bf16 v[118:121], v[170:173], v[186:189], v[118:121]
	v_mfma_f32_16x16x32_bf16 v[114:117], v[178:181], v[186:189], v[114:117]
	v_mfma_f32_16x16x32_bf16 v[102:105], v[170:173], v[194:197], v[102:105]
	v_mfma_f32_16x16x32_bf16 v[98:101], v[178:181], v[194:197], v[98:101]
	v_mfma_f32_16x16x32_bf16 v[86:89], v[170:173], v[202:205], v[86:89]
	v_mfma_f32_16x16x32_bf16 v[82:85], v[178:181], v[202:205], v[82:85]
	v_mfma_f32_16x16x32_bf16 v[70:73], v[170:173], v[210:213], v[70:73]
	v_mfma_f32_16x16x32_bf16 v[66:69], v[178:181], v[210:213], v[66:69]
	s_barrier
	s_setprio 0
	s_add_i32 s6, s95, s50
	v_lshl_add_u64 v[144:145], s[16:17], 0, v[134:135]
	s_mov_b32 m0, s6
	ds_read_b128 v[182:185], v148 offset:16384
	ds_read_b128 v[186:189], v148 offset:17408
	ds_read_b128 v[190:193], v148 offset:18432
	ds_read_b128 v[194:197], v148 offset:19456
	ds_read_b128 v[198:201], v148 offset:20480
	ds_read_b128 v[202:205], v148 offset:21504
	ds_read_b128 v[206:209], v148 offset:22528
	ds_read_b128 v[210:213], v148 offset:23552
	global_load_lds_dwordx4 v[144:145], off
	s_add_i32 m0, s6, 0x2000
	s_add_u32 s6, s16, 0x100000
	v_lshl_add_u64 v[214:215], s[16:17], 0, v[130:131]
	s_addc_u32 s7, s17, 0
	s_add_i32 s95, vcc_lo, s50
	global_load_lds_dwordx4 v[214:215], off
	v_lshl_add_u64 v[216:217], s[6:7], 0, v[134:135]
	s_mov_b32 m0, s95
	v_lshl_add_u64 v[218:219], s[42:43], 0, v[132:133]
	global_load_lds_dwordx4 v[216:217], off
	v_lshl_add_u64 v[216:217], s[6:7], 0, v[130:131]
	s_add_i32 m0, s95, 0x2000
	s_nop 0
	global_load_lds_dwordx4 v[216:217], off
	v_lshl_add_u64 v[216:217], s[42:43], 0, v[136:137]
	s_mov_b32 m0, s69
	s_nop 0
	global_load_lds_dwordx4 v[216:217], off
	s_mov_b32 m0, s72
	s_nop 0
	global_load_lds_dwordx4 v[218:219], off
	s_cmp_eq_u32 s98, 0
	s_cbranch_scc1 .Lrelax_s_lbb0_712_1
	s_waitcnt vmcnt(24)
	s_branch .Lrelax_d_lbb0_712_1

; #define PG8_STAGEA(bufoff, gbase, voff) PG8_STAGE_X(bufoff, gbase, voff, AUXA)
; #define PG8_LDA(dst, b, h) do { _Pragma("unroll") for (int m = 0; m < 4; ++m) _Pragma("unroll") for (int k = 0; k < 2; ++k) dst[m][k] = *(const PG8_LAS bf16x8*)(lds + PG8_SA(b, h) + aoff + m * 2048 + k * 1024); } while (0)
; #define PG8_LDB(dst, b, h) do { _Pragma("unroll") for (int n = 0; n < 2; ++n) _Pragma("unroll") for (int k = 0; k < 2; ++k) dst[n][k] = *(const PG8_LAS bf16x8*)(lds + PG8_SB(b, h) + boff + n * 2048 + k * 1024); } while (0)
; #define PG8_MMA(ai, bj, At, Bt) do { if (GEMM_PRIO_MODE == 0) __builtin_amdgcn_s_setprio(1); PG8_MMA_LOOPS \
;         acc[ai][bj][m][n] = __builtin_amdgcn_mfma_f32_16x16x32_bf16(Bt[n][k], At[m][k], acc[ai][bj][m][n], 0, 0, 0); if (GEMM_PRIO_MODE == 0) __builtin_amdgcn_s_setprio(0); } while (0)
; #define PG8_WAIT_V(n) asm volatile("s_waitcnt vmcnt(" #n ")" ::: "memory")
; #define PG8_WAIT_VR(n, nr, flag) asm volatile("s_cmp_eq_u32 %0, 0\n\ts_cbranch_scc1 .Lpg8s%=\n\ts_waitcnt vmcnt(" #nr ")\n\ts_branch .Lpg8d%=\n.Lpg8s%=:\n\ts_waitcnt vmcnt(" #n ")\n.Lpg8d%=:" :: "s"(flag) : "memory", "scc")
; #define PG8_WAIT_L(n) asm volatile("s_waitcnt lgkmcnt(" #n ")" ::: "memory")
; #define PG8_BAR __builtin_amdgcn_s_barrier()
; #define PG8_SCHED __builtin_amdgcn_sched_barrier(0)
;     ...
;             PG8_WAIT_VR(8, 24, relax); PG8_WAIT_L(0); PG8_BAR; PG8_MMA(1, 0, At, B0); PG8_MMA(1, 1, At, B1); PG8_BAR; PG8_SCHED;
;     ...
;             PG8_WAIT_V(8); PG8_WAIT_L(0); PG8_BAR; PG8_MMA(1, 0, At, B0); PG8_MMA(1, 1, At, B1); PG8_BAR; PG8_SCHED;
;     ...
;             PG8_LDB(B0, 1, 0); PG8_LDB(B1, 1, 1); PG8_SCHED; PG8_LDA(At, 1, 0); PG8_STAGEA(PG8_SA(0, 1), a2 + hstepA, voffA);
;             PG8_WAIT_V(8); PG8_WAIT_L(0); PG8_BAR; PG8_MMA(0, 0, At, B0); PG8_MMA(0, 1, At, B1); PG8_BAR; PG8_SCHED;
.Lrelax_d_lbb0_712_1:
	s_waitcnt lgkmcnt(0)
	s_nop 0
	s_nop 0
	s_setprio 1
	s_barrier
	v_mfma_f32_16x16x32_bf16 v[62:65], v[150:153], v[182:185], 0
	v_mfma_f32_16x16x32_bf16 v[58:61], v[158:161], v[182:185], 0
	v_mfma_f32_16x16x32_bf16 v[46:49], v[150:153], v[190:193], 0
	v_mfma_f32_16x16x32_bf16 v[42:45], v[158:161], v[190:193], 0
	v_mfma_f32_16x16x32_bf16 v[30:33], v[150:153], v[198:201], 0
	v_mfma_f32_16x16x32_bf16 v[26:29], v[158:161], v[198:201], 0
	v_mfma_f32_16x16x32_bf16 v[12:15], v[150:153], v[206:209], 0
	v_mfma_f32_16x16x32_bf16 v[8:11], v[158:161], v[206:209], 0
	v_mfma_f32_16x16x32_bf16 v[62:65], v[154:157], v[186:189], v[62:65]
	v_mfma_f32_16x16x32_bf16 v[58:61], v[162:165], v[186:189], v[58:61]
	v_mfma_f32_16x16x32_bf16 v[46:49], v[154:157], v[194:197], v[46:49]
	v_mfma_f32_16x16x32_bf16 v[42:45], v[162:165], v[194:197], v[42:45]
	v_mfma_f32_16x16x32_bf16 v[30:33], v[154:157], v[202:205], v[30:33]
	v_mfma_f32_16x16x32_bf16 v[26:29], v[162:165], v[202:205], v[26:29]
	v_mfma_f32_16x16x32_bf16 v[12:15], v[154:157], v[210:213], v[12:15]
	v_mfma_f32_16x16x32_bf16 v[8:11], v[162:165], v[210:213], v[8:11]
	v_mfma_f32_16x16x32_bf16 v[54:57], v[166:169], v[182:185], 0
	v_mfma_f32_16x16x32_bf16 v[50:53], v[174:177], v[182:185], 0
	v_mfma_f32_16x16x32_bf16 v[38:41], v[166:169], v[190:193], 0
	v_mfma_f32_16x16x32_bf16 v[34:37], v[174:177], v[190:193], 0
	v_mfma_f32_16x16x32_bf16 v[22:25], v[166:169], v[198:201], 0
	v_mfma_f32_16x16x32_bf16 v[18:21], v[174:177], v[198:201], 0
	v_mfma_f32_16x16x32_bf16 v[4:7], v[166:169], v[206:209], 0
	v_mfma_f32_16x16x32_bf16 v[0:3], v[174:177], v[206:209], 0
	v_mfma_f32_16x16x32_bf16 v[54:57], v[170:173], v[186:189], v[54:57]
	v_mfma_f32_16x16x32_bf16 v[50:53], v[178:181], v[186:189], v[50:53]
	v_mfma_f32_16x16x32_bf16 v[38:41], v[170:173], v[194:197], v[38:41]
	v_mfma_f32_16x16x32_bf16 v[34:37], v[178:181], v[194:197], v[34:37]
	v_mfma_f32_16x16x32_bf16 v[22:25], v[170:173], v[202:205], v[22:25]
	v_mfma_f32_16x16x32_bf16 v[18:21], v[178:181], v[202:205], v[18:21]
	v_mfma_f32_16x16x32_bf16 v[4:7], v[170:173], v[210:213], v[4:7]
	v_mfma_f32_16x16x32_bf16 v[0:3], v[178:181], v[210:213], v[0:3]
	s_barrier
	s_setprio 0
	s_add_i32 s95, 0, 0x18000
	v_add_u32_e32 v149, s95, v146
	s_add_i32 vcc_lo, 0, 0x1c000
	ds_read_b128 v[150:153], v149
	ds_read_b128 v[154:157], v149 offset:1024
	ds_read_b128 v[158:161], v149 offset:2048
	ds_read_b128 v[162:165], v149 offset:3072
	v_add_u32_e32 v149, vcc_lo, v146
	ds_read_b128 v[166:169], v149
	ds_read_b128 v[170:173], v149 offset:1024
	ds_read_b128 v[174:177], v149 offset:2048
	ds_read_b128 v[178:181], v149 offset:3072
	s_add_u32 s6, s42, 0x100000
	s_addc_u32 s7, s43, 0
	s_mov_b32 m0, s73
	v_lshl_add_u64 v[220:221], s[6:7], 0, v[136:137]
	ds_read_b128 v[182:185], v148 offset:32768
	ds_read_b128 v[186:189], v148 offset:33792
	ds_read_b128 v[190:193], v148 offset:34816
	ds_read_b128 v[194:197], v148 offset:35840
	ds_read_b128 v[198:201], v148 offset:36864
	ds_read_b128 v[202:205], v148 offset:37888
	ds_read_b128 v[206:209], v148 offset:38912
	ds_read_b128 v[210:213], v148 offset:39936
	global_load_lds_dwordx4 v[220:221], off
	v_lshl_add_u64 v[220:221], s[6:7], 0, v[132:133]
	s_mov_b32 m0, s82
	s_nop 0
	global_load_lds_dwordx4 v[220:221], off
	s_waitcnt vmcnt(8)
	s_waitcnt lgkmcnt(0)
	s_setprio 1
	s_barrier
	v_mfma_f32_16x16x32_bf16 v[126:129], v[150:153], v[182:185], v[126:129]
	v_mfma_f32_16x16x32_bf16 v[122:125], v[158:161], v[182:185], v[122:125]
	v_mfma_f32_16x16x32_bf16 v[110:113], v[150:153], v[190:193], v[110:113]
	v_mfma_f32_16x16x32_bf16 v[106:109], v[158:161], v[190:193], v[106:109]
	v_mfma_f32_16x16x32_bf16 v[94:97], v[150:153], v[198:201], v[94:97]
	v_mfma_f32_16x16x32_bf16 v[90:93], v[158:161], v[198:201], v[90:93]
	v_mfma_f32_16x16x32_bf16 v[78:81], v[150:153], v[206:209], v[78:81]
	v_mfma_f32_16x16x32_bf16 v[74:77], v[158:161], v[206:209], v[74:77]
	v_mfma_f32_16x16x32_bf16 v[126:129], v[154:157], v[186:189], v[126:129]
	v_mfma_f32_16x16x32_bf16 v[122:125], v[162:165], v[186:189], v[122:125]
	v_mfma_f32_16x16x32_bf16 v[110:113], v[154:157], v[194:197], v[110:113]
	v_mfma_f32_16x16x32_bf16 v[106:109], v[162:165], v[194:197], v[106:109]
	v_mfma_f32_16x16x32_bf16 v[94:97], v[154:157], v[202:205], v[94:97]
	v_mfma_f32_16x16x32_bf16 v[90:93], v[162:165], v[202:205], v[90:93]
	v_mfma_f32_16x16x32_bf16 v[78:81], v[154:157], v[210:213], v[78:81]
	v_mfma_f32_16x16x32_bf16 v[74:77], v[162:165], v[210:213], v[74:77]
	v_mfma_f32_16x16x32_bf16 v[118:121], v[166:169], v[182:185], v[118:121]
	v_mfma_f32_16x16x32_bf16 v[114:117], v[174:177], v[182:185], v[114:117]
	v_mfma_f32_16x16x32_bf16 v[102:105], v[166:169], v[190:193], v[102:105]
	v_mfma_f32_16x16x32_bf16 v[98:101], v[174:177], v[190:193], v[98:101]
	v_mfma_f32_16x16x32_bf16 v[86:89], v[166:169], v[198:201], v[86:89]
	v_mfma_f32_16x16x32_bf16 v[82:85], v[174:177], v[198:201], v[82:85]
	v_mfma_f32_16x16x32_bf16 v[70:73], v[166:169], v[206:209], v[70:73]
	v_mfma_f32_16x16x32_bf16 v[66:69], v[174:177], v[206:209], v[66:69]
	v_mfma_f32_16x16x32_bf16 v[118:121], v[170:173], v[186:189], v[118:121]
	v_mfma_f32_16x16x32_bf16 v[114:117], v[178:181], v[186:189], v[114:117]
	v_mfma_f32_16x16x32_bf16 v[102:105], v[170:173], v[194:197], v[102:105]
	v_mfma_f32_16x16x32_bf16 v[98:101], v[178:181], v[194:197], v[98:101]
	v_mfma_f32_16x16x32_bf16 v[86:89], v[170:173], v[202:205], v[86:89]
	v_mfma_f32_16x16x32_bf16 v[82:85], v[178:181], v[202:205], v[82:85]
	v_mfma_f32_16x16x32_bf16 v[70:73], v[170:173], v[210:213], v[70:73]
	v_mfma_f32_16x16x32_bf16 v[66:69], v[178:181], v[210:213], v[66:69]
	s_barrier
; #define PG8_STAGEA(bufoff, gbase, voff) PG8_STAGE_X(bufoff, gbase, voff, AUXA)
; #define PG8_STAGEB(bufoff, gbase, voff) PG8_STAGE_X(bufoff, gbase, voff, AUXB)
; #define PG8_LDA(dst, b, h) do { _Pragma("unroll") for (int m = 0; m < 4; ++m) _Pragma("unroll") for (int k = 0; k < 2; ++k) dst[m][k] = *(const PG8_LAS bf16x8*)(lds + PG8_SA(b, h) + aoff + m * 2048 + k * 1024); } while (0)
; #define PG8_WAIT_V(n) asm volatile("s_waitcnt vmcnt(" #n ")" ::: "memory")
; #define PG8_WAIT_L(n) asm volatile("s_waitcnt lgkmcnt(" #n ")" ::: "memory")
;     ...
;         for (int t = t0; t < nt; t += 2) {
;             const bool last = (t == nt - 2);
;             const char* a1 = cA + (size_t)(t + 1) * kstepA;
;             const char* a2 = last ? nA : cA + (size_t)(t + 2) * kstepA; const char* b2 = last ? nB : cB + (size_t)(t + 2) * kstepB;
;             const char* a3 = a2 + kstepA; const char* b3 = b2 + kstepB;
;             if (last && has_next) S.a_ready(nxt);
;             if constexpr (SP2) {
;             PG8_LDB(B0, 0, 0); PG8_LDB(B1, 0, 1); PG8_SCHED; PG8_LDA(At, 0, 0); PG8_STAGEA(PG8_SA(1, 1), a1 + hstepA, voffA);
;     ...
;             const int relax = __builtin_amdgcn_readfirstlane((t == 0 && ui > 0) ? 1 : 0);
;             PG8_WAIT_VR(8, 24, relax); PG8_WAIT_L(0); PG8_BAR; PG8_MMA(0, 0, At, B0); PG8_MMA(0, 1, At, B1); PG8_BAR; PG8_SCHED;
;     ...
;             PG8_WAIT_V(8); PG8_WAIT_L(0); PG8_BAR; PG8_MMA(0, 0, At, B0); PG8_MMA(0, 1, At, B1); PG8_BAR; PG8_SCHED;
;     ...
;             PG8_LDA(At, 0, 1); PG8_STAGEB(PG8_SB(0, 0), b2, voffB); PG8_STAGEB(PG8_SB(0, 1), b2 + hstepB, voffB); PG8_STAGEA(PG8_SA(0, 0), a2, voffA);
;     ...
;             PG8_WAIT_VR(8, 24, relax); PG8_WAIT_L(0); PG8_BAR; PG8_MMA(1, 0, At, B0); PG8_MMA(1, 1, At, B1); PG8_BAR; PG8_SCHED;
;     ...
;             PG8_WAIT_V(8); PG8_WAIT_L(0); PG8_BAR; PG8_MMA(1, 0, At, B0); PG8_MMA(1, 1, At, B1); PG8_BAR; PG8_SCHED;
;     ...
;             PG8_LDB(B0, 1, 0); PG8_LDB(B1, 1, 1); PG8_SCHED; PG8_LDA(At, 1, 0); PG8_STAGEA(PG8_SA(0, 1), a2 + hstepA, voffA);
;             PG8_WAIT_V(8); PG8_WAIT_L(0); PG8_BAR; PG8_MMA(0, 0, At, B0); PG8_MMA(0, 1, At, B1); PG8_BAR; PG8_SCHED;
;             PG8_LDA(At, 1, 1); PG8_STAGEB(PG8_SB(1, 0), b3, voffB); PG8_STAGEB(PG8_SB(1, 1), b3 + hstepB, voffB); PG8_STAGEA(PG8_SA(1, 0), a3, voffA);
;             PG8_WAIT_V(8); PG8_WAIT_L(0); PG8_BAR; PG8_MMA(1, 0, At, B0); PG8_MMA(1, 1, At, B1); PG8_BAR; PG8_SCHED;
	s_setprio 0
	s_add_i32 s6, s95, s50
	v_lshl_add_u64 v[144:145], v[144:145], 0, s[86:87]
	s_mov_b32 m0, s6
	ds_read_b128 v[182:185], v148 offset:49152
	ds_read_b128 v[186:189], v148 offset:50176
	ds_read_b128 v[190:193], v148 offset:51200
	ds_read_b128 v[194:197], v148 offset:52224
	ds_read_b128 v[198:201], v148 offset:53248
	ds_read_b128 v[202:205], v148 offset:54272
	ds_read_b128 v[206:209], v148 offset:55296
	ds_read_b128 v[210:213], v148 offset:56320
	global_load_lds_dwordx4 v[144:145], off
	s_add_i32 m0, s6, 0x2000
	s_add_u32 s6, s16, 0x100080
	v_lshl_add_u64 v[144:145], v[214:215], 0, s[86:87]
	s_addc_u32 s7, s17, 0
	s_add_i32 s16, vcc_lo, s50
	global_load_lds_dwordx4 v[144:145], off
	v_lshl_add_u64 v[144:145], s[6:7], 0, v[134:135]
	s_mov_b32 m0, s16
	s_nop 0
	global_load_lds_dwordx4 v[144:145], off
	v_lshl_add_u64 v[144:145], s[6:7], 0, v[130:131]
	s_add_i32 m0, s16, 0x2000
	s_nop 0
	global_load_lds_dwordx4 v[144:145], off
	v_lshl_add_u64 v[144:145], v[216:217], 0, s[86:87]
	s_mov_b32 m0, s83
	s_nop 0
	global_load_lds_dwordx4 v[144:145], off
	v_lshl_add_u64 v[144:145], v[218:219], 0, s[86:87]
	s_mov_b32 m0, s90
	s_nop 0
	global_load_lds_dwordx4 v[144:145], off
	s_waitcnt vmcnt(8)
	s_waitcnt lgkmcnt(0)
	s_nop 0
	s_setprio 1
	s_barrier
	v_mfma_f32_16x16x32_bf16 v[62:65], v[150:153], v[182:185], v[62:65]
	v_mfma_f32_16x16x32_bf16 v[58:61], v[158:161], v[182:185], v[58:61]
	v_mfma_f32_16x16x32_bf16 v[46:49], v[150:153], v[190:193], v[46:49]
	v_mfma_f32_16x16x32_bf16 v[42:45], v[158:161], v[190:193], v[42:45]
	v_mfma_f32_16x16x32_bf16 v[30:33], v[150:153], v[198:201], v[30:33]
	v_mfma_f32_16x16x32_bf16 v[26:29], v[158:161], v[198:201], v[26:29]
	v_mfma_f32_16x16x32_bf16 v[12:15], v[150:153], v[206:209], v[12:15]
	v_mfma_f32_16x16x32_bf16 v[8:11], v[158:161], v[206:209], v[8:11]
	v_mfma_f32_16x16x32_bf16 v[62:65], v[154:157], v[186:189], v[62:65]
	v_mfma_f32_16x16x32_bf16 v[58:61], v[162:165], v[186:189], v[58:61]
	v_mfma_f32_16x16x32_bf16 v[46:49], v[154:157], v[194:197], v[46:49]
	v_mfma_f32_16x16x32_bf16 v[42:45], v[162:165], v[194:197], v[42:45]
	v_mfma_f32_16x16x32_bf16 v[30:33], v[154:157], v[202:205], v[30:33]
	v_mfma_f32_16x16x32_bf16 v[26:29], v[162:165], v[202:205], v[26:29]
	v_mfma_f32_16x16x32_bf16 v[12:15], v[154:157], v[210:213], v[12:15]
	v_mfma_f32_16x16x32_bf16 v[8:11], v[162:165], v[210:213], v[8:11]
	v_mfma_f32_16x16x32_bf16 v[54:57], v[166:169], v[182:185], v[54:57]
	v_mfma_f32_16x16x32_bf16 v[50:53], v[174:177], v[182:185], v[50:53]
	v_mfma_f32_16x16x32_bf16 v[38:41], v[166:169], v[190:193], v[38:41]
	v_mfma_f32_16x16x32_bf16 v[34:37], v[174:177], v[190:193], v[34:37]
	v_mfma_f32_16x16x32_bf16 v[22:25], v[166:169], v[198:201], v[22:25]
	v_mfma_f32_16x16x32_bf16 v[18:21], v[174:177], v[198:201], v[18:21]
	v_mfma_f32_16x16x32_bf16 v[4:7], v[166:169], v[206:209], v[4:7]
	v_mfma_f32_16x16x32_bf16 v[0:3], v[174:177], v[206:209], v[0:3]
	v_mfma_f32_16x16x32_bf16 v[54:57], v[170:173], v[186:189], v[54:57]
	v_mfma_f32_16x16x32_bf16 v[50:53], v[178:181], v[186:189], v[50:53]
	v_mfma_f32_16x16x32_bf16 v[38:41], v[170:173], v[194:197], v[38:41]
	v_mfma_f32_16x16x32_bf16 v[34:37], v[178:181], v[194:197], v[34:37]
	v_mfma_f32_16x16x32_bf16 v[22:25], v[170:173], v[202:205], v[22:25]
	v_mfma_f32_16x16x32_bf16 v[18:21], v[178:181], v[202:205], v[18:21]
	v_mfma_f32_16x16x32_bf16 v[4:7], v[170:173], v[210:213], v[4:7]
	v_mfma_f32_16x16x32_bf16 v[0:3], v[178:181], v[210:213], v[0:3]
	s_barrier
	s_setprio 0
	s_add_i32 s39, s39, 2
	s_add_u32 s40, s40, 0x100
	s_addc_u32 s41, s41, 0
	s_add_u32 s12, s12, 0x100
	s_addc_u32 s13, s13, 0
	v_add_u32_e32 v222, 0x10000, v146
.LBB0_712:
	s_add_u32 s6, s40, 0xfff00080
	s_addc_u32 s7, s41, -1
	s_add_i32 s95, 0, 0x10000
	s_cmp_eq_u32 s39, 60
	s_cselect_b32 s43, s0, s7
	s_cselect_b32 s42, s1, s6
	s_cselect_b32 s17, s23, s13
	s_cselect_b32 s16, s25, s12
	s_add_i32 vcc_lo, 0, 0x14000
	ds_read_b128 v[150:153], v222
	ds_read_b128 v[154:157], v222 offset:1024
	ds_read_b128 v[158:161], v222 offset:2048
	ds_read_b128 v[162:165], v222 offset:3072
	ds_read_b128 v[166:169], v222 offset:16384
	ds_read_b128 v[170:173], v222 offset:17408
	ds_read_b128 v[174:177], v222 offset:18432
	ds_read_b128 v[178:181], v222 offset:19456
	s_add_i32 m0, s69, 0xc000
	ds_read_b128 v[182:185], v148
	ds_read_b128 v[186:189], v148 offset:1024
	ds_read_b128 v[190:193], v148 offset:2048
	ds_read_b128 v[194:197], v148 offset:3072
	ds_read_b128 v[198:201], v148 offset:4096
	ds_read_b128 v[202:205], v148 offset:5120
	ds_read_b128 v[206:209], v148 offset:6144
	ds_read_b128 v[210:213], v148 offset:7168
	global_load_lds_dwordx4 v140, s[40:41]
	s_add_i32 m0, s69, 0xe000
	s_nop 0
	global_load_lds_dwordx4 v142, s[40:41]
	s_waitcnt vmcnt(8)
	s_waitcnt lgkmcnt(0)
	s_nop 0
	s_nop 0
	s_setprio 1
	s_barrier
; #define PG8_STAGEA(bufoff, gbase, voff) PG8_STAGE_X(bufoff, gbase, voff, AUXA)
; #define PG8_STAGEB(bufoff, gbase, voff) PG8_STAGE_X(bufoff, gbase, voff, AUXB)
; #define PG8_LDA(dst, b, h) do { _Pragma("unroll") for (int m = 0; m < 4; ++m) _Pragma("unroll") for (int k = 0; k < 2; ++k) dst[m][k] = *(const PG8_LAS bf16x8*)(lds + PG8_SA(b, h) + aoff + m * 2048 + k * 1024); } while (0)
; #define PG8_LDB(dst, b, h) do { _Pragma("unroll") for (int n = 0; n < 2; ++n) _Pragma("unroll") for (int k = 0; k < 2; ++k) dst[n][k] = *(const PG8_LAS bf16x8*)(lds + PG8_SB(b, h) + boff + n * 2048 + k * 1024); } while (0)
; #define PG8_MMA(ai, bj, At, Bt) do { if (GEMM_PRIO_MODE == 0) __builtin_amdgcn_s_setprio(1); PG8_MMA_LOOPS \
;         acc[ai][bj][m][n] = __builtin_amdgcn_mfma_f32_16x16x32_bf16(Bt[n][k], At[m][k], acc[ai][bj][m][n], 0, 0, 0); if (GEMM_PRIO_MODE == 0) __builtin_amdgcn_s_setprio(0); } while (0)
; #define PG8_WAIT_V(n) asm volatile("s_waitcnt vmcnt(" #n ")" ::: "memory")
; #define PG8_WAIT_VR(n, nr, flag) asm volatile("s_cmp_eq_u32 %0, 0\n\ts_cbranch_scc1 .Lpg8s%=\n\ts_waitcnt vmcnt(" #nr ")\n\ts_branch .Lpg8d%=\n.Lpg8s%=:\n\ts_waitcnt vmcnt(" #n ")\n.Lpg8d%=:" :: "s"(flag) : "memory", "scc")
; #define PG8_WAIT_L(n) asm volatile("s_waitcnt lgkmcnt(" #n ")" ::: "memory")
; #define PG8_BAR __builtin_amdgcn_s_barrier()
; #define PG8_SCHED __builtin_amdgcn_sched_barrier(0)
;     ...
;             PG8_WAIT_V(8); PG8_WAIT_L(0); PG8_BAR; PG8_MMA(0, 0, At, B0); PG8_MMA(0, 1, At, B1); PG8_BAR; PG8_SCHED;
;     ...
;             PG8_LDA(At, 0, 1); PG8_STAGEB(PG8_SB(0, 0), b2, voffB); PG8_STAGEB(PG8_SB(0, 1), b2 + hstepB, voffB); PG8_STAGEA(PG8_SA(0, 0), a2, voffA);
;     ...
;             PG8_WAIT_VR(8, 24, relax); PG8_WAIT_L(0); PG8_BAR; PG8_MMA(1, 0, At, B0); PG8_MMA(1, 1, At, B1); PG8_BAR; PG8_SCHED;
;     ...
;             PG8_WAIT_V(8); PG8_WAIT_L(0); PG8_BAR; PG8_MMA(1, 0, At, B0); PG8_MMA(1, 1, At, B1); PG8_BAR; PG8_SCHED;
;     ...
;             PG8_LDB(B0, 1, 0); PG8_LDB(B1, 1, 1); PG8_SCHED; PG8_LDA(At, 1, 0); PG8_STAGEA(PG8_SA(0, 1), a2 + hstepA, voffA);
;             PG8_WAIT_V(8); PG8_WAIT_L(0); PG8_BAR; PG8_MMA(0, 0, At, B0); PG8_MMA(0, 1, At, B1); PG8_BAR; PG8_SCHED;
	v_mfma_f32_16x16x32_bf16 v[126:129], v[150:153], v[182:185], v[126:129]
	v_mfma_f32_16x16x32_bf16 v[122:125], v[158:161], v[182:185], v[122:125]
	v_mfma_f32_16x16x32_bf16 v[110:113], v[150:153], v[190:193], v[110:113]
	v_mfma_f32_16x16x32_bf16 v[106:109], v[158:161], v[190:193], v[106:109]
	v_mfma_f32_16x16x32_bf16 v[94:97], v[150:153], v[198:201], v[94:97]
	v_mfma_f32_16x16x32_bf16 v[90:93], v[158:161], v[198:201], v[90:93]
	v_mfma_f32_16x16x32_bf16 v[78:81], v[150:153], v[206:209], v[78:81]
	v_mfma_f32_16x16x32_bf16 v[74:77], v[158:161], v[206:209], v[74:77]
	v_mfma_f32_16x16x32_bf16 v[126:129], v[154:157], v[186:189], v[126:129]
	v_mfma_f32_16x16x32_bf16 v[122:125], v[162:165], v[186:189], v[122:125]
	v_mfma_f32_16x16x32_bf16 v[110:113], v[154:157], v[194:197], v[110:113]
	v_mfma_f32_16x16x32_bf16 v[106:109], v[162:165], v[194:197], v[106:109]
	v_mfma_f32_16x16x32_bf16 v[94:97], v[154:157], v[202:205], v[94:97]
	v_mfma_f32_16x16x32_bf16 v[90:93], v[162:165], v[202:205], v[90:93]
	v_mfma_f32_16x16x32_bf16 v[78:81], v[154:157], v[210:213], v[78:81]
	v_mfma_f32_16x16x32_bf16 v[74:77], v[162:165], v[210:213], v[74:77]
	v_mfma_f32_16x16x32_bf16 v[118:121], v[166:169], v[182:185], v[118:121]
	v_mfma_f32_16x16x32_bf16 v[114:117], v[174:177], v[182:185], v[114:117]
	v_mfma_f32_16x16x32_bf16 v[102:105], v[166:169], v[190:193], v[102:105]
	v_mfma_f32_16x16x32_bf16 v[98:101], v[174:177], v[190:193], v[98:101]
	v_mfma_f32_16x16x32_bf16 v[86:89], v[166:169], v[198:201], v[86:89]
	v_mfma_f32_16x16x32_bf16 v[82:85], v[174:177], v[198:201], v[82:85]
	v_mfma_f32_16x16x32_bf16 v[70:73], v[166:169], v[206:209], v[70:73]
	v_mfma_f32_16x16x32_bf16 v[66:69], v[174:177], v[206:209], v[66:69]
	v_mfma_f32_16x16x32_bf16 v[118:121], v[170:173], v[186:189], v[118:121]
	v_mfma_f32_16x16x32_bf16 v[114:117], v[178:181], v[186:189], v[114:117]
	v_mfma_f32_16x16x32_bf16 v[102:105], v[170:173], v[194:197], v[102:105]
	v_mfma_f32_16x16x32_bf16 v[98:101], v[178:181], v[194:197], v[98:101]
	v_mfma_f32_16x16x32_bf16 v[86:89], v[170:173], v[202:205], v[86:89]
	v_mfma_f32_16x16x32_bf16 v[82:85], v[178:181], v[202:205], v[82:85]
	v_mfma_f32_16x16x32_bf16 v[70:73], v[170:173], v[210:213], v[70:73]
	v_mfma_f32_16x16x32_bf16 v[66:69], v[178:181], v[210:213], v[66:69]
	s_barrier
	s_setprio 0
	s_add_i32 s6, s95, s50
	s_mov_b32 m0, s6
	ds_read_b128 v[182:185], v148 offset:16384
	ds_read_b128 v[186:189], v148 offset:17408
	ds_read_b128 v[190:193], v148 offset:18432
	ds_read_b128 v[194:197], v148 offset:19456
	ds_read_b128 v[198:201], v148 offset:20480
	ds_read_b128 v[202:205], v148 offset:21504
	ds_read_b128 v[206:209], v148 offset:22528
	ds_read_b128 v[210:213], v148 offset:23552
	global_load_lds_dwordx4 v134, s[16:17]
	s_add_i32 m0, s6, 0x2000
	s_add_u32 s6, s16, 0x100000
	s_addc_u32 s7, s17, 0
	s_add_i32 s95, vcc_lo, s50
	global_load_lds_dwordx4 v130, s[16:17]
	s_mov_b32 m0, s95
	s_nop 0
	global_load_lds_dwordx4 v134, s[6:7]
	s_add_i32 m0, s95, 0x2000
	s_nop 0
	global_load_lds_dwordx4 v130, s[6:7]
	s_mov_b32 m0, s69
	s_nop 0
	global_load_lds_dwordx4 v136, s[42:43]
	s_mov_b32 m0, s72
	s_nop 0
	global_load_lds_dwordx4 v132, s[42:43]
	s_waitcnt vmcnt(8)
	s_waitcnt lgkmcnt(0)
	s_nop 0
	s_setprio 1
	s_barrier
	v_mfma_f32_16x16x32_bf16 v[62:65], v[150:153], v[182:185], v[62:65]
	v_mfma_f32_16x16x32_bf16 v[58:61], v[158:161], v[182:185], v[58:61]
	v_mfma_f32_16x16x32_bf16 v[46:49], v[150:153], v[190:193], v[46:49]
	v_mfma_f32_16x16x32_bf16 v[42:45], v[158:161], v[190:193], v[42:45]
	v_mfma_f32_16x16x32_bf16 v[30:33], v[150:153], v[198:201], v[30:33]
	v_mfma_f32_16x16x32_bf16 v[26:29], v[158:161], v[198:201], v[26:29]
	v_mfma_f32_16x16x32_bf16 v[12:15], v[150:153], v[206:209], v[12:15]
	v_mfma_f32_16x16x32_bf16 v[8:11], v[158:161], v[206:209], v[8:11]
	v_mfma_f32_16x16x32_bf16 v[62:65], v[154:157], v[186:189], v[62:65]
	v_mfma_f32_16x16x32_bf16 v[58:61], v[162:165], v[186:189], v[58:61]
	v_mfma_f32_16x16x32_bf16 v[46:49], v[154:157], v[194:197], v[46:49]
	v_mfma_f32_16x16x32_bf16 v[42:45], v[162:165], v[194:197], v[42:45]
	v_mfma_f32_16x16x32_bf16 v[30:33], v[154:157], v[202:205], v[30:33]
	v_mfma_f32_16x16x32_bf16 v[26:29], v[162:165], v[202:205], v[26:29]
	v_mfma_f32_16x16x32_bf16 v[12:15], v[154:157], v[210:213], v[12:15]
	v_mfma_f32_16x16x32_bf16 v[8:11], v[162:165], v[210:213], v[8:11]
	v_mfma_f32_16x16x32_bf16 v[54:57], v[166:169], v[182:185], v[54:57]
	v_mfma_f32_16x16x32_bf16 v[50:53], v[174:177], v[182:185], v[50:53]
	v_mfma_f32_16x16x32_bf16 v[38:41], v[166:169], v[190:193], v[38:41]
	v_mfma_f32_16x16x32_bf16 v[34:37], v[174:177], v[190:193], v[34:37]
	v_mfma_f32_16x16x32_bf16 v[22:25], v[166:169], v[198:201], v[22:25]
	v_mfma_f32_16x16x32_bf16 v[18:21], v[174:177], v[198:201], v[18:21]
	v_mfma_f32_16x16x32_bf16 v[4:7], v[166:169], v[206:209], v[4:7]
	v_mfma_f32_16x16x32_bf16 v[0:3], v[174:177], v[206:209], v[0:3]
	v_mfma_f32_16x16x32_bf16 v[54:57], v[170:173], v[186:189], v[54:57]
	v_mfma_f32_16x16x32_bf16 v[50:53], v[178:181], v[186:189], v[50:53]
	v_mfma_f32_16x16x32_bf16 v[38:41], v[170:173], v[194:197], v[38:41]
	v_mfma_f32_16x16x32_bf16 v[34:37], v[178:181], v[194:197], v[34:37]
	v_mfma_f32_16x16x32_bf16 v[22:25], v[170:173], v[202:205], v[22:25]
	v_mfma_f32_16x16x32_bf16 v[18:21], v[178:181], v[202:205], v[18:21]
	v_mfma_f32_16x16x32_bf16 v[4:7], v[170:173], v[210:213], v[4:7]
	v_mfma_f32_16x16x32_bf16 v[0:3], v[178:181], v[210:213], v[0:3]
	s_barrier
; #define PG8_STAGEA(bufoff, gbase, voff) PG8_STAGE_X(bufoff, gbase, voff, AUXA)
; #define PG8_STAGEB(bufoff, gbase, voff) PG8_STAGE_X(bufoff, gbase, voff, AUXB)
; #define PG8_LDA(dst, b, h) do { _Pragma("unroll") for (int m = 0; m < 4; ++m) _Pragma("unroll") for (int k = 0; k < 2; ++k) dst[m][k] = *(const PG8_LAS bf16x8*)(lds + PG8_SA(b, h) + aoff + m * 2048 + k * 1024); } while (0)
; #define PG8_LDB(dst, b, h) do { _Pragma("unroll") for (int n = 0; n < 2; ++n) _Pragma("unroll") for (int k = 0; k < 2; ++k) dst[n][k] = *(const PG8_LAS bf16x8*)(lds + PG8_SB(b, h) + boff + n * 2048 + k * 1024); } while (0)
; #define PG8_MMA(ai, bj, At, Bt) do { if (GEMM_PRIO_MODE == 0) __builtin_amdgcn_s_setprio(1); PG8_MMA_LOOPS \
;         acc[ai][bj][m][n] = __builtin_amdgcn_mfma_f32_16x16x32_bf16(Bt[n][k], At[m][k], acc[ai][bj][m][n], 0, 0, 0); if (GEMM_PRIO_MODE == 0) __builtin_amdgcn_s_setprio(0); } while (0)
; #define PG8_WAIT_V(n) asm volatile("s_waitcnt vmcnt(" #n ")" ::: "memory")
; #define PG8_WAIT_L(n) asm volatile("s_waitcnt lgkmcnt(" #n ")" ::: "memory")
; #define PG8_BAR __builtin_amdgcn_s_barrier()
; #define PG8_SCHED __builtin_amdgcn_sched_barrier(0)
;     ...
;             PG8_LDB(B0, 1, 0); PG8_LDB(B1, 1, 1); PG8_SCHED; PG8_LDA(At, 1, 0); PG8_STAGEA(PG8_SA(0, 1), a2 + hstepA, voffA);
;             PG8_WAIT_V(8); PG8_WAIT_L(0); PG8_BAR; PG8_MMA(0, 0, At, B0); PG8_MMA(0, 1, At, B1); PG8_BAR; PG8_SCHED;
;             PG8_LDA(At, 1, 1); PG8_STAGEB(PG8_SB(1, 0), b3, voffB); PG8_STAGEB(PG8_SB(1, 1), b3 + hstepB, voffB); PG8_STAGEA(PG8_SA(1, 0), a3, voffA);
;             PG8_WAIT_V(8); PG8_WAIT_L(0); PG8_BAR; PG8_MMA(1, 0, At, B0); PG8_MMA(1, 1, At, B1); PG8_BAR; PG8_SCHED;
;     ...
;         if constexpr (ALIGN_EPI) { if (wr == 0) PG8_BAR; }
	s_setprio 0
	s_add_i32 s95, 0, 0x18000
	s_add_i32 vcc_lo, 0, 0x1c000
	ds_read_b128 v[150:153], v222 offset:32768
	ds_read_b128 v[154:157], v222 offset:33792
	ds_read_b128 v[158:161], v222 offset:34816
	ds_read_b128 v[162:165], v222 offset:35840
	ds_read_b128 v[166:169], v222 offset:49152
	ds_read_b128 v[170:173], v222 offset:50176
	ds_read_b128 v[174:177], v222 offset:51200
	ds_read_b128 v[178:181], v222 offset:52224
	s_add_u32 s6, s42, 0x100000
	s_addc_u32 s7, s43, 0
	s_mov_b32 m0, s73
	ds_read_b128 v[182:185], v148 offset:32768
	ds_read_b128 v[186:189], v148 offset:33792
	ds_read_b128 v[190:193], v148 offset:34816
	ds_read_b128 v[194:197], v148 offset:35840
	ds_read_b128 v[198:201], v148 offset:36864
	ds_read_b128 v[202:205], v148 offset:37888
	ds_read_b128 v[206:209], v148 offset:38912
	ds_read_b128 v[210:213], v148 offset:39936
	global_load_lds_dwordx4 v136, s[6:7]
	s_mov_b32 m0, s82
	s_nop 0
	global_load_lds_dwordx4 v132, s[6:7]
	s_waitcnt vmcnt(8)
	s_waitcnt lgkmcnt(0)
	s_setprio 1
	s_barrier
	v_mfma_f32_16x16x32_bf16 v[126:129], v[150:153], v[182:185], v[126:129]
	v_mfma_f32_16x16x32_bf16 v[122:125], v[158:161], v[182:185], v[122:125]
	v_mfma_f32_16x16x32_bf16 v[110:113], v[150:153], v[190:193], v[110:113]
	v_mfma_f32_16x16x32_bf16 v[106:109], v[158:161], v[190:193], v[106:109]
	v_mfma_f32_16x16x32_bf16 v[94:97], v[150:153], v[198:201], v[94:97]
	v_mfma_f32_16x16x32_bf16 v[90:93], v[158:161], v[198:201], v[90:93]
	v_mfma_f32_16x16x32_bf16 v[78:81], v[150:153], v[206:209], v[78:81]
	v_mfma_f32_16x16x32_bf16 v[74:77], v[158:161], v[206:209], v[74:77]
	v_mfma_f32_16x16x32_bf16 v[126:129], v[154:157], v[186:189], v[126:129]
	v_mfma_f32_16x16x32_bf16 v[122:125], v[162:165], v[186:189], v[122:125]
	v_mfma_f32_16x16x32_bf16 v[110:113], v[154:157], v[194:197], v[110:113]
	v_mfma_f32_16x16x32_bf16 v[106:109], v[162:165], v[194:197], v[106:109]
	v_mfma_f32_16x16x32_bf16 v[94:97], v[154:157], v[202:205], v[94:97]
	v_mfma_f32_16x16x32_bf16 v[90:93], v[162:165], v[202:205], v[90:93]
	v_mfma_f32_16x16x32_bf16 v[78:81], v[154:157], v[210:213], v[78:81]
	v_mfma_f32_16x16x32_bf16 v[74:77], v[162:165], v[210:213], v[74:77]
	v_mfma_f32_16x16x32_bf16 v[118:121], v[166:169], v[182:185], v[118:121]
	v_mfma_f32_16x16x32_bf16 v[114:117], v[174:177], v[182:185], v[114:117]
	v_mfma_f32_16x16x32_bf16 v[102:105], v[166:169], v[190:193], v[102:105]
	v_mfma_f32_16x16x32_bf16 v[98:101], v[174:177], v[190:193], v[98:101]
	v_mfma_f32_16x16x32_bf16 v[86:89], v[166:169], v[198:201], v[86:89]
	v_mfma_f32_16x16x32_bf16 v[82:85], v[174:177], v[198:201], v[82:85]
	v_mfma_f32_16x16x32_bf16 v[70:73], v[166:169], v[206:209], v[70:73]
	v_mfma_f32_16x16x32_bf16 v[66:69], v[174:177], v[206:209], v[66:69]
	v_mfma_f32_16x16x32_bf16 v[118:121], v[170:173], v[186:189], v[118:121]
	v_mfma_f32_16x16x32_bf16 v[114:117], v[178:181], v[186:189], v[114:117]
	v_mfma_f32_16x16x32_bf16 v[102:105], v[170:173], v[194:197], v[102:105]
	v_mfma_f32_16x16x32_bf16 v[98:101], v[178:181], v[194:197], v[98:101]
	v_mfma_f32_16x16x32_bf16 v[86:89], v[170:173], v[202:205], v[86:89]
	v_mfma_f32_16x16x32_bf16 v[82:85], v[178:181], v[202:205], v[82:85]
	v_mfma_f32_16x16x32_bf16 v[70:73], v[170:173], v[210:213], v[70:73]
	v_mfma_f32_16x16x32_bf16 v[66:69], v[178:181], v[210:213], v[66:69]
	s_barrier
	s_setprio 0
	s_add_i32 s6, s95, s50
	s_mov_b32 m0, s6
	ds_read_b128 v[182:185], v148 offset:49152
	ds_read_b128 v[186:189], v148 offset:50176
	ds_read_b128 v[190:193], v148 offset:51200
	ds_read_b128 v[194:197], v148 offset:52224
	ds_read_b128 v[198:201], v148 offset:53248
	ds_read_b128 v[202:205], v148 offset:54272
	ds_read_b128 v[206:209], v148 offset:55296
	ds_read_b128 v[210:213], v148 offset:56320
	s_add_u32 s100, s16, 0x80
	s_addc_u32 s101, s17, 0
	global_load_lds_dwordx4 v134, s[100:101]
	s_add_i32 m0, s6, 0x2000
	s_add_u32 s6, s16, 0x100080
	s_addc_u32 s7, s17, 0
	s_add_i32 s16, vcc_lo, s50
	global_load_lds_dwordx4 v130, s[100:101]
	s_mov_b32 m0, s16
	s_nop 0
	global_load_lds_dwordx4 v134, s[6:7]
	s_add_i32 m0, s16, 0x2000
	s_nop 0
	global_load_lds_dwordx4 v130, s[6:7]
	s_mov_b32 m0, s83
	s_nop 0
	s_add_u32 s100, s42, 0x80
	s_addc_u32 s101, s43, 0
	global_load_lds_dwordx4 v136, s[100:101]
	s_mov_b32 m0, s90
	s_nop 0
	global_load_lds_dwordx4 v132, s[100:101]
	s_waitcnt vmcnt(8)
	s_waitcnt lgkmcnt(0)
	s_nop 0
	s_setprio 1
	s_barrier
	v_mfma_f32_16x16x32_bf16 v[62:65], v[150:153], v[182:185], v[62:65]
	v_mfma_f32_16x16x32_bf16 v[58:61], v[158:161], v[182:185], v[58:61]
	v_mfma_f32_16x16x32_bf16 v[46:49], v[150:153], v[190:193], v[46:49]
	v_mfma_f32_16x16x32_bf16 v[42:45], v[158:161], v[190:193], v[42:45]
	v_mfma_f32_16x16x32_bf16 v[30:33], v[150:153], v[198:201], v[30:33]
	v_mfma_f32_16x16x32_bf16 v[26:29], v[158:161], v[198:201], v[26:29]
	v_mfma_f32_16x16x32_bf16 v[12:15], v[150:153], v[206:209], v[12:15]
	v_mfma_f32_16x16x32_bf16 v[8:11], v[158:161], v[206:209], v[8:11]
	v_mfma_f32_16x16x32_bf16 v[62:65], v[154:157], v[186:189], v[62:65]
	v_mfma_f32_16x16x32_bf16 v[58:61], v[162:165], v[186:189], v[58:61]
	v_mfma_f32_16x16x32_bf16 v[46:49], v[154:157], v[194:197], v[46:49]
	v_mfma_f32_16x16x32_bf16 v[42:45], v[162:165], v[194:197], v[42:45]
	v_mfma_f32_16x16x32_bf16 v[30:33], v[154:157], v[202:205], v[30:33]
	v_mfma_f32_16x16x32_bf16 v[26:29], v[162:165], v[202:205], v[26:29]
	v_mfma_f32_16x16x32_bf16 v[12:15], v[154:157], v[210:213], v[12:15]
	v_mfma_f32_16x16x32_bf16 v[8:11], v[162:165], v[210:213], v[8:11]
	v_mfma_f32_16x16x32_bf16 v[54:57], v[166:169], v[182:185], v[54:57]
	v_mfma_f32_16x16x32_bf16 v[50:53], v[174:177], v[182:185], v[50:53]
	v_mfma_f32_16x16x32_bf16 v[38:41], v[166:169], v[190:193], v[38:41]
	v_mfma_f32_16x16x32_bf16 v[34:37], v[174:177], v[190:193], v[34:37]
	v_mfma_f32_16x16x32_bf16 v[22:25], v[166:169], v[198:201], v[22:25]
	v_mfma_f32_16x16x32_bf16 v[18:21], v[174:177], v[198:201], v[18:21]
	v_mfma_f32_16x16x32_bf16 v[4:7], v[166:169], v[206:209], v[4:7]
	v_mfma_f32_16x16x32_bf16 v[0:3], v[174:177], v[206:209], v[0:3]
	v_mfma_f32_16x16x32_bf16 v[54:57], v[170:173], v[186:189], v[54:57]
	v_mfma_f32_16x16x32_bf16 v[50:53], v[178:181], v[186:189], v[50:53]
	v_mfma_f32_16x16x32_bf16 v[38:41], v[170:173], v[194:197], v[38:41]
	v_mfma_f32_16x16x32_bf16 v[34:37], v[178:181], v[194:197], v[34:37]
	v_mfma_f32_16x16x32_bf16 v[22:25], v[170:173], v[202:205], v[22:25]
	v_mfma_f32_16x16x32_bf16 v[18:21], v[178:181], v[202:205], v[18:21]
	v_mfma_f32_16x16x32_bf16 v[4:7], v[170:173], v[210:213], v[4:7]
	v_mfma_f32_16x16x32_bf16 v[0:3], v[178:181], v[210:213], v[0:3]
	s_barrier
	s_setprio 0
	s_add_i32 s39, s39, 2
	s_add_u32 s40, s40, 0x100
	s_addc_u32 s41, s41, 0
	s_add_u32 s12, s12, 0x100
	s_addc_u32 s13, s13, 0
	s_cmp_gt_u32 s39, 61
	s_cbranch_scc0 .LBB0_712
	s_mov_b32 s98, 1
	s_and_b64 vcc, exec, s[18:19]
	s_cbranch_vccz .LBB0_715
	s_barrier

; #define PG8_STAGEA(bufoff, gbase, voff) PG8_STAGE_X(bufoff, gbase, voff, AUXA)
; #define PG8_STAGEB(bufoff, gbase, voff) PG8_STAGE_X(bufoff, gbase, voff, AUXB)
; #define PG8_WAIT_V(n) asm volatile("s_waitcnt vmcnt(" #n ")" ::: "memory")
; #define PG8_BAR __builtin_amdgcn_s_barrier()
;     ...
;     const int wid = __builtin_amdgcn_readfirstlane(tid >> 6), lane = tid & 63, wr = wid >> 2, wc = wid & 3, fr = lane & 15, fq = lane >> 4;
;     const int K = g.K, nt = K / BK;
;     unsigned voffA[2], voffB[2];
; #pragma unroll
;     for (int i = 0; i < 2; ++i) { int R, C; stage_rc(tid * 16 + i * 8192, R, C); const int Rb = Epi::PERM ? ((R & ~31) + perm32(R & 31)) : R;
;         voffA[i] = (unsigned)(R * (ABLK ? 64 : g.lda) + C) * 2u; voffB[i] = (unsigned)(Rb * (BBLK ? 64 : g.ldb) + C) * 2u; }
;     const size_t kstepA = ABLK ? 32768 : 128, kstepB = BBLK ? 32768 : 128;
;     const size_t hstepA = (size_t)HALF * (ABLK ? 64 : g.lda) * 2, hstepB = (size_t)HALF * (BBLK ? 64 : g.ldb) * 2;
;     const size_t tstepA = ABLK ? (size_t)(K / 64) * 32768 : (size_t)256 * g.lda * 2, tstepB = BBLK ? (size_t)(K / 64) * 32768 : (size_t)256 * g.ldb * 2;
;     const unsigned ldsw = (unsigned)wid * 1024u;
;     const int aoff = lds_byte(wr * 64 + fr, fq * 8), boff = lds_byte(wc * 32 + fr, fq * 8);
;     ...
;     if constexpr (SP2) {
;         PG8_STAGEB(PG8_SB(0, 0), cB, voffB); PG8_STAGEB(PG8_SB(0, 1), cB + hstepB, voffB); PG8_STAGEA(PG8_SA(0, 0), cA, voffA); PG8_STAGEA(PG8_SA(0, 1), cA + hstepA, voffA);
;         if (wr == 1) PG8_BAR;
;         PG8_WAIT_V(2); PG8_BAR;
;         PG8_STAGEB(PG8_SB(1, 0), cB + kstepB, voffB); PG8_STAGEA(PG8_SA(1, 0), cA + kstepA, voffA); PG8_STAGEB(PG8_SB(1, 1), cB + hstepB + kstepB, voffB);
;         PG8_WAIT_V(6); PG8_BAR;
.LBB0_842:
	s_mov_b32 s98, 0
	s_and_b32 s43, s4, 3
	s_lshl_b32 s8, s1, 13
	s_lshl_b32 s9, s43, 12
	s_add_u32 s4, s16, 0x8000
	s_addc_u32 s5, s17, 0
	v_mov_b32_e32 v139, v17
	s_add_i32 m0, s39, 0x18000
	v_lshl_add_u64 v[8:9], s[4:5], 0, v[16:17]
	s_waitcnt vmcnt(2)
	s_barrier
	global_load_lds_dwordx4 v[8:9], off
	v_lshl_add_u64 v[8:9], s[4:5], 0, v[138:139]
	v_readlane_b32 s4, v254, 27
	v_mov_b32_e32 v143, v17
	s_add_i32 m0, s39, 0x1a000
	v_readlane_b32 s5, v254, 28
	s_add_i32 s50, s39, 0x8000
	v_mov_b32_e32 v141, v17
	global_load_lds_dwordx4 v[8:9], off
	v_lshl_add_u64 v[8:9], s[4:5], 0, v[142:143]
	s_mov_b32 m0, s50
	s_add_i32 s51, s39, 0xa000
	global_load_lds_dwordx4 v[8:9], off
	v_lshl_add_u64 v[8:9], s[4:5], 0, v[140:141]
	s_add_u32 s4, s16, 0xc000
	s_mov_b32 m0, s51
	s_addc_u32 s5, s17, 0
	global_load_lds_dwordx4 v[8:9], off
	s_add_i32 m0, s39, 0x1c000
	v_lshl_add_u64 v[8:9], s[4:5], 0, v[16:17]
	global_load_lds_dwordx4 v[8:9], off
	v_lshl_add_u64 v[8:9], s[4:5], 0, v[138:139]
	s_add_i32 m0, s39, 0x1e000
	v_and_b32_e32 v7, 15, v1
	global_load_lds_dwordx4 v[8:9], off
	v_bfe_u32 v8, v1, 4, 2
	v_lshlrev_b32_e32 v10, 4, v8
	v_lshlrev_b32_e32 v1, 2, v1
	v_lshl_or_b32 v156, s1, 6, v7
	v_lshl_or_b32 v7, v7, 6, v10
	v_and_b32_e32 v1, 32, v1
	v_bitop3_b32 v10, v7, s8, v1 bitop3:0xde
	v_bitop3_b32 v157, v7, s9, v1 bitop3:0xde
	v_xor_b32_e32 v1, 16, v233
	v_cmp_lt_i32_e32 vcc, v1, v235
	s_cmpk_lt_u32 s0, 0x100
	v_readlane_b32 s0, v254, 19
	v_cndmask_b32_e32 v1, v233, v1, vcc
	v_lshlrev_b32_e32 v159, 2, v1
	v_xor_b32_e32 v1, 32, v233
	v_cmp_lt_i32_e32 vcc, v1, v235
	v_readlane_b32 s1, v254, 20
	s_mov_b32 s69, s0
	v_cndmask_b32_e32 v1, v233, v1, vcc
	v_lshlrev_b32_e32 v160, 2, v1
	v_lshlrev_b32_e32 v1, 10, v5
	v_and_b32_e32 v1, 0xfffff800, v1
	v_lshl_add_u32 v1, v4, 7, v1
	v_and_b32_e32 v4, 1, v5
	v_lshl_or_b32 v1, v4, 6, v1
	v_lshl_add_u32 v144, v6, 1, v1
	v_lshlrev_b32_e32 v1, 10, v0
	v_and_b32_e32 v1, 0xfffff800, v1
	v_readlane_b32 s0, v254, 17
	s_waitcnt vmcnt(6)
	v_lshl_add_u32 v1, v2, 7, v1
	v_and_b32_e32 v0, 1, v0
	v_readlane_b32 s1, v254, 18
	v_lshlrev_b32_e32 v9, 3, v8
	v_lshl_or_b32 v0, v0, 6, v1
	s_mov_b32 s72, s0
	v_readlane_b32 s0, v254, 25
	v_lshl_or_b32 v158, s43, 5, v9
	s_cselect_b64 s[8:9], -1, 0
	s_mov_b32 s68, 0
	v_cmp_eq_u32_e64 s[4:5], 0, v8
	v_mov_b32_e32 v145, v17
	v_lshl_add_u32 v146, v3, 1, v0
	v_mov_b32_e32 v147, v17
	v_add_u32_e32 v161, 0, v10
	v_readlane_b32 s1, v254, 26
	s_barrier
	s_branch .LBB0_845

; #define PG8_STAGEA(bufoff, gbase, voff) PG8_STAGE_X(bufoff, gbase, voff, AUXA)
; #define PG8_LDA(dst, b, h) do { _Pragma("unroll") for (int m = 0; m < 4; ++m) _Pragma("unroll") for (int k = 0; k < 2; ++k) dst[m][k] = *(const PG8_LAS bf16x8*)(lds + PG8_SA(b, h) + aoff + m * 2048 + k * 1024); } while (0)
; #define PG8_LDB(dst, b, h) do { _Pragma("unroll") for (int n = 0; n < 2; ++n) _Pragma("unroll") for (int k = 0; k < 2; ++k) dst[n][k] = *(const PG8_LAS bf16x8*)(lds + PG8_SB(b, h) + boff + n * 2048 + k * 1024); } while (0)
; #define PG8_MMA(ai, bj, At, Bt) do { if (GEMM_PRIO_MODE == 0) __builtin_amdgcn_s_setprio(1); PG8_MMA_LOOPS \
;         acc[ai][bj][m][n] = __builtin_amdgcn_mfma_f32_16x16x32_bf16(Bt[n][k], At[m][k], acc[ai][bj][m][n], 0, 0, 0); if (GEMM_PRIO_MODE == 0) __builtin_amdgcn_s_setprio(0); } while (0)
; #define PG8_WAIT_VR(n, nr, flag) asm volatile("s_cmp_eq_u32 %0, 0\n\ts_cbranch_scc1 .Lpg8s%=\n\ts_waitcnt vmcnt(" #nr ")\n\ts_branch .Lpg8d%=\n.Lpg8s%=:\n\ts_waitcnt vmcnt(" #n ")\n.Lpg8d%=:" :: "s"(flag) : "memory", "scc")
; #define PG8_WAIT_L(n) asm volatile("s_waitcnt lgkmcnt(" #n ")" ::: "memory")
; #define PG8_BAR __builtin_amdgcn_s_barrier()
; #define PG8_SCHED __builtin_amdgcn_sched_barrier(0)
;     ...
;         for (int t = t0; t < nt; t += 2) {
;             const bool last = (t == nt - 2);
;             const char* a1 = cA + (size_t)(t + 1) * kstepA;
;             const char* a2 = last ? nA : cA + (size_t)(t + 2) * kstepA; const char* b2 = last ? nB : cB + (size_t)(t + 2) * kstepB;
;             const char* a3 = a2 + kstepA; const char* b3 = b2 + kstepB;
;             if (last && has_next) S.a_ready(nxt);
;             if constexpr (SP2) {
;             PG8_LDB(B0, 0, 0); PG8_LDB(B1, 0, 1); PG8_SCHED; PG8_LDA(At, 0, 0); PG8_STAGEA(PG8_SA(1, 1), a1 + hstepA, voffA);
;     ...
;             const int relax = __builtin_amdgcn_readfirstlane((t == 0 && ui > 0) ? 1 : 0);
;             PG8_WAIT_VR(8, 24, relax); PG8_WAIT_L(0); PG8_BAR; PG8_MMA(0, 0, At, B0); PG8_MMA(0, 1, At, B1); PG8_BAR; PG8_SCHED;
.LBB0_847:
	s_ashr_i32 s11, s10, 31
	s_lshl_b64 s[18:19], s[10:11], 23
	s_add_u32 s18, s62, s18
	s_addc_u32 s19, s63, s19
	s_and_b64 s[22:23], s[20:21], exec
	s_cselect_b32 s11, s19, s1
	s_cselect_b32 s73, s18, s0
	s_ashr_i32 s15, s14, 31
	s_lshl_b64 s[22:23], s[14:15], 23
	s_add_u32 s22, s12, s22
	s_addc_u32 s23, s13, s23
	s_and_b64 s[24:25], s[20:21], exec
	s_cselect_b32 s15, s23, s17
	s_cselect_b32 s78, s22, s16
	s_add_u32 s24, s0, 0xc000
	s_addc_u32 s25, s1, 0
	s_add_u32 s0, s16, 0x10000
	s_addc_u32 s1, s17, 0
	s_mov_b32 s82, -2
	s_waitcnt lgkmcnt(0)
	s_add_u32 s16, s24, 0x4000
	s_addc_u32 s17, s25, 0
	s_cmpk_eq_i32 s82, 0xfc
	s_cselect_b32 s36, s73, s16
	s_cselect_b32 s37, s11, s17
	s_cselect_b32 s16, s78, s0
	s_cselect_b32 s17, s15, s1
	s_add_u32 s26, s36, 0x8000
	s_addc_u32 s27, s37, 0
	s_add_i32 s83, 0, 0x10000
	s_add_i32 s94, 0, 0x14000
	v_add_u32_e32 v152, s83, v157
	v_add_u32_e32 v174, s94, v157
	ds_read_b128 v[130:133], v152
	ds_read_b128 v[134:137], v152 offset:1024
	ds_read_b128 v[148:151], v152 offset:2048
	ds_read_b128 v[152:155], v152 offset:3072
	ds_read_b128 v[162:165], v174
	ds_read_b128 v[166:169], v174 offset:1024
	ds_read_b128 v[170:173], v174 offset:2048
	ds_read_b128 v[174:177], v174 offset:3072
	v_lshl_add_u64 v[210:211], s[24:25], 0, v[144:145]
	s_add_i32 m0, s39, 0xc000
	ds_read_b128 v[178:181], v161
	ds_read_b128 v[182:185], v161 offset:1024
	ds_read_b128 v[186:189], v161 offset:2048
	ds_read_b128 v[190:193], v161 offset:3072
	ds_read_b128 v[194:197], v161 offset:4096
	ds_read_b128 v[198:201], v161 offset:5120
	ds_read_b128 v[202:205], v161 offset:6144
	ds_read_b128 v[206:209], v161 offset:7168
	global_load_lds_dwordx4 v[210:211], off
	v_lshl_add_u64 v[210:211], s[24:25], 0, v[146:147]
	s_add_i32 m0, s39, 0xe000
	s_nop 0
	global_load_lds_dwordx4 v[210:211], off
	s_cmp_eq_u32 s98, 0
	s_cbranch_scc1 .Lrelax_s_lbb0_848_0
	s_waitcnt vmcnt(24)
	s_branch .Lrelax_d_lbb0_848_0

; #define PG8_STAGEA(bufoff, gbase, voff) PG8_STAGE_X(bufoff, gbase, voff, AUXA)
; #define PG8_STAGEB(bufoff, gbase, voff) PG8_STAGE_X(bufoff, gbase, voff, AUXB)
; #define PG8_LDA(dst, b, h) do { _Pragma("unroll") for (int m = 0; m < 4; ++m) _Pragma("unroll") for (int k = 0; k < 2; ++k) dst[m][k] = *(const PG8_LAS bf16x8*)(lds + PG8_SA(b, h) + aoff + m * 2048 + k * 1024); } while (0)
; #define PG8_MMA(ai, bj, At, Bt) do { if (GEMM_PRIO_MODE == 0) __builtin_amdgcn_s_setprio(1); PG8_MMA_LOOPS \
;         acc[ai][bj][m][n] = __builtin_amdgcn_mfma_f32_16x16x32_bf16(Bt[n][k], At[m][k], acc[ai][bj][m][n], 0, 0, 0); if (GEMM_PRIO_MODE == 0) __builtin_amdgcn_s_setprio(0); } while (0)
; #define PG8_WAIT_V(n) asm volatile("s_waitcnt vmcnt(" #n ")" ::: "memory")
; #define PG8_WAIT_VR(n, nr, flag) asm volatile("s_cmp_eq_u32 %0, 0\n\ts_cbranch_scc1 .Lpg8s%=\n\ts_waitcnt vmcnt(" #nr ")\n\ts_branch .Lpg8d%=\n.Lpg8s%=:\n\ts_waitcnt vmcnt(" #n ")\n.Lpg8d%=:" :: "s"(flag) : "memory", "scc")
; #define PG8_WAIT_L(n) asm volatile("s_waitcnt lgkmcnt(" #n ")" ::: "memory")
; #define PG8_BAR __builtin_amdgcn_s_barrier()
; #define PG8_SCHED __builtin_amdgcn_sched_barrier(0)
;     ...
;             PG8_WAIT_VR(8, 24, relax); PG8_WAIT_L(0); PG8_BAR; PG8_MMA(0, 0, At, B0); PG8_MMA(0, 1, At, B1); PG8_BAR; PG8_SCHED;
;     ...
;             PG8_WAIT_V(8); PG8_WAIT_L(0); PG8_BAR; PG8_MMA(0, 0, At, B0); PG8_MMA(0, 1, At, B1); PG8_BAR; PG8_SCHED;
;     ...
;             PG8_LDA(At, 0, 1); PG8_STAGEB(PG8_SB(0, 0), b2, voffB); PG8_STAGEB(PG8_SB(0, 1), b2 + hstepB, voffB); PG8_STAGEA(PG8_SA(0, 0), a2, voffA);
;     ...
;             PG8_WAIT_VR(8, 24, relax); PG8_WAIT_L(0); PG8_BAR; PG8_MMA(1, 0, At, B0); PG8_MMA(1, 1, At, B1); PG8_BAR; PG8_SCHED;
.Lrelax_d_lbb0_848_0:
	s_waitcnt lgkmcnt(0)
	s_setprio 1
	s_barrier
	v_mfma_f32_16x16x32_bf16 v[126:129], v[130:133], v[178:181], 0
	v_mfma_f32_16x16x32_bf16 v[122:125], v[148:151], v[178:181], 0
	v_mfma_f32_16x16x32_bf16 v[110:113], v[130:133], v[186:189], 0
	v_mfma_f32_16x16x32_bf16 v[106:109], v[148:151], v[186:189], 0
	v_mfma_f32_16x16x32_bf16 v[94:97], v[130:133], v[194:197], 0
	v_mfma_f32_16x16x32_bf16 v[90:93], v[148:151], v[194:197], 0
	v_mfma_f32_16x16x32_bf16 v[78:81], v[130:133], v[202:205], 0
	v_mfma_f32_16x16x32_bf16 v[74:77], v[148:151], v[202:205], 0
	v_mfma_f32_16x16x32_bf16 v[126:129], v[134:137], v[182:185], v[126:129]
	v_mfma_f32_16x16x32_bf16 v[122:125], v[152:155], v[182:185], v[122:125]
	v_mfma_f32_16x16x32_bf16 v[110:113], v[134:137], v[190:193], v[110:113]
	v_mfma_f32_16x16x32_bf16 v[106:109], v[152:155], v[190:193], v[106:109]
	v_mfma_f32_16x16x32_bf16 v[94:97], v[134:137], v[198:201], v[94:97]
	v_mfma_f32_16x16x32_bf16 v[90:93], v[152:155], v[198:201], v[90:93]
	v_mfma_f32_16x16x32_bf16 v[78:81], v[134:137], v[206:209], v[78:81]
	v_mfma_f32_16x16x32_bf16 v[74:77], v[152:155], v[206:209], v[74:77]
	v_mfma_f32_16x16x32_bf16 v[118:121], v[162:165], v[178:181], 0
	v_mfma_f32_16x16x32_bf16 v[114:117], v[170:173], v[178:181], 0
	v_mfma_f32_16x16x32_bf16 v[102:105], v[162:165], v[186:189], 0
	v_mfma_f32_16x16x32_bf16 v[98:101], v[170:173], v[186:189], 0
	v_mfma_f32_16x16x32_bf16 v[86:89], v[162:165], v[194:197], 0
	v_mfma_f32_16x16x32_bf16 v[82:85], v[170:173], v[194:197], 0
	v_mfma_f32_16x16x32_bf16 v[70:73], v[162:165], v[202:205], 0
	v_mfma_f32_16x16x32_bf16 v[66:69], v[170:173], v[202:205], 0
	v_mfma_f32_16x16x32_bf16 v[118:121], v[166:169], v[182:185], v[118:121]
	v_mfma_f32_16x16x32_bf16 v[114:117], v[174:177], v[182:185], v[114:117]
	v_mfma_f32_16x16x32_bf16 v[102:105], v[166:169], v[190:193], v[102:105]
	v_mfma_f32_16x16x32_bf16 v[98:101], v[174:177], v[190:193], v[98:101]
	v_mfma_f32_16x16x32_bf16 v[86:89], v[166:169], v[198:201], v[86:89]
	v_mfma_f32_16x16x32_bf16 v[82:85], v[174:177], v[198:201], v[82:85]
	v_mfma_f32_16x16x32_bf16 v[70:73], v[166:169], v[206:209], v[70:73]
	v_mfma_f32_16x16x32_bf16 v[66:69], v[174:177], v[206:209], v[66:69]
	s_barrier
	s_setprio 0
	s_add_i32 s83, s83, s38
	v_lshl_add_u64 v[210:211], s[16:17], 0, v[16:17]
	s_mov_b32 m0, s83
	ds_read_b128 v[178:181], v161 offset:16384
	ds_read_b128 v[182:185], v161 offset:17408
	ds_read_b128 v[186:189], v161 offset:18432
	ds_read_b128 v[190:193], v161 offset:19456
	ds_read_b128 v[194:197], v161 offset:20480
	ds_read_b128 v[198:201], v161 offset:21504
	ds_read_b128 v[202:205], v161 offset:22528
	ds_read_b128 v[206:209], v161 offset:23552
	global_load_lds_dwordx4 v[210:211], off
	s_add_i32 m0, s83, 0x2000
	s_add_u32 s90, s16, 0x4000
	v_lshl_add_u64 v[210:211], s[16:17], 0, v[138:139]
	s_addc_u32 s91, s17, 0
	s_add_i32 s83, s94, s38
	global_load_lds_dwordx4 v[210:211], off
	v_lshl_add_u64 v[210:211], s[90:91], 0, v[16:17]
	s_mov_b32 m0, s83
	s_nop 0
	global_load_lds_dwordx4 v[210:211], off
	v_lshl_add_u64 v[210:211], s[90:91], 0, v[138:139]
	s_add_i32 m0, s83, 0x2000
	s_nop 0
	global_load_lds_dwordx4 v[210:211], off
	v_lshl_add_u64 v[210:211], s[36:37], 0, v[142:143]
	s_mov_b32 m0, s39
	s_nop 0
	global_load_lds_dwordx4 v[210:211], off
	v_lshl_add_u64 v[210:211], s[36:37], 0, v[140:141]
	s_mov_b32 m0, s40
	s_nop 0
	global_load_lds_dwordx4 v[210:211], off
	s_cmp_eq_u32 s98, 0
	s_cbranch_scc1 .Lrelax_s_lbb0_848_1
	s_waitcnt vmcnt(24)
	s_branch .Lrelax_d_lbb0_848_1

; #define PG8_STAGEA(bufoff, gbase, voff) PG8_STAGE_X(bufoff, gbase, voff, AUXA)
; #define PG8_LDA(dst, b, h) do { _Pragma("unroll") for (int m = 0; m < 4; ++m) _Pragma("unroll") for (int k = 0; k < 2; ++k) dst[m][k] = *(const PG8_LAS bf16x8*)(lds + PG8_SA(b, h) + aoff + m * 2048 + k * 1024); } while (0)
; #define PG8_LDB(dst, b, h) do { _Pragma("unroll") for (int n = 0; n < 2; ++n) _Pragma("unroll") for (int k = 0; k < 2; ++k) dst[n][k] = *(const PG8_LAS bf16x8*)(lds + PG8_SB(b, h) + boff + n * 2048 + k * 1024); } while (0)
; #define PG8_MMA(ai, bj, At, Bt) do { if (GEMM_PRIO_MODE == 0) __builtin_amdgcn_s_setprio(1); PG8_MMA_LOOPS \
;         acc[ai][bj][m][n] = __builtin_amdgcn_mfma_f32_16x16x32_bf16(Bt[n][k], At[m][k], acc[ai][bj][m][n], 0, 0, 0); if (GEMM_PRIO_MODE == 0) __builtin_amdgcn_s_setprio(0); } while (0)
; #define PG8_WAIT_V(n) asm volatile("s_waitcnt vmcnt(" #n ")" ::: "memory")
; #define PG8_WAIT_VR(n, nr, flag) asm volatile("s_cmp_eq_u32 %0, 0\n\ts_cbranch_scc1 .Lpg8s%=\n\ts_waitcnt vmcnt(" #nr ")\n\ts_branch .Lpg8d%=\n.Lpg8s%=:\n\ts_waitcnt vmcnt(" #n ")\n.Lpg8d%=:" :: "s"(flag) : "memory", "scc")
; #define PG8_WAIT_L(n) asm volatile("s_waitcnt lgkmcnt(" #n ")" ::: "memory")
; #define PG8_BAR __builtin_amdgcn_s_barrier()
; #define PG8_SCHED __builtin_amdgcn_sched_barrier(0)
;     ...
;             PG8_WAIT_VR(8, 24, relax); PG8_WAIT_L(0); PG8_BAR; PG8_MMA(1, 0, At, B0); PG8_MMA(1, 1, At, B1); PG8_BAR; PG8_SCHED;
;     ...
;             PG8_WAIT_V(8); PG8_WAIT_L(0); PG8_BAR; PG8_MMA(1, 0, At, B0); PG8_MMA(1, 1, At, B1); PG8_BAR; PG8_SCHED;
;     ...
;             PG8_LDB(B0, 1, 0); PG8_LDB(B1, 1, 1); PG8_SCHED; PG8_LDA(At, 1, 0); PG8_STAGEA(PG8_SA(0, 1), a2 + hstepA, voffA);
;             PG8_WAIT_V(8); PG8_WAIT_L(0); PG8_BAR; PG8_MMA(0, 0, At, B0); PG8_MMA(0, 1, At, B1); PG8_BAR; PG8_SCHED;
.Lrelax_d_lbb0_848_1:
	s_waitcnt lgkmcnt(0)
	s_nop 0
	s_setprio 1
	s_barrier
	v_mfma_f32_16x16x32_bf16 v[62:65], v[130:133], v[178:181], 0
	v_mfma_f32_16x16x32_bf16 v[58:61], v[148:151], v[178:181], 0
	v_mfma_f32_16x16x32_bf16 v[46:49], v[130:133], v[186:189], 0
	v_mfma_f32_16x16x32_bf16 v[42:45], v[148:151], v[186:189], 0
	v_mfma_f32_16x16x32_bf16 v[30:33], v[130:133], v[194:197], 0
	v_mfma_f32_16x16x32_bf16 v[26:29], v[148:151], v[194:197], 0
	v_mfma_f32_16x16x32_bf16 v[12:15], v[130:133], v[202:205], 0
	v_mfma_f32_16x16x32_bf16 v[8:11], v[148:151], v[202:205], 0
	v_mfma_f32_16x16x32_bf16 v[62:65], v[134:137], v[182:185], v[62:65]
	v_mfma_f32_16x16x32_bf16 v[58:61], v[152:155], v[182:185], v[58:61]
	v_mfma_f32_16x16x32_bf16 v[46:49], v[134:137], v[190:193], v[46:49]
	v_mfma_f32_16x16x32_bf16 v[42:45], v[152:155], v[190:193], v[42:45]
	v_mfma_f32_16x16x32_bf16 v[30:33], v[134:137], v[198:201], v[30:33]
	v_mfma_f32_16x16x32_bf16 v[26:29], v[152:155], v[198:201], v[26:29]
	v_mfma_f32_16x16x32_bf16 v[12:15], v[134:137], v[206:209], v[12:15]
	v_mfma_f32_16x16x32_bf16 v[8:11], v[152:155], v[206:209], v[8:11]
	v_mfma_f32_16x16x32_bf16 v[54:57], v[162:165], v[178:181], 0
	v_mfma_f32_16x16x32_bf16 v[50:53], v[170:173], v[178:181], 0
	v_mfma_f32_16x16x32_bf16 v[38:41], v[162:165], v[186:189], 0
	v_mfma_f32_16x16x32_bf16 v[34:37], v[170:173], v[186:189], 0
	v_mfma_f32_16x16x32_bf16 v[22:25], v[162:165], v[194:197], 0
	v_mfma_f32_16x16x32_bf16 v[18:21], v[170:173], v[194:197], 0
	v_mfma_f32_16x16x32_bf16 v[4:7], v[162:165], v[202:205], 0
	v_mfma_f32_16x16x32_bf16 v[0:3], v[170:173], v[202:205], 0
	v_mfma_f32_16x16x32_bf16 v[54:57], v[166:169], v[182:185], v[54:57]
	v_mfma_f32_16x16x32_bf16 v[50:53], v[174:177], v[182:185], v[50:53]
	v_mfma_f32_16x16x32_bf16 v[38:41], v[166:169], v[190:193], v[38:41]
	v_mfma_f32_16x16x32_bf16 v[34:37], v[174:177], v[190:193], v[34:37]
	v_mfma_f32_16x16x32_bf16 v[22:25], v[166:169], v[198:201], v[22:25]
	v_mfma_f32_16x16x32_bf16 v[18:21], v[174:177], v[198:201], v[18:21]
	v_mfma_f32_16x16x32_bf16 v[4:7], v[166:169], v[206:209], v[4:7]
	v_mfma_f32_16x16x32_bf16 v[0:3], v[174:177], v[206:209], v[0:3]
	s_barrier
	s_setprio 0
	s_add_i32 s83, 0, 0x18000
	s_add_i32 s90, 0, 0x1c000
	v_add_u32_e32 v152, s83, v157
	v_add_u32_e32 v174, s90, v157
	ds_read_b128 v[130:133], v152
	ds_read_b128 v[134:137], v152 offset:1024
	ds_read_b128 v[148:151], v152 offset:2048
	ds_read_b128 v[152:155], v152 offset:3072
	ds_read_b128 v[162:165], v174
	ds_read_b128 v[166:169], v174 offset:1024
	ds_read_b128 v[170:173], v174 offset:2048
	ds_read_b128 v[174:177], v174 offset:3072
	s_add_u32 s36, s36, 0x4000
	s_addc_u32 s37, s37, 0
	s_mov_b32 m0, s41
	v_lshl_add_u64 v[210:211], s[36:37], 0, v[142:143]
	ds_read_b128 v[178:181], v161 offset:32768
	ds_read_b128 v[182:185], v161 offset:33792
	ds_read_b128 v[186:189], v161 offset:34816
	ds_read_b128 v[190:193], v161 offset:35840
	ds_read_b128 v[194:197], v161 offset:36864
	ds_read_b128 v[198:201], v161 offset:37888
	ds_read_b128 v[202:205], v161 offset:38912
	ds_read_b128 v[206:209], v161 offset:39936
	global_load_lds_dwordx4 v[210:211], off
	v_lshl_add_u64 v[210:211], s[36:37], 0, v[140:141]
	s_mov_b32 m0, s42
	s_nop 0
	global_load_lds_dwordx4 v[210:211], off
	s_waitcnt vmcnt(8)
	s_waitcnt lgkmcnt(0)
	s_setprio 1
	s_barrier
	v_mfma_f32_16x16x32_bf16 v[126:129], v[130:133], v[178:181], v[126:129]
	v_mfma_f32_16x16x32_bf16 v[122:125], v[148:151], v[178:181], v[122:125]
	v_mfma_f32_16x16x32_bf16 v[110:113], v[130:133], v[186:189], v[110:113]
	v_mfma_f32_16x16x32_bf16 v[106:109], v[148:151], v[186:189], v[106:109]
	v_mfma_f32_16x16x32_bf16 v[94:97], v[130:133], v[194:197], v[94:97]
	v_mfma_f32_16x16x32_bf16 v[90:93], v[148:151], v[194:197], v[90:93]
	v_mfma_f32_16x16x32_bf16 v[78:81], v[130:133], v[202:205], v[78:81]
	v_mfma_f32_16x16x32_bf16 v[74:77], v[148:151], v[202:205], v[74:77]
	v_mfma_f32_16x16x32_bf16 v[126:129], v[134:137], v[182:185], v[126:129]
	v_mfma_f32_16x16x32_bf16 v[122:125], v[152:155], v[182:185], v[122:125]
	v_mfma_f32_16x16x32_bf16 v[110:113], v[134:137], v[190:193], v[110:113]
	v_mfma_f32_16x16x32_bf16 v[106:109], v[152:155], v[190:193], v[106:109]
	v_mfma_f32_16x16x32_bf16 v[94:97], v[134:137], v[198:201], v[94:97]
	v_mfma_f32_16x16x32_bf16 v[90:93], v[152:155], v[198:201], v[90:93]
	v_mfma_f32_16x16x32_bf16 v[78:81], v[134:137], v[206:209], v[78:81]
	v_mfma_f32_16x16x32_bf16 v[74:77], v[152:155], v[206:209], v[74:77]
	v_mfma_f32_16x16x32_bf16 v[118:121], v[162:165], v[178:181], v[118:121]
	v_mfma_f32_16x16x32_bf16 v[114:117], v[170:173], v[178:181], v[114:117]
	v_mfma_f32_16x16x32_bf16 v[102:105], v[162:165], v[186:189], v[102:105]
	v_mfma_f32_16x16x32_bf16 v[98:101], v[170:173], v[186:189], v[98:101]
	v_mfma_f32_16x16x32_bf16 v[86:89], v[162:165], v[194:197], v[86:89]
	v_mfma_f32_16x16x32_bf16 v[82:85], v[170:173], v[194:197], v[82:85]
	v_mfma_f32_16x16x32_bf16 v[70:73], v[162:165], v[202:205], v[70:73]
	v_mfma_f32_16x16x32_bf16 v[66:69], v[170:173], v[202:205], v[66:69]
	v_mfma_f32_16x16x32_bf16 v[118:121], v[166:169], v[182:185], v[118:121]
	v_mfma_f32_16x16x32_bf16 v[114:117], v[174:177], v[182:185], v[114:117]
	v_mfma_f32_16x16x32_bf16 v[102:105], v[166:169], v[190:193], v[102:105]
	v_mfma_f32_16x16x32_bf16 v[98:101], v[174:177], v[190:193], v[98:101]
	v_mfma_f32_16x16x32_bf16 v[86:89], v[166:169], v[198:201], v[86:89]
	v_mfma_f32_16x16x32_bf16 v[82:85], v[174:177], v[198:201], v[82:85]
	v_mfma_f32_16x16x32_bf16 v[70:73], v[166:169], v[206:209], v[70:73]
	v_mfma_f32_16x16x32_bf16 v[66:69], v[174:177], v[206:209], v[66:69]
	s_barrier
; #define PG8_STAGEA(bufoff, gbase, voff) PG8_STAGE_X(bufoff, gbase, voff, AUXA)
; #define PG8_STAGEB(bufoff, gbase, voff) PG8_STAGE_X(bufoff, gbase, voff, AUXB)
; #define PG8_LDA(dst, b, h) do { _Pragma("unroll") for (int m = 0; m < 4; ++m) _Pragma("unroll") for (int k = 0; k < 2; ++k) dst[m][k] = *(const PG8_LAS bf16x8*)(lds + PG8_SA(b, h) + aoff + m * 2048 + k * 1024); } while (0)
; #define PG8_WAIT_V(n) asm volatile("s_waitcnt vmcnt(" #n ")" ::: "memory")
; #define PG8_WAIT_L(n) asm volatile("s_waitcnt lgkmcnt(" #n ")" ::: "memory")
;     ...
;         for (int t = t0; t < nt; t += 2) {
;             const bool last = (t == nt - 2);
;             const char* a1 = cA + (size_t)(t + 1) * kstepA;
;             const char* a2 = last ? nA : cA + (size_t)(t + 2) * kstepA; const char* b2 = last ? nB : cB + (size_t)(t + 2) * kstepB;
;             const char* a3 = a2 + kstepA; const char* b3 = b2 + kstepB;
;             if (last && has_next) S.a_ready(nxt);
;             if constexpr (SP2) {
;             PG8_LDB(B0, 0, 0); PG8_LDB(B1, 0, 1); PG8_SCHED; PG8_LDA(At, 0, 0); PG8_STAGEA(PG8_SA(1, 1), a1 + hstepA, voffA);
;     ...
;             const int relax = __builtin_amdgcn_readfirstlane((t == 0 && ui > 0) ? 1 : 0);
;             PG8_WAIT_VR(8, 24, relax); PG8_WAIT_L(0); PG8_BAR; PG8_MMA(0, 0, At, B0); PG8_MMA(0, 1, At, B1); PG8_BAR; PG8_SCHED;
;     ...
;             PG8_WAIT_V(8); PG8_WAIT_L(0); PG8_BAR; PG8_MMA(0, 0, At, B0); PG8_MMA(0, 1, At, B1); PG8_BAR; PG8_SCHED;
;     ...
;             PG8_LDA(At, 0, 1); PG8_STAGEB(PG8_SB(0, 0), b2, voffB); PG8_STAGEB(PG8_SB(0, 1), b2 + hstepB, voffB); PG8_STAGEA(PG8_SA(0, 0), a2, voffA);
;     ...
;             PG8_WAIT_VR(8, 24, relax); PG8_WAIT_L(0); PG8_BAR; PG8_MMA(1, 0, At, B0); PG8_MMA(1, 1, At, B1); PG8_BAR; PG8_SCHED;
;     ...
;             PG8_WAIT_V(8); PG8_WAIT_L(0); PG8_BAR; PG8_MMA(1, 0, At, B0); PG8_MMA(1, 1, At, B1); PG8_BAR; PG8_SCHED;
;     ...
;             PG8_LDB(B0, 1, 0); PG8_LDB(B1, 1, 1); PG8_SCHED; PG8_LDA(At, 1, 0); PG8_STAGEA(PG8_SA(0, 1), a2 + hstepA, voffA);
;             PG8_WAIT_V(8); PG8_WAIT_L(0); PG8_BAR; PG8_MMA(0, 0, At, B0); PG8_MMA(0, 1, At, B1); PG8_BAR; PG8_SCHED;
;             PG8_LDA(At, 1, 1); PG8_STAGEB(PG8_SB(1, 0), b3, voffB); PG8_STAGEB(PG8_SB(1, 1), b3 + hstepB, voffB); PG8_STAGEA(PG8_SA(1, 0), a3, voffA);
;             PG8_WAIT_V(8); PG8_WAIT_L(0); PG8_BAR; PG8_MMA(1, 0, At, B0); PG8_MMA(1, 1, At, B1); PG8_BAR; PG8_SCHED;
	s_setprio 0
	s_add_u32 s36, s16, 0x8000
	s_addc_u32 s37, s17, 0
	s_add_i32 s83, s83, s38
	v_lshl_add_u64 v[210:211], s[36:37], 0, v[16:17]
	s_mov_b32 m0, s83
	ds_read_b128 v[178:181], v161 offset:49152
	ds_read_b128 v[182:185], v161 offset:50176
	ds_read_b128 v[186:189], v161 offset:51200
	ds_read_b128 v[190:193], v161 offset:52224
	ds_read_b128 v[194:197], v161 offset:53248
	ds_read_b128 v[198:201], v161 offset:54272
	ds_read_b128 v[202:205], v161 offset:55296
	ds_read_b128 v[206:209], v161 offset:56320
	global_load_lds_dwordx4 v[210:211], off
	s_add_i32 m0, s83, 0x2000
	s_add_u32 s16, s16, 0xc000
	v_lshl_add_u64 v[210:211], s[36:37], 0, v[138:139]
	s_addc_u32 s17, s17, 0
	s_add_i32 s36, s90, s38
	global_load_lds_dwordx4 v[210:211], off
	v_lshl_add_u64 v[210:211], s[16:17], 0, v[16:17]
	s_mov_b32 m0, s36
	s_nop 0
	global_load_lds_dwordx4 v[210:211], off
	v_lshl_add_u64 v[210:211], s[16:17], 0, v[138:139]
	s_add_i32 m0, s36, 0x2000
	s_nop 0
	global_load_lds_dwordx4 v[210:211], off
	v_lshl_add_u64 v[210:211], s[26:27], 0, v[142:143]
	s_mov_b32 m0, s50
	s_nop 0
	global_load_lds_dwordx4 v[210:211], off
	v_lshl_add_u64 v[210:211], s[26:27], 0, v[140:141]
	s_mov_b32 m0, s51
	s_nop 0
	global_load_lds_dwordx4 v[210:211], off
	s_waitcnt vmcnt(8)
	s_waitcnt lgkmcnt(0)
	s_setprio 1
	s_barrier
	v_mfma_f32_16x16x32_bf16 v[62:65], v[130:133], v[178:181], v[62:65]
	v_mfma_f32_16x16x32_bf16 v[58:61], v[148:151], v[178:181], v[58:61]
	v_mfma_f32_16x16x32_bf16 v[46:49], v[130:133], v[186:189], v[46:49]
	v_mfma_f32_16x16x32_bf16 v[42:45], v[148:151], v[186:189], v[42:45]
	v_mfma_f32_16x16x32_bf16 v[30:33], v[130:133], v[194:197], v[30:33]
	v_mfma_f32_16x16x32_bf16 v[26:29], v[148:151], v[194:197], v[26:29]
	v_mfma_f32_16x16x32_bf16 v[12:15], v[130:133], v[202:205], v[12:15]
	v_mfma_f32_16x16x32_bf16 v[8:11], v[148:151], v[202:205], v[8:11]
	v_mfma_f32_16x16x32_bf16 v[62:65], v[134:137], v[182:185], v[62:65]
	v_mfma_f32_16x16x32_bf16 v[58:61], v[152:155], v[182:185], v[58:61]
	v_mfma_f32_16x16x32_bf16 v[46:49], v[134:137], v[190:193], v[46:49]
	v_mfma_f32_16x16x32_bf16 v[42:45], v[152:155], v[190:193], v[42:45]
	v_mfma_f32_16x16x32_bf16 v[30:33], v[134:137], v[198:201], v[30:33]
	v_mfma_f32_16x16x32_bf16 v[26:29], v[152:155], v[198:201], v[26:29]
	v_mfma_f32_16x16x32_bf16 v[12:15], v[134:137], v[206:209], v[12:15]
	v_mfma_f32_16x16x32_bf16 v[8:11], v[152:155], v[206:209], v[8:11]
	v_mfma_f32_16x16x32_bf16 v[54:57], v[162:165], v[178:181], v[54:57]
	v_mfma_f32_16x16x32_bf16 v[50:53], v[170:173], v[178:181], v[50:53]
	v_mfma_f32_16x16x32_bf16 v[38:41], v[162:165], v[186:189], v[38:41]
	v_mfma_f32_16x16x32_bf16 v[34:37], v[170:173], v[186:189], v[34:37]
	v_mfma_f32_16x16x32_bf16 v[22:25], v[162:165], v[194:197], v[22:25]
	v_mfma_f32_16x16x32_bf16 v[18:21], v[170:173], v[194:197], v[18:21]
	v_mfma_f32_16x16x32_bf16 v[4:7], v[162:165], v[202:205], v[4:7]
	v_mfma_f32_16x16x32_bf16 v[0:3], v[170:173], v[202:205], v[0:3]
	v_mfma_f32_16x16x32_bf16 v[54:57], v[166:169], v[182:185], v[54:57]
	v_mfma_f32_16x16x32_bf16 v[50:53], v[174:177], v[182:185], v[50:53]
	v_mfma_f32_16x16x32_bf16 v[38:41], v[166:169], v[190:193], v[38:41]
	v_mfma_f32_16x16x32_bf16 v[34:37], v[174:177], v[190:193], v[34:37]
	v_mfma_f32_16x16x32_bf16 v[22:25], v[166:169], v[198:201], v[22:25]
	v_mfma_f32_16x16x32_bf16 v[18:21], v[174:177], v[198:201], v[18:21]
	v_mfma_f32_16x16x32_bf16 v[4:7], v[166:169], v[206:209], v[4:7]
	v_mfma_f32_16x16x32_bf16 v[0:3], v[174:177], v[206:209], v[0:3]
	s_barrier
	s_setprio 0
	s_add_i32 s82, s82, 2
	s_add_u32 s24, s24, 0x10000
	s_addc_u32 s25, s25, 0
	s_add_u32 s0, s0, 0x10000
	s_addc_u32 s1, s1, 0
	v_add_u32_e32 v212, 0x10000, v157
.LBB0_848:
	s_add_u32 s16, s24, 0x4000
	s_addc_u32 s17, s25, 0
	s_cmpk_eq_i32 s82, 0xfc
	s_cselect_b32 s36, s73, s16
	s_cselect_b32 s37, s11, s17
	s_cselect_b32 s16, s78, s0
	s_cselect_b32 s17, s15, s1
	s_add_u32 s26, s36, 0x8000
	s_addc_u32 s27, s37, 0
	s_add_i32 s83, 0, 0x10000
	s_add_i32 s94, 0, 0x14000
	ds_read_b128 v[130:133], v212
	ds_read_b128 v[134:137], v212 offset:1024
	ds_read_b128 v[148:151], v212 offset:2048
	ds_read_b128 v[152:155], v212 offset:3072
	ds_read_b128 v[162:165], v212 offset:16384
	ds_read_b128 v[166:169], v212 offset:17408
	ds_read_b128 v[170:173], v212 offset:18432
	ds_read_b128 v[174:177], v212 offset:19456
	s_add_i32 m0, s39, 0xc000
	ds_read_b128 v[178:181], v161
	ds_read_b128 v[182:185], v161 offset:1024
	ds_read_b128 v[186:189], v161 offset:2048
	ds_read_b128 v[190:193], v161 offset:3072
	ds_read_b128 v[194:197], v161 offset:4096
	ds_read_b128 v[198:201], v161 offset:5120
	ds_read_b128 v[202:205], v161 offset:6144
	ds_read_b128 v[206:209], v161 offset:7168
	global_load_lds_dwordx4 v144, s[24:25]
	s_add_i32 m0, s39, 0xe000
	s_nop 0
	global_load_lds_dwordx4 v146, s[24:25]
	s_waitcnt vmcnt(8)
	s_waitcnt lgkmcnt(0)
	s_nop 0
	s_setprio 1
	s_barrier
; #define PG8_STAGEA(bufoff, gbase, voff) PG8_STAGE_X(bufoff, gbase, voff, AUXA)
; #define PG8_STAGEB(bufoff, gbase, voff) PG8_STAGE_X(bufoff, gbase, voff, AUXB)
; #define PG8_LDA(dst, b, h) do { _Pragma("unroll") for (int m = 0; m < 4; ++m) _Pragma("unroll") for (int k = 0; k < 2; ++k) dst[m][k] = *(const PG8_LAS bf16x8*)(lds + PG8_SA(b, h) + aoff + m * 2048 + k * 1024); } while (0)
; #define PG8_LDB(dst, b, h) do { _Pragma("unroll") for (int n = 0; n < 2; ++n) _Pragma("unroll") for (int k = 0; k < 2; ++k) dst[n][k] = *(const PG8_LAS bf16x8*)(lds + PG8_SB(b, h) + boff + n * 2048 + k * 1024); } while (0)
; #define PG8_MMA(ai, bj, At, Bt) do { if (GEMM_PRIO_MODE == 0) __builtin_amdgcn_s_setprio(1); PG8_MMA_LOOPS \
;         acc[ai][bj][m][n] = __builtin_amdgcn_mfma_f32_16x16x32_bf16(Bt[n][k], At[m][k], acc[ai][bj][m][n], 0, 0, 0); if (GEMM_PRIO_MODE == 0) __builtin_amdgcn_s_setprio(0); } while (0)
; #define PG8_WAIT_V(n) asm volatile("s_waitcnt vmcnt(" #n ")" ::: "memory")
; #define PG8_WAIT_VR(n, nr, flag) asm volatile("s_cmp_eq_u32 %0, 0\n\ts_cbranch_scc1 .Lpg8s%=\n\ts_waitcnt vmcnt(" #nr ")\n\ts_branch .Lpg8d%=\n.Lpg8s%=:\n\ts_waitcnt vmcnt(" #n ")\n.Lpg8d%=:" :: "s"(flag) : "memory", "scc")
; #define PG8_WAIT_L(n) asm volatile("s_waitcnt lgkmcnt(" #n ")" ::: "memory")
; #define PG8_BAR __builtin_amdgcn_s_barrier()
; #define PG8_SCHED __builtin_amdgcn_sched_barrier(0)
;     ...
;             PG8_WAIT_V(8); PG8_WAIT_L(0); PG8_BAR; PG8_MMA(0, 0, At, B0); PG8_MMA(0, 1, At, B1); PG8_BAR; PG8_SCHED;
;     ...
;             PG8_LDA(At, 0, 1); PG8_STAGEB(PG8_SB(0, 0), b2, voffB); PG8_STAGEB(PG8_SB(0, 1), b2 + hstepB, voffB); PG8_STAGEA(PG8_SA(0, 0), a2, voffA);
;     ...
;             PG8_WAIT_VR(8, 24, relax); PG8_WAIT_L(0); PG8_BAR; PG8_MMA(1, 0, At, B0); PG8_MMA(1, 1, At, B1); PG8_BAR; PG8_SCHED;
;     ...
;             PG8_WAIT_V(8); PG8_WAIT_L(0); PG8_BAR; PG8_MMA(1, 0, At, B0); PG8_MMA(1, 1, At, B1); PG8_BAR; PG8_SCHED;
;     ...
;             PG8_LDB(B0, 1, 0); PG8_LDB(B1, 1, 1); PG8_SCHED; PG8_LDA(At, 1, 0); PG8_STAGEA(PG8_SA(0, 1), a2 + hstepA, voffA);
;             PG8_WAIT_V(8); PG8_WAIT_L(0); PG8_BAR; PG8_MMA(0, 0, At, B0); PG8_MMA(0, 1, At, B1); PG8_BAR; PG8_SCHED;
	v_mfma_f32_16x16x32_bf16 v[126:129], v[130:133], v[178:181], v[126:129]
	v_mfma_f32_16x16x32_bf16 v[122:125], v[148:151], v[178:181], v[122:125]
	v_mfma_f32_16x16x32_bf16 v[110:113], v[130:133], v[186:189], v[110:113]
	v_mfma_f32_16x16x32_bf16 v[106:109], v[148:151], v[186:189], v[106:109]
	v_mfma_f32_16x16x32_bf16 v[94:97], v[130:133], v[194:197], v[94:97]
	v_mfma_f32_16x16x32_bf16 v[90:93], v[148:151], v[194:197], v[90:93]
	v_mfma_f32_16x16x32_bf16 v[78:81], v[130:133], v[202:205], v[78:81]
	v_mfma_f32_16x16x32_bf16 v[74:77], v[148:151], v[202:205], v[74:77]
	v_mfma_f32_16x16x32_bf16 v[126:129], v[134:137], v[182:185], v[126:129]
	v_mfma_f32_16x16x32_bf16 v[122:125], v[152:155], v[182:185], v[122:125]
	v_mfma_f32_16x16x32_bf16 v[110:113], v[134:137], v[190:193], v[110:113]
	v_mfma_f32_16x16x32_bf16 v[106:109], v[152:155], v[190:193], v[106:109]
	v_mfma_f32_16x16x32_bf16 v[94:97], v[134:137], v[198:201], v[94:97]
	v_mfma_f32_16x16x32_bf16 v[90:93], v[152:155], v[198:201], v[90:93]
	v_mfma_f32_16x16x32_bf16 v[78:81], v[134:137], v[206:209], v[78:81]
	v_mfma_f32_16x16x32_bf16 v[74:77], v[152:155], v[206:209], v[74:77]
	v_mfma_f32_16x16x32_bf16 v[118:121], v[162:165], v[178:181], v[118:121]
	v_mfma_f32_16x16x32_bf16 v[114:117], v[170:173], v[178:181], v[114:117]
	v_mfma_f32_16x16x32_bf16 v[102:105], v[162:165], v[186:189], v[102:105]
	v_mfma_f32_16x16x32_bf16 v[98:101], v[170:173], v[186:189], v[98:101]
	v_mfma_f32_16x16x32_bf16 v[86:89], v[162:165], v[194:197], v[86:89]
	v_mfma_f32_16x16x32_bf16 v[82:85], v[170:173], v[194:197], v[82:85]
	v_mfma_f32_16x16x32_bf16 v[70:73], v[162:165], v[202:205], v[70:73]
	v_mfma_f32_16x16x32_bf16 v[66:69], v[170:173], v[202:205], v[66:69]
	v_mfma_f32_16x16x32_bf16 v[118:121], v[166:169], v[182:185], v[118:121]
	v_mfma_f32_16x16x32_bf16 v[114:117], v[174:177], v[182:185], v[114:117]
	v_mfma_f32_16x16x32_bf16 v[102:105], v[166:169], v[190:193], v[102:105]
	v_mfma_f32_16x16x32_bf16 v[98:101], v[174:177], v[190:193], v[98:101]
	v_mfma_f32_16x16x32_bf16 v[86:89], v[166:169], v[198:201], v[86:89]
	v_mfma_f32_16x16x32_bf16 v[82:85], v[174:177], v[198:201], v[82:85]
	v_mfma_f32_16x16x32_bf16 v[70:73], v[166:169], v[206:209], v[70:73]
	v_mfma_f32_16x16x32_bf16 v[66:69], v[174:177], v[206:209], v[66:69]
	s_barrier
	s_setprio 0
	s_add_i32 s83, s83, s38
	s_mov_b32 m0, s83
	ds_read_b128 v[178:181], v161 offset:16384
	ds_read_b128 v[182:185], v161 offset:17408
	ds_read_b128 v[186:189], v161 offset:18432
	ds_read_b128 v[190:193], v161 offset:19456
	ds_read_b128 v[194:197], v161 offset:20480
	ds_read_b128 v[198:201], v161 offset:21504
	ds_read_b128 v[202:205], v161 offset:22528
	ds_read_b128 v[206:209], v161 offset:23552
	global_load_lds_dwordx4 v16, s[16:17]
	s_add_i32 m0, s83, 0x2000
	s_add_u32 s90, s16, 0x4000
	s_addc_u32 s91, s17, 0
	s_add_i32 s83, s94, s38
	global_load_lds_dwordx4 v138, s[16:17]
	s_mov_b32 m0, s83
	s_nop 0
	global_load_lds_dwordx4 v16, s[90:91]
	s_add_i32 m0, s83, 0x2000
	s_nop 0
	global_load_lds_dwordx4 v138, s[90:91]
	s_mov_b32 m0, s39
	s_nop 0
	global_load_lds_dwordx4 v142, s[36:37]
	s_mov_b32 m0, s40
	s_nop 0
	global_load_lds_dwordx4 v140, s[36:37]
	s_waitcnt vmcnt(8)
	s_waitcnt lgkmcnt(0)
	s_nop 0
	s_nop 0
	s_nop 0
	s_setprio 1
	s_barrier
	v_mfma_f32_16x16x32_bf16 v[62:65], v[130:133], v[178:181], v[62:65]
	v_mfma_f32_16x16x32_bf16 v[58:61], v[148:151], v[178:181], v[58:61]
	v_mfma_f32_16x16x32_bf16 v[46:49], v[130:133], v[186:189], v[46:49]
	v_mfma_f32_16x16x32_bf16 v[42:45], v[148:151], v[186:189], v[42:45]
	v_mfma_f32_16x16x32_bf16 v[30:33], v[130:133], v[194:197], v[30:33]
	v_mfma_f32_16x16x32_bf16 v[26:29], v[148:151], v[194:197], v[26:29]
	v_mfma_f32_16x16x32_bf16 v[12:15], v[130:133], v[202:205], v[12:15]
	v_mfma_f32_16x16x32_bf16 v[8:11], v[148:151], v[202:205], v[8:11]
	v_mfma_f32_16x16x32_bf16 v[62:65], v[134:137], v[182:185], v[62:65]
	v_mfma_f32_16x16x32_bf16 v[58:61], v[152:155], v[182:185], v[58:61]
	v_mfma_f32_16x16x32_bf16 v[46:49], v[134:137], v[190:193], v[46:49]
	v_mfma_f32_16x16x32_bf16 v[42:45], v[152:155], v[190:193], v[42:45]
	v_mfma_f32_16x16x32_bf16 v[30:33], v[134:137], v[198:201], v[30:33]
	v_mfma_f32_16x16x32_bf16 v[26:29], v[152:155], v[198:201], v[26:29]
	v_mfma_f32_16x16x32_bf16 v[12:15], v[134:137], v[206:209], v[12:15]
	v_mfma_f32_16x16x32_bf16 v[8:11], v[152:155], v[206:209], v[8:11]
	v_mfma_f32_16x16x32_bf16 v[54:57], v[162:165], v[178:181], v[54:57]
	v_mfma_f32_16x16x32_bf16 v[50:53], v[170:173], v[178:181], v[50:53]
	v_mfma_f32_16x16x32_bf16 v[38:41], v[162:165], v[186:189], v[38:41]
	v_mfma_f32_16x16x32_bf16 v[34:37], v[170:173], v[186:189], v[34:37]
	v_mfma_f32_16x16x32_bf16 v[22:25], v[162:165], v[194:197], v[22:25]
	v_mfma_f32_16x16x32_bf16 v[18:21], v[170:173], v[194:197], v[18:21]
	v_mfma_f32_16x16x32_bf16 v[4:7], v[162:165], v[202:205], v[4:7]
	v_mfma_f32_16x16x32_bf16 v[0:3], v[170:173], v[202:205], v[0:3]
	v_mfma_f32_16x16x32_bf16 v[54:57], v[166:169], v[182:185], v[54:57]
	v_mfma_f32_16x16x32_bf16 v[50:53], v[174:177], v[182:185], v[50:53]
	v_mfma_f32_16x16x32_bf16 v[38:41], v[166:169], v[190:193], v[38:41]
	v_mfma_f32_16x16x32_bf16 v[34:37], v[174:177], v[190:193], v[34:37]
	v_mfma_f32_16x16x32_bf16 v[22:25], v[166:169], v[198:201], v[22:25]
	v_mfma_f32_16x16x32_bf16 v[18:21], v[174:177], v[198:201], v[18:21]
	v_mfma_f32_16x16x32_bf16 v[4:7], v[166:169], v[206:209], v[4:7]
	v_mfma_f32_16x16x32_bf16 v[0:3], v[174:177], v[206:209], v[0:3]
	s_barrier
; #define PG8_STAGEA(bufoff, gbase, voff) PG8_STAGE_X(bufoff, gbase, voff, AUXA)
; #define PG8_STAGEB(bufoff, gbase, voff) PG8_STAGE_X(bufoff, gbase, voff, AUXB)
; #define PG8_LDA(dst, b, h) do { _Pragma("unroll") for (int m = 0; m < 4; ++m) _Pragma("unroll") for (int k = 0; k < 2; ++k) dst[m][k] = *(const PG8_LAS bf16x8*)(lds + PG8_SA(b, h) + aoff + m * 2048 + k * 1024); } while (0)
; #define PG8_LDB(dst, b, h) do { _Pragma("unroll") for (int n = 0; n < 2; ++n) _Pragma("unroll") for (int k = 0; k < 2; ++k) dst[n][k] = *(const PG8_LAS bf16x8*)(lds + PG8_SB(b, h) + boff + n * 2048 + k * 1024); } while (0)
; #define PG8_MMA(ai, bj, At, Bt) do { if (GEMM_PRIO_MODE == 0) __builtin_amdgcn_s_setprio(1); PG8_MMA_LOOPS \
;         acc[ai][bj][m][n] = __builtin_amdgcn_mfma_f32_16x16x32_bf16(Bt[n][k], At[m][k], acc[ai][bj][m][n], 0, 0, 0); if (GEMM_PRIO_MODE == 0) __builtin_amdgcn_s_setprio(0); } while (0)
; #define PG8_WAIT_V(n) asm volatile("s_waitcnt vmcnt(" #n ")" ::: "memory")
; #define PG8_WAIT_L(n) asm volatile("s_waitcnt lgkmcnt(" #n ")" ::: "memory")
; #define PG8_BAR __builtin_amdgcn_s_barrier()
; #define PG8_SCHED __builtin_amdgcn_sched_barrier(0)
;     ...
;             PG8_LDB(B0, 1, 0); PG8_LDB(B1, 1, 1); PG8_SCHED; PG8_LDA(At, 1, 0); PG8_STAGEA(PG8_SA(0, 1), a2 + hstepA, voffA);
;             PG8_WAIT_V(8); PG8_WAIT_L(0); PG8_BAR; PG8_MMA(0, 0, At, B0); PG8_MMA(0, 1, At, B1); PG8_BAR; PG8_SCHED;
;             PG8_LDA(At, 1, 1); PG8_STAGEB(PG8_SB(1, 0), b3, voffB); PG8_STAGEB(PG8_SB(1, 1), b3 + hstepB, voffB); PG8_STAGEA(PG8_SA(1, 0), a3, voffA);
;             PG8_WAIT_V(8); PG8_WAIT_L(0); PG8_BAR; PG8_MMA(1, 0, At, B0); PG8_MMA(1, 1, At, B1); PG8_BAR; PG8_SCHED;
;     ...
;         if constexpr (ALIGN_EPI) { if (wr == 0) PG8_BAR; }
	s_setprio 0
	s_add_i32 s83, 0, 0x18000
	s_add_i32 s90, 0, 0x1c000
	ds_read_b128 v[130:133], v212 offset:32768
	ds_read_b128 v[134:137], v212 offset:33792
	ds_read_b128 v[148:151], v212 offset:34816
	ds_read_b128 v[152:155], v212 offset:35840
	ds_read_b128 v[162:165], v212 offset:49152
	ds_read_b128 v[166:169], v212 offset:50176
	ds_read_b128 v[170:173], v212 offset:51200
	ds_read_b128 v[174:177], v212 offset:52224
	s_add_u32 s36, s36, 0x4000
	s_addc_u32 s37, s37, 0
	s_mov_b32 m0, s41
	ds_read_b128 v[178:181], v161 offset:32768
	ds_read_b128 v[182:185], v161 offset:33792
	ds_read_b128 v[186:189], v161 offset:34816
	ds_read_b128 v[190:193], v161 offset:35840
	ds_read_b128 v[194:197], v161 offset:36864
	ds_read_b128 v[198:201], v161 offset:37888
	ds_read_b128 v[202:205], v161 offset:38912
	ds_read_b128 v[206:209], v161 offset:39936
	global_load_lds_dwordx4 v142, s[36:37]
	s_mov_b32 m0, s42
	s_nop 0
	global_load_lds_dwordx4 v140, s[36:37]
	s_waitcnt vmcnt(8)
	s_waitcnt lgkmcnt(0)
	s_setprio 1
	s_barrier
	v_mfma_f32_16x16x32_bf16 v[126:129], v[130:133], v[178:181], v[126:129]
	v_mfma_f32_16x16x32_bf16 v[122:125], v[148:151], v[178:181], v[122:125]
	v_mfma_f32_16x16x32_bf16 v[110:113], v[130:133], v[186:189], v[110:113]
	v_mfma_f32_16x16x32_bf16 v[106:109], v[148:151], v[186:189], v[106:109]
	v_mfma_f32_16x16x32_bf16 v[94:97], v[130:133], v[194:197], v[94:97]
	v_mfma_f32_16x16x32_bf16 v[90:93], v[148:151], v[194:197], v[90:93]
	v_mfma_f32_16x16x32_bf16 v[78:81], v[130:133], v[202:205], v[78:81]
	v_mfma_f32_16x16x32_bf16 v[74:77], v[148:151], v[202:205], v[74:77]
	v_mfma_f32_16x16x32_bf16 v[126:129], v[134:137], v[182:185], v[126:129]
	v_mfma_f32_16x16x32_bf16 v[122:125], v[152:155], v[182:185], v[122:125]
	v_mfma_f32_16x16x32_bf16 v[110:113], v[134:137], v[190:193], v[110:113]
	v_mfma_f32_16x16x32_bf16 v[106:109], v[152:155], v[190:193], v[106:109]
	v_mfma_f32_16x16x32_bf16 v[94:97], v[134:137], v[198:201], v[94:97]
	v_mfma_f32_16x16x32_bf16 v[90:93], v[152:155], v[198:201], v[90:93]
	v_mfma_f32_16x16x32_bf16 v[78:81], v[134:137], v[206:209], v[78:81]
	v_mfma_f32_16x16x32_bf16 v[74:77], v[152:155], v[206:209], v[74:77]
	v_mfma_f32_16x16x32_bf16 v[118:121], v[162:165], v[178:181], v[118:121]
	v_mfma_f32_16x16x32_bf16 v[114:117], v[170:173], v[178:181], v[114:117]
	v_mfma_f32_16x16x32_bf16 v[102:105], v[162:165], v[186:189], v[102:105]
	v_mfma_f32_16x16x32_bf16 v[98:101], v[170:173], v[186:189], v[98:101]
	v_mfma_f32_16x16x32_bf16 v[86:89], v[162:165], v[194:197], v[86:89]
	v_mfma_f32_16x16x32_bf16 v[82:85], v[170:173], v[194:197], v[82:85]
	v_mfma_f32_16x16x32_bf16 v[70:73], v[162:165], v[202:205], v[70:73]
	v_mfma_f32_16x16x32_bf16 v[66:69], v[170:173], v[202:205], v[66:69]
	v_mfma_f32_16x16x32_bf16 v[118:121], v[166:169], v[182:185], v[118:121]
	v_mfma_f32_16x16x32_bf16 v[114:117], v[174:177], v[182:185], v[114:117]
	v_mfma_f32_16x16x32_bf16 v[102:105], v[166:169], v[190:193], v[102:105]
	v_mfma_f32_16x16x32_bf16 v[98:101], v[174:177], v[190:193], v[98:101]
	v_mfma_f32_16x16x32_bf16 v[86:89], v[166:169], v[198:201], v[86:89]
	v_mfma_f32_16x16x32_bf16 v[82:85], v[174:177], v[198:201], v[82:85]
	v_mfma_f32_16x16x32_bf16 v[70:73], v[166:169], v[206:209], v[70:73]
	v_mfma_f32_16x16x32_bf16 v[66:69], v[174:177], v[206:209], v[66:69]
	s_barrier
	s_setprio 0
	s_add_u32 s36, s16, 0x8000
	s_addc_u32 s37, s17, 0
	s_add_i32 s83, s83, s38
	s_mov_b32 m0, s83
	ds_read_b128 v[178:181], v161 offset:49152
	ds_read_b128 v[182:185], v161 offset:50176
	ds_read_b128 v[186:189], v161 offset:51200
	ds_read_b128 v[190:193], v161 offset:52224
	ds_read_b128 v[194:197], v161 offset:53248
	ds_read_b128 v[198:201], v161 offset:54272
	ds_read_b128 v[202:205], v161 offset:55296
	ds_read_b128 v[206:209], v161 offset:56320
	global_load_lds_dwordx4 v16, s[36:37]
	s_add_i32 m0, s83, 0x2000
	s_add_u32 s16, s16, 0xc000
	s_addc_u32 s17, s17, 0
	global_load_lds_dwordx4 v138, s[36:37]
	s_add_i32 s36, s90, s38
	s_mov_b32 m0, s36
	s_nop 0
	global_load_lds_dwordx4 v16, s[16:17]
	s_add_i32 m0, s36, 0x2000
	s_nop 0
	global_load_lds_dwordx4 v138, s[16:17]
	s_mov_b32 m0, s50
	s_nop 0
	global_load_lds_dwordx4 v142, s[26:27]
	s_mov_b32 m0, s51
	s_nop 0
	global_load_lds_dwordx4 v140, s[26:27]
	s_waitcnt vmcnt(8)
	s_waitcnt lgkmcnt(0)
	s_setprio 1
	s_barrier
	v_mfma_f32_16x16x32_bf16 v[62:65], v[130:133], v[178:181], v[62:65]
	v_mfma_f32_16x16x32_bf16 v[58:61], v[148:151], v[178:181], v[58:61]
	v_mfma_f32_16x16x32_bf16 v[46:49], v[130:133], v[186:189], v[46:49]
	v_mfma_f32_16x16x32_bf16 v[42:45], v[148:151], v[186:189], v[42:45]
	v_mfma_f32_16x16x32_bf16 v[30:33], v[130:133], v[194:197], v[30:33]
	v_mfma_f32_16x16x32_bf16 v[26:29], v[148:151], v[194:197], v[26:29]
	v_mfma_f32_16x16x32_bf16 v[12:15], v[130:133], v[202:205], v[12:15]
	v_mfma_f32_16x16x32_bf16 v[8:11], v[148:151], v[202:205], v[8:11]
	v_mfma_f32_16x16x32_bf16 v[62:65], v[134:137], v[182:185], v[62:65]
	v_mfma_f32_16x16x32_bf16 v[58:61], v[152:155], v[182:185], v[58:61]
	v_mfma_f32_16x16x32_bf16 v[46:49], v[134:137], v[190:193], v[46:49]
	v_mfma_f32_16x16x32_bf16 v[42:45], v[152:155], v[190:193], v[42:45]
	v_mfma_f32_16x16x32_bf16 v[30:33], v[134:137], v[198:201], v[30:33]
	v_mfma_f32_16x16x32_bf16 v[26:29], v[152:155], v[198:201], v[26:29]
	v_mfma_f32_16x16x32_bf16 v[12:15], v[134:137], v[206:209], v[12:15]
	v_mfma_f32_16x16x32_bf16 v[8:11], v[152:155], v[206:209], v[8:11]
	v_mfma_f32_16x16x32_bf16 v[54:57], v[162:165], v[178:181], v[54:57]
	v_mfma_f32_16x16x32_bf16 v[50:53], v[170:173], v[178:181], v[50:53]
	v_mfma_f32_16x16x32_bf16 v[38:41], v[162:165], v[186:189], v[38:41]
	v_mfma_f32_16x16x32_bf16 v[34:37], v[170:173], v[186:189], v[34:37]
	v_mfma_f32_16x16x32_bf16 v[22:25], v[162:165], v[194:197], v[22:25]
	v_mfma_f32_16x16x32_bf16 v[18:21], v[170:173], v[194:197], v[18:21]
	v_mfma_f32_16x16x32_bf16 v[4:7], v[162:165], v[202:205], v[4:7]
	v_mfma_f32_16x16x32_bf16 v[0:3], v[170:173], v[202:205], v[0:3]
	v_mfma_f32_16x16x32_bf16 v[54:57], v[166:169], v[182:185], v[54:57]
	v_mfma_f32_16x16x32_bf16 v[50:53], v[174:177], v[182:185], v[50:53]
	v_mfma_f32_16x16x32_bf16 v[38:41], v[166:169], v[190:193], v[38:41]
	v_mfma_f32_16x16x32_bf16 v[34:37], v[174:177], v[190:193], v[34:37]
	v_mfma_f32_16x16x32_bf16 v[22:25], v[166:169], v[198:201], v[22:25]
	v_mfma_f32_16x16x32_bf16 v[18:21], v[174:177], v[198:201], v[18:21]
	v_mfma_f32_16x16x32_bf16 v[4:7], v[166:169], v[206:209], v[4:7]
	v_mfma_f32_16x16x32_bf16 v[0:3], v[174:177], v[206:209], v[0:3]
	s_barrier
	s_setprio 0
	s_add_i32 s82, s82, 2
	s_add_u32 s24, s24, 0x10000
	s_addc_u32 s25, s25, 0
	s_add_u32 s0, s0, 0x10000
	s_addc_u32 s1, s1, 0
	s_cmpk_gt_u32 s82, 0xfd
	s_cbranch_scc0 .LBB0_848
	s_mov_b32 s98, 1
	s_and_b64 vcc, exec, s[8:9]
	s_cbranch_vccz .LBB0_851
	s_barrier
